# GEMM K-loops: issue LDS-DMA tile loads in SGPR-base + 32-bit VGPR-offset form (drops a 64-bit VALU address add and its dependency per load)
# speedup vs baseline: 1.0202x; 1.0150x over previous
; #define PG8_STAGE(bufoff, gbase, voff) do { _Pragma("unroll") for (int _i = 0; _i < 2; ++_i) \
;         __builtin_amdgcn_global_load_lds((const unsigned*)((const char*)(gbase) + (voff)[_i]), (LAS unsigned*)(lds + (bufoff) + ldsw + _i * 8192), 16, 0, 0); } while (0)
; #define PG8_LDA(dst, b, h) do { _Pragma("unroll") for (int m = 0; m < 4; ++m) _Pragma("unroll") for (int k = 0; k < 2; ++k) dst[m][k] = *(const LAS bf16x8*)(lds + PG8_SA(b, h) + aoff + m * 2048 + k * 1024); } while (0)
; #define PG8_LDB(dst, b, h) do { _Pragma("unroll") for (int n = 0; n < 2; ++n) _Pragma("unroll") for (int k = 0; k < 2; ++k) dst[n][k] = *(const LAS bf16x8*)(lds + PG8_SB(b, h) + boff + n * 2048 + k * 1024); } while (0)
; #define PG8_MMA(ai, bj, At, Bt) do { __builtin_amdgcn_s_setprio(1); _Pragma("unroll") for (int m = 0; m < 4; ++m) _Pragma("unroll") for (int n = 0; n < 2; ++n) _Pragma("unroll") for (int k = 0; k < 2; ++k) \
;         acc[ai][bj][m][n] = __builtin_amdgcn_mfma_f32_16x16x32_bf16(Bt[n][k], At[m][k], acc[ai][bj][m][n], 0, 0, 0); __builtin_amdgcn_s_setprio(0); } while (0)
; #define PG8_WAIT_V(n) asm volatile("s_waitcnt vmcnt(" #n ")" ::: "memory")
; #define PG8_WAIT_L(n) asm volatile("s_waitcnt lgkmcnt(" #n ")" ::: "memory")
; #define PG8_BAR __builtin_amdgcn_s_barrier()
; #define PG8_SCHED __builtin_amdgcn_sched_barrier(0)
; template <class Epi>
; __device__ __forceinline__ void gemm_phase(LAS unsigned char* lds, const Gemm g, const StaticOrder& S, const Epi& E) {
;     ...
;             PG8_LDB(B0, 0, 0); PG8_SCHED; PG8_LDA(At, 0, 0); PG8_STAGE(PG8_SA(1, 1), a1 + hstep, voffA);
;             PG8_WAIT_L(8); PG8_BAR; PG8_WAIT_L(0); PG8_MMA(0, 0, At, B0); PG8_BAR; PG8_SCHED;
;             PG8_LDB(B1, 0, 1); PG8_STAGE(PG8_SB(0, 0), b2, voffB);
;             PG8_BAR; PG8_WAIT_L(0); PG8_MMA(0, 1, At, B1); PG8_BAR;
;             PG8_LDA(At, 0, 1); PG8_STAGE(PG8_SA(0, 0), a2, voffA);
;             PG8_BAR; PG8_WAIT_L(0); PG8_MMA(1, 0, At, B0); PG8_BAR; PG8_SCHED;
;             PG8_STAGE(PG8_SB(0, 1), b2 + hstep, voffB);
;             PG8_WAIT_V(6); PG8_BAR; PG8_MMA(1, 1, At, B1); PG8_BAR;
.LBB0_203:
	ds_read_b128 v[144:147], v153
	ds_read_b128 v[160:163], v153 offset:1024
	ds_read_b128 v[164:167], v153 offset:2048
	ds_read_b128 v[168:171], v153 offset:3072
	s_add_u32 s44, s42, 0xfff80080
	s_addc_u32 s45, s43, -1
	s_cmp_eq_u32 s54, 28
	s_cselect_b32 s47, s25, s45
	s_cselect_b32 s46, s50, s44
	s_cselect_b32 s45, s23, s53
	s_cselect_b32 s44, s51, s52
	s_add_i32 m0, s11, 0xc000
	ds_read_b128 v[172:175], v154
	ds_read_b128 v[176:179], v154 offset:1024
	ds_read_b128 v[180:183], v154 offset:2048
	ds_read_b128 v[184:187], v154 offset:3072
	ds_read_b128 v[188:191], v154 offset:4096
	ds_read_b128 v[192:195], v154 offset:5120
	ds_read_b128 v[196:199], v154 offset:6144
	ds_read_b128 v[200:203], v154 offset:7168
	global_load_lds_dwordx4 v136, s[42:43]
	s_add_i32 m0, s11, 0xe000
	s_nop 0
	global_load_lds_dwordx4 v138, s[42:43]
	s_waitcnt lgkmcnt(8)
	s_barrier
	s_waitcnt lgkmcnt(0)
	s_setprio 1
	s_waitcnt lgkmcnt(0)
	v_mfma_f32_16x16x32_bf16 v[124:127], v[144:147], v[172:175], v[124:127]
	v_mfma_f32_16x16x32_bf16 v[120:123], v[164:167], v[172:175], v[120:123]
	v_mfma_f32_16x16x32_bf16 v[108:111], v[144:147], v[180:183], v[108:111]
	v_mfma_f32_16x16x32_bf16 v[104:107], v[164:167], v[180:183], v[104:107]
	v_mfma_f32_16x16x32_bf16 v[92:95], v[144:147], v[188:191], v[92:95]
	v_mfma_f32_16x16x32_bf16 v[88:91], v[164:167], v[188:191], v[88:91]
	v_mfma_f32_16x16x32_bf16 v[76:79], v[144:147], v[196:199], v[76:79]
	v_mfma_f32_16x16x32_bf16 v[72:75], v[164:167], v[196:199], v[72:75]
	v_mfma_f32_16x16x32_bf16 v[124:127], v[160:163], v[176:179], v[124:127]
	v_mfma_f32_16x16x32_bf16 v[120:123], v[168:171], v[176:179], v[120:123]
	v_mfma_f32_16x16x32_bf16 v[108:111], v[160:163], v[184:187], v[108:111]
	v_mfma_f32_16x16x32_bf16 v[104:107], v[168:171], v[184:187], v[104:107]
	v_mfma_f32_16x16x32_bf16 v[92:95], v[160:163], v[192:195], v[92:95]
	v_mfma_f32_16x16x32_bf16 v[88:91], v[168:171], v[192:195], v[88:91]
	v_mfma_f32_16x16x32_bf16 v[76:79], v[160:163], v[200:203], v[76:79]
	v_mfma_f32_16x16x32_bf16 v[72:75], v[168:171], v[200:203], v[72:75]
	s_setprio 0
	s_barrier
	s_add_i32 s55, s41, s10
	v_lshl_add_u64 v[148:149], s[44:45], 0, v[132:133]
	s_mov_b32 m0, s55
	ds_read_b128 v[204:207], v155
	ds_read_b128 v[208:211], v155 offset:1024
	ds_read_b128 v[212:215], v155 offset:2048
	ds_read_b128 v[216:219], v155 offset:3072
	global_load_lds_dwordx4 v132, s[44:45]
	v_lshl_add_u64 v[156:157], s[44:45], 0, v[128:129]
	s_add_i32 m0, s55, 0x2000
	s_nop 0
	global_load_lds_dwordx4 v128, s[44:45]
	s_barrier
	s_waitcnt lgkmcnt(0)
	s_setprio 1
	s_waitcnt lgkmcnt(0)
	v_mfma_f32_16x16x32_bf16 v[116:119], v[204:207], v[172:175], v[116:119]
	v_mfma_f32_16x16x32_bf16 v[112:115], v[212:215], v[172:175], v[112:115]
	v_mfma_f32_16x16x32_bf16 v[100:103], v[204:207], v[180:183], v[100:103]
	v_mfma_f32_16x16x32_bf16 v[96:99], v[212:215], v[180:183], v[96:99]
	v_mfma_f32_16x16x32_bf16 v[84:87], v[204:207], v[188:191], v[84:87]
	v_mfma_f32_16x16x32_bf16 v[80:83], v[212:215], v[188:191], v[80:83]
	v_mfma_f32_16x16x32_bf16 v[68:71], v[204:207], v[196:199], v[68:71]
	v_mfma_f32_16x16x32_bf16 v[64:67], v[212:215], v[196:199], v[64:67]
	v_mfma_f32_16x16x32_bf16 v[116:119], v[208:211], v[176:179], v[116:119]
	v_mfma_f32_16x16x32_bf16 v[112:115], v[216:219], v[176:179], v[112:115]
	v_mfma_f32_16x16x32_bf16 v[100:103], v[208:211], v[184:187], v[100:103]
	v_mfma_f32_16x16x32_bf16 v[96:99], v[216:219], v[184:187], v[96:99]
	v_mfma_f32_16x16x32_bf16 v[84:87], v[208:211], v[192:195], v[84:87]
	v_mfma_f32_16x16x32_bf16 v[80:83], v[216:219], v[192:195], v[80:83]
	v_mfma_f32_16x16x32_bf16 v[68:71], v[208:211], v[200:203], v[68:71]
	v_mfma_f32_16x16x32_bf16 v[64:67], v[216:219], v[200:203], v[64:67]
	s_setprio 0
	s_mov_b32 m0, s11
	v_lshl_add_u64 v[220:221], s[46:47], 0, v[134:135]
	s_barrier
	ds_read_b128 v[172:175], v154 offset:16384
	ds_read_b128 v[176:179], v154 offset:17408
	ds_read_b128 v[180:183], v154 offset:18432
	ds_read_b128 v[184:187], v154 offset:19456
	ds_read_b128 v[188:191], v154 offset:20480
	ds_read_b128 v[192:195], v154 offset:21504
	ds_read_b128 v[196:199], v154 offset:22528
	ds_read_b128 v[200:203], v154 offset:23552
	global_load_lds_dwordx4 v134, s[46:47]
	v_lshl_add_u64 v[222:223], s[46:47], 0, v[130:131]
	s_mov_b32 m0, s13
	s_nop 0
	global_load_lds_dwordx4 v130, s[46:47]
	s_barrier
	s_waitcnt lgkmcnt(0)
	s_setprio 1
	s_waitcnt lgkmcnt(0)
	v_mfma_f32_16x16x32_bf16 v[60:63], v[144:147], v[172:175], v[60:63]
	v_mfma_f32_16x16x32_bf16 v[56:59], v[164:167], v[172:175], v[56:59]
	v_mfma_f32_16x16x32_bf16 v[44:47], v[144:147], v[180:183], v[44:47]
	v_mfma_f32_16x16x32_bf16 v[40:43], v[164:167], v[180:183], v[40:43]
	v_mfma_f32_16x16x32_bf16 v[28:31], v[144:147], v[188:191], v[28:31]
	v_mfma_f32_16x16x32_bf16 v[24:27], v[164:167], v[188:191], v[24:27]
	v_mfma_f32_16x16x32_bf16 v[12:15], v[144:147], v[196:199], v[12:15]
	v_mfma_f32_16x16x32_bf16 v[8:11], v[164:167], v[196:199], v[8:11]
	v_mfma_f32_16x16x32_bf16 v[60:63], v[160:163], v[176:179], v[60:63]
	v_mfma_f32_16x16x32_bf16 v[56:59], v[168:171], v[176:179], v[56:59]
	v_mfma_f32_16x16x32_bf16 v[44:47], v[160:163], v[184:187], v[44:47]
	v_mfma_f32_16x16x32_bf16 v[40:43], v[168:171], v[184:187], v[40:43]
	v_mfma_f32_16x16x32_bf16 v[28:31], v[160:163], v[192:195], v[28:31]
	v_mfma_f32_16x16x32_bf16 v[24:27], v[168:171], v[192:195], v[24:27]
	v_mfma_f32_16x16x32_bf16 v[12:15], v[160:163], v[200:203], v[12:15]
	v_mfma_f32_16x16x32_bf16 v[8:11], v[168:171], v[200:203], v[8:11]
	s_setprio 0
	s_barrier
	s_add_u32 s56, s44, 0x80000
	s_addc_u32 s57, s45, 0
	s_add_i32 s55, s48, s10
	s_mov_b32 m0, s55
	s_nop 0
	global_load_lds_dwordx4 v132, s[56:57]
	s_add_i32 m0, s55, 0x2000
	s_nop 0
	global_load_lds_dwordx4 v128, s[56:57]
	s_waitcnt vmcnt(6)
	s_barrier
; #define PG8_STAGE(bufoff, gbase, voff) do { _Pragma("unroll") for (int _i = 0; _i < 2; ++_i) \
;         __builtin_amdgcn_global_load_lds((const unsigned*)((const char*)(gbase) + (voff)[_i]), (LAS unsigned*)(lds + (bufoff) + ldsw + _i * 8192), 16, 0, 0); } while (0)
; #define PG8_LDA(dst, b, h) do { _Pragma("unroll") for (int m = 0; m < 4; ++m) _Pragma("unroll") for (int k = 0; k < 2; ++k) dst[m][k] = *(const LAS bf16x8*)(lds + PG8_SA(b, h) + aoff + m * 2048 + k * 1024); } while (0)
; #define PG8_LDB(dst, b, h) do { _Pragma("unroll") for (int n = 0; n < 2; ++n) _Pragma("unroll") for (int k = 0; k < 2; ++k) dst[n][k] = *(const LAS bf16x8*)(lds + PG8_SB(b, h) + boff + n * 2048 + k * 1024); } while (0)
; #define PG8_MMA(ai, bj, At, Bt) do { __builtin_amdgcn_s_setprio(1); _Pragma("unroll") for (int m = 0; m < 4; ++m) _Pragma("unroll") for (int n = 0; n < 2; ++n) _Pragma("unroll") for (int k = 0; k < 2; ++k) \
;         acc[ai][bj][m][n] = __builtin_amdgcn_mfma_f32_16x16x32_bf16(Bt[n][k], At[m][k], acc[ai][bj][m][n], 0, 0, 0); __builtin_amdgcn_s_setprio(0); } while (0)
; #define PG8_WAIT_L(n) asm volatile("s_waitcnt lgkmcnt(" #n ")" ::: "memory")
; #define PG8_BAR __builtin_amdgcn_s_barrier()
; #define PG8_SCHED __builtin_amdgcn_sched_barrier(0)
; template <class Epi>
; __device__ __forceinline__ void gemm_phase(LAS unsigned char* lds, const Gemm g, const StaticOrder& S, const Epi& E) {
;     ...
;             PG8_LDB(B0, 1, 0); PG8_SCHED; PG8_LDA(At, 1, 0); PG8_STAGE(PG8_SA(0, 1), a2 + hstep, voffA);
;             PG8_WAIT_L(8); PG8_BAR; PG8_WAIT_L(0); PG8_MMA(0, 0, At, B0); PG8_BAR; PG8_SCHED;
;             PG8_LDB(B1, 1, 1); PG8_STAGE(PG8_SB(1, 0), b3, voffB);
;             PG8_BAR; PG8_WAIT_L(0); PG8_MMA(0, 1, At, B1); PG8_BAR;
;             PG8_LDA(At, 1, 1); PG8_STAGE(PG8_SA(1, 0), a3, voffA);
;             PG8_BAR; PG8_WAIT_L(0); PG8_MMA(1, 0, At, B0); PG8_BAR; PG8_SCHED;
	s_setprio 1
	v_mfma_f32_16x16x32_bf16 v[52:55], v[204:207], v[172:175], v[52:55]
	v_mfma_f32_16x16x32_bf16 v[48:51], v[212:215], v[172:175], v[48:51]
	v_mfma_f32_16x16x32_bf16 v[36:39], v[204:207], v[180:183], v[36:39]
	v_mfma_f32_16x16x32_bf16 v[32:35], v[212:215], v[180:183], v[32:35]
	v_mfma_f32_16x16x32_bf16 v[20:23], v[204:207], v[188:191], v[20:23]
	v_mfma_f32_16x16x32_bf16 v[16:19], v[212:215], v[188:191], v[16:19]
	v_mfma_f32_16x16x32_bf16 v[4:7], v[204:207], v[196:199], v[4:7]
	v_mfma_f32_16x16x32_bf16 v[0:3], v[212:215], v[196:199], v[0:3]
	v_mfma_f32_16x16x32_bf16 v[52:55], v[208:211], v[176:179], v[52:55]
	v_mfma_f32_16x16x32_bf16 v[48:51], v[216:219], v[176:179], v[48:51]
	v_mfma_f32_16x16x32_bf16 v[36:39], v[208:211], v[184:187], v[36:39]
	v_mfma_f32_16x16x32_bf16 v[32:35], v[216:219], v[184:187], v[32:35]
	v_mfma_f32_16x16x32_bf16 v[20:23], v[208:211], v[192:195], v[20:23]
	v_mfma_f32_16x16x32_bf16 v[16:19], v[216:219], v[192:195], v[16:19]
	v_mfma_f32_16x16x32_bf16 v[4:7], v[208:211], v[200:203], v[4:7]
	v_mfma_f32_16x16x32_bf16 v[0:3], v[216:219], v[200:203], v[0:3]
	s_setprio 0
	s_add_i32 s55, 0, 0x18000
	v_add_u32_e32 v168, s55, v151
	s_barrier
	ds_read_b128 v[144:147], v168
	ds_read_b128 v[160:163], v168 offset:1024
	ds_read_b128 v[164:167], v168 offset:2048
	ds_read_b128 v[168:171], v168 offset:3072
	s_add_u32 s46, s46, 0x80000
	s_addc_u32 s47, s47, 0
	s_mov_b32 m0, s30
	ds_read_b128 v[172:175], v154 offset:32768
	ds_read_b128 v[176:179], v154 offset:33792
	ds_read_b128 v[180:183], v154 offset:34816
	ds_read_b128 v[184:187], v154 offset:35840
	ds_read_b128 v[188:191], v154 offset:36864
	ds_read_b128 v[192:195], v154 offset:37888
	ds_read_b128 v[196:199], v154 offset:38912
	ds_read_b128 v[200:203], v154 offset:39936
	global_load_lds_dwordx4 v134, s[46:47]
	s_mov_b32 m0, s31
	s_nop 0
	global_load_lds_dwordx4 v130, s[46:47]
	s_waitcnt lgkmcnt(8)
	s_barrier
	s_waitcnt lgkmcnt(0)
	s_setprio 1
	s_waitcnt lgkmcnt(0)
	v_mfma_f32_16x16x32_bf16 v[124:127], v[144:147], v[172:175], v[124:127]
	v_mfma_f32_16x16x32_bf16 v[120:123], v[164:167], v[172:175], v[120:123]
	v_mfma_f32_16x16x32_bf16 v[108:111], v[144:147], v[180:183], v[108:111]
	v_mfma_f32_16x16x32_bf16 v[104:107], v[164:167], v[180:183], v[104:107]
	v_mfma_f32_16x16x32_bf16 v[92:95], v[144:147], v[188:191], v[92:95]
	v_mfma_f32_16x16x32_bf16 v[88:91], v[164:167], v[188:191], v[88:91]
	v_mfma_f32_16x16x32_bf16 v[76:79], v[144:147], v[196:199], v[76:79]
	v_mfma_f32_16x16x32_bf16 v[72:75], v[164:167], v[196:199], v[72:75]
	v_mfma_f32_16x16x32_bf16 v[124:127], v[160:163], v[176:179], v[124:127]
	v_mfma_f32_16x16x32_bf16 v[120:123], v[168:171], v[176:179], v[120:123]
	v_mfma_f32_16x16x32_bf16 v[108:111], v[160:163], v[184:187], v[108:111]
	v_mfma_f32_16x16x32_bf16 v[104:107], v[168:171], v[184:187], v[104:107]
	v_mfma_f32_16x16x32_bf16 v[92:95], v[160:163], v[192:195], v[92:95]
	v_mfma_f32_16x16x32_bf16 v[88:91], v[168:171], v[192:195], v[88:91]
	v_mfma_f32_16x16x32_bf16 v[76:79], v[160:163], v[200:203], v[76:79]
	v_mfma_f32_16x16x32_bf16 v[72:75], v[168:171], v[200:203], v[72:75]
	s_setprio 0
	s_barrier
	s_add_i32 s46, 0, 0x1c000
	s_add_i32 s47, s55, s10
	v_add_u32_e32 v216, s46, v151
	v_lshl_add_u64 v[148:149], v[148:149], 0, s[8:9]
	s_mov_b32 m0, s47
	ds_read_b128 v[204:207], v216
	ds_read_b128 v[208:211], v216 offset:1024
	ds_read_b128 v[212:215], v216 offset:2048
	ds_read_b128 v[216:219], v216 offset:3072
	global_load_lds_dwordx4 v[148:149], off
	v_lshl_add_u64 v[148:149], v[156:157], 0, s[8:9]
	s_add_i32 m0, s47, 0x2000
	s_nop 0
	global_load_lds_dwordx4 v[148:149], off
	s_barrier
	s_waitcnt lgkmcnt(0)
	s_setprio 1
	s_waitcnt lgkmcnt(0)
	v_mfma_f32_16x16x32_bf16 v[116:119], v[204:207], v[172:175], v[116:119]
	v_mfma_f32_16x16x32_bf16 v[112:115], v[212:215], v[172:175], v[112:115]
	v_mfma_f32_16x16x32_bf16 v[100:103], v[204:207], v[180:183], v[100:103]
	v_mfma_f32_16x16x32_bf16 v[96:99], v[212:215], v[180:183], v[96:99]
	v_mfma_f32_16x16x32_bf16 v[84:87], v[204:207], v[188:191], v[84:87]
	v_mfma_f32_16x16x32_bf16 v[80:83], v[212:215], v[188:191], v[80:83]
	v_mfma_f32_16x16x32_bf16 v[68:71], v[204:207], v[196:199], v[68:71]
	v_mfma_f32_16x16x32_bf16 v[64:67], v[212:215], v[196:199], v[64:67]
	v_mfma_f32_16x16x32_bf16 v[116:119], v[208:211], v[176:179], v[116:119]
	v_mfma_f32_16x16x32_bf16 v[112:115], v[216:219], v[176:179], v[112:115]
	v_mfma_f32_16x16x32_bf16 v[100:103], v[208:211], v[184:187], v[100:103]
	v_mfma_f32_16x16x32_bf16 v[96:99], v[216:219], v[184:187], v[96:99]
	v_mfma_f32_16x16x32_bf16 v[84:87], v[208:211], v[192:195], v[84:87]
	v_mfma_f32_16x16x32_bf16 v[80:83], v[216:219], v[192:195], v[80:83]
	v_mfma_f32_16x16x32_bf16 v[68:71], v[208:211], v[200:203], v[68:71]
	v_mfma_f32_16x16x32_bf16 v[64:67], v[216:219], v[200:203], v[64:67]
	s_setprio 0
	s_mov_b32 m0, s36
	v_lshl_add_u64 v[148:149], v[220:221], 0, s[8:9]
	s_barrier
	ds_read_b128 v[172:175], v154 offset:49152
	ds_read_b128 v[176:179], v154 offset:50176
	ds_read_b128 v[180:183], v154 offset:51200
	ds_read_b128 v[184:187], v154 offset:52224
	ds_read_b128 v[188:191], v154 offset:53248
	ds_read_b128 v[192:195], v154 offset:54272
	ds_read_b128 v[196:199], v154 offset:55296
	ds_read_b128 v[200:203], v154 offset:56320
	global_load_lds_dwordx4 v[148:149], off
	v_lshl_add_u64 v[148:149], v[222:223], 0, s[8:9]
	s_mov_b32 m0, s37
	s_nop 0
	global_load_lds_dwordx4 v[148:149], off
	s_barrier
; __device__ __forceinline__ float fast_rcp(float x) { return __builtin_amdgcn_rcpf(x); }
; __device__ __forceinline__ float fast_exp2(float x) { return __builtin_amdgcn_exp2f(x); }
; #define PG8_STAGE(bufoff, gbase, voff) do { _Pragma("unroll") for (int _i = 0; _i < 2; ++_i) \
;         __builtin_amdgcn_global_load_lds((const unsigned*)((const char*)(gbase) + (voff)[_i]), (LAS unsigned*)(lds + (bufoff) + ldsw + _i * 8192), 16, 0, 0); } while (0)
; #define PG8_MMA(ai, bj, At, Bt) do { __builtin_amdgcn_s_setprio(1); _Pragma("unroll") for (int m = 0; m < 4; ++m) _Pragma("unroll") for (int n = 0; n < 2; ++n) _Pragma("unroll") for (int k = 0; k < 2; ++k) \
;         acc[ai][bj][m][n] = __builtin_amdgcn_mfma_f32_16x16x32_bf16(Bt[n][k], At[m][k], acc[ai][bj][m][n], 0, 0, 0); __builtin_amdgcn_s_setprio(0); } while (0)
; #define PG8_WAIT_V(n) asm volatile("s_waitcnt vmcnt(" #n ")" ::: "memory")
; #define PG8_BAR __builtin_amdgcn_s_barrier()
; template <class Epi>
; __device__ __forceinline__ void gemm_phase(LAS unsigned char* lds, const Gemm g, const StaticOrder& S, const Epi& E) {
;     ...
;             PG8_STAGE(PG8_SB(1, 1), b3 + hstep, voffB);
;             PG8_WAIT_V(6); PG8_BAR; PG8_MMA(1, 1, At, B1); PG8_BAR;
;         }
;         E(acc, cur, wr, wc, fr, fq);
;     __device__ __forceinline__ void operator()(const f32x4 (&acc)[2][2][4][2], const Unit& u, int wr, int wc, int fr, int fq) const {
;         const int row0 = u.pm * BM + wr * 64 + fr, col0 = u.pn * HALF + wc * 32 + 8 * fq;
; #pragma unroll
;         for (int ai = 0; ai < 2; ++ai)
; #pragma unroll
;             for (int m = 0; m < 4; ++m) { bf16_t* rowp = O + (size_t)(row0 + ai * HALF + m * 16) * DFF + col0;
;                 const float r = rs[row0 + ai * HALF + m * 16], r2 = r * r;
;                 f32x4 h0, h1;
; #pragma unroll
;                 for (int j = 0; j < 4; ++j) {
;                     const float g0 = acc[ai][0][m][0][j], g1 = acc[ai][0][m][1][j];
;                     h0[j] = g0 * r2 * fast_rcp(1.0f + fast_exp2(g0 * (-LOG2E * r))) * acc[ai][1][m][0][j];
;                     h1[j] = g1 * r2 * fast_rcp(1.0f + fast_exp2(g1 * (-LOG2E * r))) * acc[ai][1][m][1][j]; }
;                 *(u32x4*)rowp = pack8(h0, h1); }
	s_waitcnt lgkmcnt(0)
	s_setprio 1
	s_waitcnt lgkmcnt(0)
	v_mfma_f32_16x16x32_bf16 v[60:63], v[144:147], v[172:175], v[60:63]
	v_mfma_f32_16x16x32_bf16 v[56:59], v[164:167], v[172:175], v[56:59]
	v_mfma_f32_16x16x32_bf16 v[44:47], v[144:147], v[180:183], v[44:47]
	v_mfma_f32_16x16x32_bf16 v[40:43], v[164:167], v[180:183], v[40:43]
	v_mfma_f32_16x16x32_bf16 v[28:31], v[144:147], v[188:191], v[28:31]
	v_mfma_f32_16x16x32_bf16 v[24:27], v[164:167], v[188:191], v[24:27]
	v_mfma_f32_16x16x32_bf16 v[12:15], v[144:147], v[196:199], v[12:15]
	v_mfma_f32_16x16x32_bf16 v[8:11], v[164:167], v[196:199], v[8:11]
	v_mfma_f32_16x16x32_bf16 v[60:63], v[160:163], v[176:179], v[60:63]
	v_mfma_f32_16x16x32_bf16 v[56:59], v[168:171], v[176:179], v[56:59]
	v_mfma_f32_16x16x32_bf16 v[44:47], v[160:163], v[184:187], v[44:47]
	v_mfma_f32_16x16x32_bf16 v[40:43], v[168:171], v[184:187], v[40:43]
	v_mfma_f32_16x16x32_bf16 v[28:31], v[160:163], v[192:195], v[28:31]
	v_mfma_f32_16x16x32_bf16 v[24:27], v[168:171], v[192:195], v[24:27]
	v_mfma_f32_16x16x32_bf16 v[12:15], v[160:163], v[200:203], v[12:15]
	v_mfma_f32_16x16x32_bf16 v[8:11], v[168:171], v[200:203], v[8:11]
	s_setprio 0
	s_barrier
	s_add_u32 s44, s44, 0x80080
	s_addc_u32 s45, s45, 0
	s_add_i32 s46, s46, s10
	s_mov_b32 m0, s46
	s_nop 0
	global_load_lds_dwordx4 v132, s[44:45]
	s_add_i32 m0, s46, 0x2000
	s_nop 0
	global_load_lds_dwordx4 v128, s[44:45]
	s_waitcnt vmcnt(6)
	s_barrier
	s_setprio 1
	v_mfma_f32_16x16x32_bf16 v[52:55], v[204:207], v[172:175], v[52:55]
	v_mfma_f32_16x16x32_bf16 v[48:51], v[212:215], v[172:175], v[48:51]
	v_mfma_f32_16x16x32_bf16 v[36:39], v[204:207], v[180:183], v[36:39]
	v_mfma_f32_16x16x32_bf16 v[32:35], v[212:215], v[180:183], v[32:35]
	v_mfma_f32_16x16x32_bf16 v[20:23], v[204:207], v[188:191], v[20:23]
	v_mfma_f32_16x16x32_bf16 v[16:19], v[212:215], v[188:191], v[16:19]
	v_mfma_f32_16x16x32_bf16 v[4:7], v[204:207], v[196:199], v[4:7]
	v_mfma_f32_16x16x32_bf16 v[0:3], v[212:215], v[196:199], v[0:3]
	v_mfma_f32_16x16x32_bf16 v[52:55], v[208:211], v[176:179], v[52:55]
	v_mfma_f32_16x16x32_bf16 v[48:51], v[216:219], v[176:179], v[48:51]
	v_mfma_f32_16x16x32_bf16 v[36:39], v[208:211], v[184:187], v[36:39]
	v_mfma_f32_16x16x32_bf16 v[32:35], v[216:219], v[184:187], v[32:35]
	v_mfma_f32_16x16x32_bf16 v[20:23], v[208:211], v[192:195], v[20:23]
	v_mfma_f32_16x16x32_bf16 v[16:19], v[216:219], v[192:195], v[16:19]
	v_mfma_f32_16x16x32_bf16 v[4:7], v[208:211], v[200:203], v[4:7]
	v_mfma_f32_16x16x32_bf16 v[0:3], v[216:219], v[200:203], v[0:3]
	s_setprio 0
	s_add_i32 s54, s54, 2
	s_add_u32 s42, s42, 0x100
	s_addc_u32 s43, s43, 0
	s_add_u32 s52, s52, 0x100
	s_addc_u32 s53, s53, 0
	s_cmp_gt_u32 s54, 29
	s_barrier
	s_cbranch_scc0 .LBB0_203
	v_lshl_add_u32 v144, s40, 8, v150
	v_ashrrev_i32_e32 v145, 31, v144
	v_lshl_add_u64 v[148:149], v[144:145], 2, s[14:15]
	v_mov_b32_e32 v145, v224
	v_mov_b32_e32 v204, v225
	v_mov_b32_e32 v205, v226
	v_mov_b32_e32 v206, v227
	v_mov_b32_e32 v207, v228
	v_mov_b32_e32 v208, v229
	v_mov_b32_e32 v209, v230
	v_mov_b32_e32 v210, v231
	v_lshl_or_b32 v156, s34, 7, v152
	v_ashrrev_i32_e32 v157, 31, v156
	v_mov_b64_e32 v[146:147], s[20:21]
	v_mad_i64_i32 v[160:161], s[42:43], v144, s49, v[146:147]
	s_and_b64 vcc, exec, s[4:5]
	s_mov_b32 s34, s22
	s_mov_b32 s40, s24
	s_mov_b64 s[44:45], s[28:29]
	v_mul_f32_e32 v162, v145, v145
	v_mul_f32_e32 v145, 0xbfb8aa3b, v145
	v_mul_f32_e32 v163, v124, v162
	v_mul_f32_e32 v124, v124, v145
	v_exp_f32_e32 v124, v124
	s_nop 0
	v_add_f32_e32 v124, 1.0, v124
	v_rcp_f32_e32 v124, v124
	s_nop 0
	v_mul_f32_e32 v124, v163, v124
	v_mul_f32_e32 v116, v116, v124
	v_mul_f32_e32 v124, v120, v162
	v_mul_f32_e32 v120, v120, v145
	v_exp_f32_e32 v120, v120
	s_nop 0
	v_add_f32_e32 v120, 1.0, v120
	v_rcp_f32_e32 v120, v120
	s_nop 0
	v_mul_f32_e32 v120, v124, v120
	v_mul_f32_e32 v124, v125, v145
	v_exp_f32_e32 v124, v124
	v_mul_f32_e32 v120, v112, v120
	v_mul_f32_e32 v112, v125, v162
	v_add_f32_e32 v124, 1.0, v124
	v_rcp_f32_e32 v124, v124
	s_nop 0
	v_mul_f32_e32 v112, v112, v124
	v_mul_f32_e32 v117, v117, v112
	v_mul_f32_e32 v112, v121, v162
	v_mul_f32_e32 v121, v121, v145
	v_exp_f32_e32 v121, v121
	s_nop 0
	v_add_f32_e32 v121, 1.0, v121
	v_rcp_f32_e32 v121, v121
	s_nop 0
	v_mul_f32_e32 v112, v112, v121
	v_mul_f32_e32 v121, v113, v112
	v_mul_f32_e32 v113, v126, v145
	v_exp_f32_e32 v113, v113
	v_mul_f32_e32 v112, v126, v162
	v_add_f32_e32 v113, 1.0, v113
	v_rcp_f32_e32 v113, v113
	s_nop 0
	v_mul_f32_e32 v112, v112, v113
	v_mul_f32_e32 v113, v122, v145
	v_exp_f32_e32 v113, v113
	v_mul_f32_e32 v124, v118, v112
	v_mul_f32_e32 v112, v122, v162
	v_add_f32_e32 v113, 1.0, v113
	v_rcp_f32_e32 v113, v113
	s_nop 0
	v_mul_f32_e32 v112, v112, v113
	v_mul_f32_e32 v113, v127, v145
	v_exp_f32_e32 v113, v113
	v_mul_f32_e32 v122, v114, v112
	v_mul_f32_e32 v112, v127, v162
	v_cvt_pk_bf16_f32 v114, v116, v117
	v_add_f32_e32 v113, 1.0, v113
	v_rcp_f32_e32 v113, v113
	s_nop 0
	v_mul_f32_e32 v112, v112, v113
	v_mul_f32_e32 v113, v123, v145
	v_exp_f32_e32 v113, v113
	v_mul_f32_e32 v125, v119, v112
	v_mul_f32_e32 v112, v123, v162
	v_add_f32_e32 v113, 1.0, v113
	v_rcp_f32_e32 v113, v113
	s_nop 0
	v_mul_f32_e32 v112, v112, v113
	v_mul_f32_e32 v123, v115, v112
	v_lshlrev_b64 v[112:113], 1, v[156:157]
	v_lshl_add_u64 v[118:119], v[160:161], 0, v[112:113]
	v_cvt_pk_bf16_f32 v115, v124, v125
	v_cvt_pk_bf16_f32 v116, v120, v121
	v_cvt_pk_bf16_f32 v117, v122, v123
	global_store_dwordx4 v[118:119], v[114:117], off
	s_nop 1
	v_mov_b32_e32 v116, v204
	s_nop 0
	v_or_b32_e32 v114, 16, v144
	v_mad_i64_i32 v[114:115], s[42:43], v114, s49, v[146:147]
	v_mul_f32_e32 v117, v116, v116
; __device__ __forceinline__ float fast_rcp(float x) { return __builtin_amdgcn_rcpf(x); }
; __device__ __forceinline__ float fast_exp2(float x) { return __builtin_amdgcn_exp2f(x); }
; __device__ __forceinline__ u32x4 pack8(f32x4 v0, f32x4 v1) { u32x4 w; w.x = cvt_pk_bf16(v0[0], v0[1]); w.y = cvt_pk_bf16(v0[2], v0[3]); w.z = cvt_pk_bf16(v1[0], v1[1]); w.w = cvt_pk_bf16(v1[2], v1[3]); return w; }
;     __device__ __forceinline__ void operator()(const f32x4 (&acc)[2][2][4][2], const Unit& u, int wr, int wc, int fr, int fq) const {
;         const int row0 = u.pm * BM + wr * 64 + fr, col0 = u.pn * HALF + wc * 32 + 8 * fq;
; #pragma unroll
;         for (int ai = 0; ai < 2; ++ai)
; #pragma unroll
;             for (int m = 0; m < 4; ++m) { bf16_t* rowp = O + (size_t)(row0 + ai * HALF + m * 16) * DFF + col0;
;                 const float r = rs[row0 + ai * HALF + m * 16], r2 = r * r;
;                 f32x4 h0, h1;
; #pragma unroll
;                 for (int j = 0; j < 4; ++j) {
;                     const float g0 = acc[ai][0][m][0][j], g1 = acc[ai][0][m][1][j];
;                     h0[j] = g0 * r2 * fast_rcp(1.0f + fast_exp2(g0 * (-LOG2E * r))) * acc[ai][1][m][0][j];
;                     h1[j] = g1 * r2 * fast_rcp(1.0f + fast_exp2(g1 * (-LOG2E * r))) * acc[ai][1][m][1][j]; }
;                 *(u32x4*)rowp = pack8(h0, h1); }
	v_mul_f32_e32 v116, 0xbfb8aa3b, v116
	v_mul_f32_e32 v118, v108, v117
	v_mul_f32_e32 v108, v108, v116
	v_exp_f32_e32 v108, v108
	s_nop 0
	v_add_f32_e32 v108, 1.0, v108
	v_rcp_f32_e32 v108, v108
	s_nop 0
	v_mul_f32_e32 v108, v118, v108
	v_mul_f32_e32 v108, v100, v108
	v_mul_f32_e32 v100, v104, v117
	v_mul_f32_e32 v104, v104, v116
	v_exp_f32_e32 v104, v104
	s_nop 0
	v_add_f32_e32 v104, 1.0, v104
	v_rcp_f32_e32 v104, v104
	s_nop 0
	v_mul_f32_e32 v100, v100, v104
	v_mul_f32_e32 v104, v96, v100
	v_mul_f32_e32 v100, v109, v116
	v_exp_f32_e32 v100, v100
	v_mul_f32_e32 v96, v109, v117
	v_add_f32_e32 v100, 1.0, v100
	v_rcp_f32_e32 v100, v100
	s_nop 0
	v_mul_f32_e32 v96, v96, v100
	v_mul_f32_e32 v96, v101, v96
	v_mul_f32_e32 v101, v105, v116
	v_exp_f32_e32 v101, v101
	v_mul_f32_e32 v100, v105, v117
	v_cvt_pk_bf16_f32 v96, v108, v96
	v_add_f32_e32 v101, 1.0, v101
	v_rcp_f32_e32 v101, v101
	s_nop 0
	v_mul_f32_e32 v100, v100, v101
	v_mul_f32_e32 v105, v97, v100
	v_mul_f32_e32 v100, v110, v116
	v_exp_f32_e32 v100, v100
	v_mul_f32_e32 v101, v106, v116
	v_exp_f32_e32 v101, v101
	v_mul_f32_e32 v97, v110, v117
	v_add_f32_e32 v100, 1.0, v100
	v_rcp_f32_e32 v100, v100
	v_add_f32_e32 v101, 1.0, v101
	v_rcp_f32_e32 v101, v101
	v_mul_f32_e32 v97, v97, v100
	v_mul_f32_e32 v100, v106, v117
	v_mul_f32_e32 v100, v100, v101
	v_mul_f32_e32 v97, v102, v97
	v_mul_f32_e32 v102, v98, v100
	v_mul_f32_e32 v100, v111, v116
	v_exp_f32_e32 v100, v100
	v_mul_f32_e32 v101, v107, v116
	v_exp_f32_e32 v101, v101
	v_mul_f32_e32 v98, v111, v117
	v_add_f32_e32 v100, 1.0, v100
	v_rcp_f32_e32 v100, v100
	v_add_f32_e32 v101, 1.0, v101
	v_rcp_f32_e32 v101, v101
	v_mul_f32_e32 v98, v98, v100
	v_mul_f32_e32 v100, v107, v117
	v_mul_f32_e32 v100, v100, v101
	v_mul_f32_e32 v98, v103, v98
	v_mul_f32_e32 v99, v99, v100
	v_lshl_add_u64 v[100:101], v[114:115], 0, v[112:113]
	v_cvt_pk_bf16_f32 v97, v97, v98
	v_cvt_pk_bf16_f32 v98, v104, v105
	v_cvt_pk_bf16_f32 v99, v102, v99
	global_store_dwordx4 v[100:101], v[96:99], off
	s_nop 1
	v_mov_b32_e32 v98, v205
	s_nop 0
	v_or_b32_e32 v96, 32, v144
	v_mad_i64_i32 v[96:97], s[42:43], v96, s49, v[146:147]
	v_mul_f32_e32 v99, v98, v98
	v_mul_f32_e32 v98, 0xbfb8aa3b, v98
	v_mul_f32_e32 v100, v92, v99
	v_mul_f32_e32 v92, v92, v98
	v_exp_f32_e32 v92, v92
	s_nop 0
	v_add_f32_e32 v92, 1.0, v92
	v_rcp_f32_e32 v92, v92
	s_nop 0
	v_mul_f32_e32 v92, v100, v92
	v_mul_f32_e32 v92, v84, v92
	v_mul_f32_e32 v84, v88, v99
	v_mul_f32_e32 v88, v88, v98
	v_exp_f32_e32 v88, v88
	s_nop 0
	v_add_f32_e32 v88, 1.0, v88
	v_rcp_f32_e32 v88, v88
	s_nop 0
	v_mul_f32_e32 v84, v84, v88
	v_mul_f32_e32 v88, v80, v84
	v_mul_f32_e32 v84, v93, v98
	v_exp_f32_e32 v84, v84
	v_mul_f32_e32 v80, v93, v99
	v_add_f32_e32 v84, 1.0, v84
	v_rcp_f32_e32 v84, v84
	s_nop 0
	v_mul_f32_e32 v80, v80, v84
	v_mul_f32_e32 v80, v85, v80
	v_mul_f32_e32 v85, v89, v98
	v_exp_f32_e32 v85, v85
	v_mul_f32_e32 v84, v89, v99
	v_cvt_pk_bf16_f32 v80, v92, v80
	v_add_f32_e32 v85, 1.0, v85
	v_rcp_f32_e32 v85, v85
	s_nop 0
	v_mul_f32_e32 v84, v84, v85
	v_mul_f32_e32 v89, v81, v84
	v_mul_f32_e32 v84, v94, v98
	v_exp_f32_e32 v84, v84
	v_mul_f32_e32 v85, v90, v98
	v_exp_f32_e32 v85, v85
	v_mul_f32_e32 v81, v94, v99
	v_add_f32_e32 v84, 1.0, v84
	v_rcp_f32_e32 v84, v84
	v_add_f32_e32 v85, 1.0, v85
	v_rcp_f32_e32 v85, v85
	v_mul_f32_e32 v81, v81, v84
	v_mul_f32_e32 v84, v90, v99
	v_mul_f32_e32 v84, v84, v85
	v_mul_f32_e32 v81, v86, v81
	v_mul_f32_e32 v86, v82, v84
	v_mul_f32_e32 v84, v95, v98
	v_exp_f32_e32 v84, v84
	v_mul_f32_e32 v85, v91, v98
	v_exp_f32_e32 v85, v85
	v_mul_f32_e32 v82, v95, v99
	v_add_f32_e32 v84, 1.0, v84
	v_rcp_f32_e32 v84, v84
	v_add_f32_e32 v85, 1.0, v85
	v_rcp_f32_e32 v85, v85
	v_mul_f32_e32 v82, v82, v84
	v_mul_f32_e32 v84, v91, v99
	v_mul_f32_e32 v84, v84, v85
	v_mul_f32_e32 v82, v87, v82
	v_mul_f32_e32 v83, v83, v84
	v_lshl_add_u64 v[84:85], v[96:97], 0, v[112:113]
	v_cvt_pk_bf16_f32 v81, v81, v82
	v_cvt_pk_bf16_f32 v82, v88, v89
	v_cvt_pk_bf16_f32 v83, v86, v83
	global_store_dwordx4 v[84:85], v[80:83], off
	s_nop 1
	v_mov_b32_e32 v82, v206
	s_nop 0
	v_or_b32_e32 v80, 48, v144
	v_mad_i64_i32 v[80:81], s[42:43], v80, s49, v[146:147]
	v_mul_f32_e32 v83, v82, v82
	v_mul_f32_e32 v82, 0xbfb8aa3b, v82
	v_mul_f32_e32 v84, v76, v83
	v_mul_f32_e32 v76, v76, v82
	v_exp_f32_e32 v76, v76
	s_nop 0
	v_add_f32_e32 v76, 1.0, v76
	v_rcp_f32_e32 v76, v76
	s_nop 0
	v_mul_f32_e32 v76, v84, v76
	v_mul_f32_e32 v76, v68, v76
	v_mul_f32_e32 v68, v72, v83
	v_mul_f32_e32 v72, v72, v82
	v_exp_f32_e32 v72, v72
	s_nop 0
	v_add_f32_e32 v72, 1.0, v72
	v_rcp_f32_e32 v72, v72
	s_nop 0
	v_mul_f32_e32 v68, v68, v72
	v_mul_f32_e32 v72, v64, v68
	v_mul_f32_e32 v68, v77, v82
	v_exp_f32_e32 v68, v68
	v_mul_f32_e32 v64, v77, v83
	v_add_f32_e32 v68, 1.0, v68
	v_rcp_f32_e32 v68, v68
	s_nop 0
	v_mul_f32_e32 v64, v64, v68
	v_mul_f32_e32 v64, v69, v64
	v_mul_f32_e32 v69, v73, v82
	v_exp_f32_e32 v69, v69
	v_mul_f32_e32 v68, v73, v83
	v_cvt_pk_bf16_f32 v64, v76, v64
	v_add_f32_e32 v69, 1.0, v69
	v_rcp_f32_e32 v69, v69
	s_nop 0
	v_mul_f32_e32 v68, v68, v69
	v_mul_f32_e32 v73, v65, v68
	v_mul_f32_e32 v68, v78, v82
	v_exp_f32_e32 v68, v68
	v_mul_f32_e32 v69, v74, v82
	v_exp_f32_e32 v69, v69
	v_mul_f32_e32 v65, v78, v83
	v_add_f32_e32 v68, 1.0, v68
	v_rcp_f32_e32 v68, v68
	v_add_f32_e32 v69, 1.0, v69
	v_rcp_f32_e32 v69, v69
	v_mul_f32_e32 v65, v65, v68
	v_mul_f32_e32 v68, v74, v83
	v_mul_f32_e32 v68, v68, v69
	v_mul_f32_e32 v65, v70, v65
	v_mul_f32_e32 v70, v66, v68
	v_mul_f32_e32 v68, v79, v82
	v_exp_f32_e32 v68, v68
	v_mul_f32_e32 v69, v75, v82
	v_exp_f32_e32 v69, v69
	v_mul_f32_e32 v66, v79, v83
	v_add_f32_e32 v68, 1.0, v68
	v_rcp_f32_e32 v68, v68
; __device__ __forceinline__ float fast_rcp(float x) { return __builtin_amdgcn_rcpf(x); }
; __device__ __forceinline__ float fast_exp2(float x) { return __builtin_amdgcn_exp2f(x); }
; __device__ __forceinline__ u32x4 pack8(f32x4 v0, f32x4 v1) { u32x4 w; w.x = cvt_pk_bf16(v0[0], v0[1]); w.y = cvt_pk_bf16(v0[2], v0[3]); w.z = cvt_pk_bf16(v1[0], v1[1]); w.w = cvt_pk_bf16(v1[2], v1[3]); return w; }
;     __device__ __forceinline__ void operator()(const f32x4 (&acc)[2][2][4][2], const Unit& u, int wr, int wc, int fr, int fq) const {
;         const int row0 = u.pm * BM + wr * 64 + fr, col0 = u.pn * HALF + wc * 32 + 8 * fq;
; #pragma unroll
;         for (int ai = 0; ai < 2; ++ai)
; #pragma unroll
;             for (int m = 0; m < 4; ++m) { bf16_t* rowp = O + (size_t)(row0 + ai * HALF + m * 16) * DFF + col0;
;                 const float r = rs[row0 + ai * HALF + m * 16], r2 = r * r;
;                 f32x4 h0, h1;
; #pragma unroll
;                 for (int j = 0; j < 4; ++j) {
;                     const float g0 = acc[ai][0][m][0][j], g1 = acc[ai][0][m][1][j];
;                     h0[j] = g0 * r2 * fast_rcp(1.0f + fast_exp2(g0 * (-LOG2E * r))) * acc[ai][1][m][0][j];
;                     h1[j] = g1 * r2 * fast_rcp(1.0f + fast_exp2(g1 * (-LOG2E * r))) * acc[ai][1][m][1][j]; }
;                 *(u32x4*)rowp = pack8(h0, h1); }
	v_add_f32_e32 v69, 1.0, v69
	v_rcp_f32_e32 v69, v69
	v_mul_f32_e32 v66, v66, v68
	v_mul_f32_e32 v68, v75, v83
	v_mul_f32_e32 v68, v68, v69
	v_mul_f32_e32 v66, v71, v66
	v_mul_f32_e32 v67, v67, v68
	v_lshl_add_u64 v[68:69], v[80:81], 0, v[112:113]
	v_cvt_pk_bf16_f32 v65, v65, v66
	v_cvt_pk_bf16_f32 v66, v72, v73
	v_cvt_pk_bf16_f32 v67, v70, v67
	global_store_dwordx4 v[68:69], v[64:67], off
	s_nop 1
	v_mov_b32_e32 v66, v207
	s_nop 0
	v_add_u32_e32 v64, 0x80, v144
	v_mad_i64_i32 v[64:65], s[42:43], v64, s49, v[146:147]
	v_mul_f32_e32 v67, v66, v66
	v_mul_f32_e32 v66, 0xbfb8aa3b, v66
	v_mul_f32_e32 v68, v60, v67
	v_mul_f32_e32 v60, v60, v66
	v_exp_f32_e32 v60, v60
	s_nop 0
	v_add_f32_e32 v60, 1.0, v60
	v_rcp_f32_e32 v60, v60
	s_nop 0
	v_mul_f32_e32 v60, v68, v60
	v_mul_f32_e32 v60, v52, v60
	v_mul_f32_e32 v52, v56, v67
	v_mul_f32_e32 v56, v56, v66
	v_exp_f32_e32 v56, v56
	s_nop 0
	v_add_f32_e32 v56, 1.0, v56
	v_rcp_f32_e32 v56, v56
	s_nop 0
	v_mul_f32_e32 v52, v52, v56
	v_mul_f32_e32 v56, v48, v52
	v_mul_f32_e32 v52, v61, v66
	v_exp_f32_e32 v52, v52
	v_mul_f32_e32 v48, v61, v67
	v_add_f32_e32 v52, 1.0, v52
	v_rcp_f32_e32 v52, v52
	s_nop 0
	v_mul_f32_e32 v48, v48, v52
	v_mul_f32_e32 v48, v53, v48
	v_mul_f32_e32 v53, v57, v66
	v_exp_f32_e32 v53, v53
	v_mul_f32_e32 v52, v57, v67
	v_cvt_pk_bf16_f32 v48, v60, v48
	v_add_f32_e32 v53, 1.0, v53
	v_rcp_f32_e32 v53, v53
	s_nop 0
	v_mul_f32_e32 v52, v52, v53
	v_mul_f32_e32 v57, v49, v52
	v_mul_f32_e32 v52, v62, v66
	v_exp_f32_e32 v52, v52
	v_mul_f32_e32 v53, v58, v66
	v_exp_f32_e32 v53, v53
	v_mul_f32_e32 v49, v62, v67
	v_add_f32_e32 v52, 1.0, v52
	v_rcp_f32_e32 v52, v52
	v_add_f32_e32 v53, 1.0, v53
	v_rcp_f32_e32 v53, v53
	v_mul_f32_e32 v49, v49, v52
	v_mul_f32_e32 v52, v58, v67
	v_mul_f32_e32 v52, v52, v53
	v_mul_f32_e32 v49, v54, v49
	v_mul_f32_e32 v54, v50, v52
	v_mul_f32_e32 v52, v63, v66
	v_exp_f32_e32 v52, v52
	v_mul_f32_e32 v53, v59, v66
	v_exp_f32_e32 v53, v53
	v_mul_f32_e32 v50, v63, v67
	v_add_f32_e32 v52, 1.0, v52
	v_rcp_f32_e32 v52, v52
	v_add_f32_e32 v53, 1.0, v53
	v_rcp_f32_e32 v53, v53
	v_mul_f32_e32 v50, v50, v52
	v_mul_f32_e32 v52, v59, v67
	v_mul_f32_e32 v52, v52, v53
	v_mul_f32_e32 v50, v55, v50
	v_mul_f32_e32 v51, v51, v52
	v_lshl_add_u64 v[52:53], v[64:65], 0, v[112:113]
	v_cvt_pk_bf16_f32 v49, v49, v50
	v_cvt_pk_bf16_f32 v50, v56, v57
	v_cvt_pk_bf16_f32 v51, v54, v51
	global_store_dwordx4 v[52:53], v[48:51], off
	s_nop 1
	v_mov_b32_e32 v50, v208
	s_nop 0
	v_add_u32_e32 v48, 0x90, v144
	v_mad_i64_i32 v[48:49], s[42:43], v48, s49, v[146:147]
	v_mul_f32_e32 v51, v50, v50
	v_mul_f32_e32 v50, 0xbfb8aa3b, v50
	v_mul_f32_e32 v52, v44, v51
	v_mul_f32_e32 v44, v44, v50
	v_exp_f32_e32 v44, v44
	s_nop 0
	v_add_f32_e32 v44, 1.0, v44
	v_rcp_f32_e32 v44, v44
	s_nop 0
	v_mul_f32_e32 v44, v52, v44
	v_mul_f32_e32 v44, v36, v44
	v_mul_f32_e32 v36, v40, v51
	v_mul_f32_e32 v40, v40, v50
	v_exp_f32_e32 v40, v40
	s_nop 0
	v_add_f32_e32 v40, 1.0, v40
	v_rcp_f32_e32 v40, v40
	s_nop 0
	v_mul_f32_e32 v36, v36, v40
	v_mul_f32_e32 v40, v32, v36
	v_mul_f32_e32 v36, v45, v50
	v_exp_f32_e32 v36, v36
	v_mul_f32_e32 v32, v45, v51
	v_add_f32_e32 v36, 1.0, v36
	v_rcp_f32_e32 v36, v36
	s_nop 0
	v_mul_f32_e32 v32, v32, v36
	v_mul_f32_e32 v32, v37, v32
	v_mul_f32_e32 v37, v41, v50
	v_exp_f32_e32 v37, v37
	v_mul_f32_e32 v36, v41, v51
	v_cvt_pk_bf16_f32 v32, v44, v32
	v_add_f32_e32 v37, 1.0, v37
	v_rcp_f32_e32 v37, v37
	s_nop 0
	v_mul_f32_e32 v36, v36, v37
	v_mul_f32_e32 v41, v33, v36
	v_mul_f32_e32 v36, v46, v50
	v_exp_f32_e32 v36, v36
	v_mul_f32_e32 v37, v42, v50
	v_exp_f32_e32 v37, v37
	v_mul_f32_e32 v33, v46, v51
	v_add_f32_e32 v36, 1.0, v36
	v_rcp_f32_e32 v36, v36
	v_add_f32_e32 v37, 1.0, v37
	v_rcp_f32_e32 v37, v37
	v_mul_f32_e32 v33, v33, v36
	v_mul_f32_e32 v36, v42, v51
	v_mul_f32_e32 v36, v36, v37
	v_mul_f32_e32 v33, v38, v33
	v_mul_f32_e32 v38, v34, v36
	v_mul_f32_e32 v36, v47, v50
	v_exp_f32_e32 v36, v36
	v_mul_f32_e32 v37, v43, v50
	v_exp_f32_e32 v37, v37
	v_mul_f32_e32 v34, v47, v51
	v_add_f32_e32 v36, 1.0, v36
	v_rcp_f32_e32 v36, v36
	v_add_f32_e32 v37, 1.0, v37
	v_rcp_f32_e32 v37, v37
	v_mul_f32_e32 v34, v34, v36
	v_mul_f32_e32 v36, v43, v51
	v_mul_f32_e32 v36, v36, v37
	v_mul_f32_e32 v34, v39, v34
	v_mul_f32_e32 v35, v35, v36
; __device__ __forceinline__ float fast_rcp(float x) { return __builtin_amdgcn_rcpf(x); }
; __device__ __forceinline__ float fast_exp2(float x) { return __builtin_amdgcn_exp2f(x); }
; #define PG8_WAIT_V(n) asm volatile("s_waitcnt vmcnt(" #n ")" ::: "memory")
; #define PG8_BAR __builtin_amdgcn_s_barrier()
; __device__ __forceinline__ u32x4 pack8(f32x4 v0, f32x4 v1) { u32x4 w; w.x = cvt_pk_bf16(v0[0], v0[1]); w.y = cvt_pk_bf16(v0[2], v0[3]); w.z = cvt_pk_bf16(v1[0], v1[1]); w.w = cvt_pk_bf16(v1[2], v1[3]); return w; }
; template <class Epi>
; __device__ __forceinline__ void gemm_phase(LAS unsigned char* lds, const Gemm g, const StaticOrder& S, const Epi& E) {
;     ...
;     PG8_WAIT_V(0);
;     if (wr == 0) PG8_BAR;
;     PG8_BAR;
;     __device__ __forceinline__ void operator()(const f32x4 (&acc)[2][2][4][2], const Unit& u, int wr, int wc, int fr, int fq) const {
;         const int row0 = u.pm * BM + wr * 64 + fr, col0 = u.pn * HALF + wc * 32 + 8 * fq;
; #pragma unroll
;         for (int ai = 0; ai < 2; ++ai)
; #pragma unroll
;             for (int m = 0; m < 4; ++m) { bf16_t* rowp = O + (size_t)(row0 + ai * HALF + m * 16) * DFF + col0;
;                 const float r = rs[row0 + ai * HALF + m * 16], r2 = r * r;
;                 f32x4 h0, h1;
; #pragma unroll
;                 for (int j = 0; j < 4; ++j) {
;                     const float g0 = acc[ai][0][m][0][j], g1 = acc[ai][0][m][1][j];
;                     h0[j] = g0 * r2 * fast_rcp(1.0f + fast_exp2(g0 * (-LOG2E * r))) * acc[ai][1][m][0][j];
;                     h1[j] = g1 * r2 * fast_rcp(1.0f + fast_exp2(g1 * (-LOG2E * r))) * acc[ai][1][m][1][j]; }
;                 *(u32x4*)rowp = pack8(h0, h1); }
	v_lshl_add_u64 v[36:37], v[48:49], 0, v[112:113]
	v_cvt_pk_bf16_f32 v33, v33, v34
	v_cvt_pk_bf16_f32 v34, v40, v41
	v_cvt_pk_bf16_f32 v35, v38, v35
	global_store_dwordx4 v[36:37], v[32:35], off
	s_nop 1
	v_mov_b32_e32 v34, v209
	s_nop 0
	v_add_u32_e32 v32, 0xa0, v144
	v_mad_i64_i32 v[32:33], s[42:43], v32, s49, v[146:147]
	v_mul_f32_e32 v35, v34, v34
	v_mul_f32_e32 v34, 0xbfb8aa3b, v34
	v_mul_f32_e32 v36, v28, v35
	v_mul_f32_e32 v28, v28, v34
	v_exp_f32_e32 v28, v28
	s_nop 0
	v_add_f32_e32 v28, 1.0, v28
	v_rcp_f32_e32 v28, v28
	s_nop 0
	v_mul_f32_e32 v28, v36, v28
	v_mul_f32_e32 v28, v20, v28
	v_mul_f32_e32 v20, v24, v35
	v_mul_f32_e32 v24, v24, v34
	v_exp_f32_e32 v24, v24
	s_nop 0
	v_add_f32_e32 v24, 1.0, v24
	v_rcp_f32_e32 v24, v24
	s_nop 0
	v_mul_f32_e32 v20, v20, v24
	v_mul_f32_e32 v24, v16, v20
	v_mul_f32_e32 v20, v29, v34
	v_exp_f32_e32 v20, v20
	v_mul_f32_e32 v16, v29, v35
	v_add_f32_e32 v20, 1.0, v20
	v_rcp_f32_e32 v20, v20
	s_nop 0
	v_mul_f32_e32 v16, v16, v20
	v_mul_f32_e32 v16, v21, v16
	v_mul_f32_e32 v21, v25, v34
	v_exp_f32_e32 v21, v21
	v_mul_f32_e32 v20, v25, v35
	v_cvt_pk_bf16_f32 v16, v28, v16
	v_add_f32_e32 v21, 1.0, v21
	v_rcp_f32_e32 v21, v21
	s_nop 0
	v_mul_f32_e32 v20, v20, v21
	v_mul_f32_e32 v25, v17, v20
	v_mul_f32_e32 v20, v30, v34
	v_exp_f32_e32 v20, v20
	v_mul_f32_e32 v21, v26, v34
	v_exp_f32_e32 v21, v21
	v_mul_f32_e32 v17, v30, v35
	v_add_f32_e32 v20, 1.0, v20
	v_rcp_f32_e32 v20, v20
	v_add_f32_e32 v21, 1.0, v21
	v_rcp_f32_e32 v21, v21
	v_mul_f32_e32 v17, v17, v20
	v_mul_f32_e32 v20, v26, v35
	v_mul_f32_e32 v20, v20, v21
	v_mul_f32_e32 v17, v22, v17
	v_mul_f32_e32 v22, v18, v20
	v_mul_f32_e32 v20, v31, v34
	v_exp_f32_e32 v20, v20
	v_mul_f32_e32 v21, v27, v34
	v_exp_f32_e32 v21, v21
	v_mul_f32_e32 v18, v31, v35
	v_add_f32_e32 v20, 1.0, v20
	v_rcp_f32_e32 v20, v20
	v_add_f32_e32 v21, 1.0, v21
	v_rcp_f32_e32 v21, v21
	v_mul_f32_e32 v18, v18, v20
	v_mul_f32_e32 v20, v27, v35
	v_mul_f32_e32 v20, v20, v21
	v_mul_f32_e32 v18, v23, v18
	v_mul_f32_e32 v19, v19, v20
	v_lshl_add_u64 v[20:21], v[32:33], 0, v[112:113]
	v_cvt_pk_bf16_f32 v17, v17, v18
	v_cvt_pk_bf16_f32 v18, v24, v25
	v_cvt_pk_bf16_f32 v19, v22, v19
	global_store_dwordx4 v[20:21], v[16:19], off
	s_nop 1
	v_mov_b32_e32 v18, v210
	s_nop 0
	v_add_u32_e32 v16, 0xb0, v144
	v_mad_i64_i32 v[16:17], s[42:43], v16, s49, v[146:147]
	s_mov_b64 s[42:43], s[26:27]
	v_mul_f32_e32 v19, v18, v18
	v_mul_f32_e32 v18, 0xbfb8aa3b, v18
	v_mul_f32_e32 v20, v12, v19
	v_mul_f32_e32 v12, v12, v18
	v_exp_f32_e32 v12, v12
	s_nop 0
	v_add_f32_e32 v12, 1.0, v12
	v_rcp_f32_e32 v12, v12
	s_nop 0
	v_mul_f32_e32 v12, v20, v12
	v_mul_f32_e32 v12, v4, v12
	v_mul_f32_e32 v4, v8, v19
	v_mul_f32_e32 v8, v8, v18
	v_exp_f32_e32 v8, v8
	s_nop 0
	v_add_f32_e32 v8, 1.0, v8
	v_rcp_f32_e32 v8, v8
	s_nop 0
	v_mul_f32_e32 v4, v4, v8
	v_mul_f32_e32 v8, v0, v4
	v_mul_f32_e32 v4, v13, v18
	v_exp_f32_e32 v4, v4
	v_mul_f32_e32 v0, v13, v19
	v_add_f32_e32 v4, 1.0, v4
	v_rcp_f32_e32 v4, v4
	s_nop 0
	v_mul_f32_e32 v0, v0, v4
	v_mul_f32_e32 v0, v5, v0
	v_mul_f32_e32 v5, v9, v18
	v_exp_f32_e32 v5, v5
	v_mul_f32_e32 v4, v9, v19
	v_cvt_pk_bf16_f32 v0, v12, v0
	v_add_f32_e32 v5, 1.0, v5
	v_rcp_f32_e32 v5, v5
	s_nop 0
	v_mul_f32_e32 v4, v4, v5
	v_mul_f32_e32 v9, v1, v4
	v_mul_f32_e32 v4, v14, v18
	v_exp_f32_e32 v4, v4
	v_mul_f32_e32 v5, v10, v18
	v_exp_f32_e32 v5, v5
	v_mul_f32_e32 v1, v14, v19
	v_add_f32_e32 v4, 1.0, v4
	v_rcp_f32_e32 v4, v4
	v_add_f32_e32 v5, 1.0, v5
	v_rcp_f32_e32 v5, v5
	v_mul_f32_e32 v1, v1, v4
	v_mul_f32_e32 v4, v10, v19
	v_mul_f32_e32 v4, v4, v5
	v_mul_f32_e32 v1, v6, v1
	v_mul_f32_e32 v6, v2, v4
	v_mul_f32_e32 v4, v15, v18
	v_exp_f32_e32 v4, v4
	v_mul_f32_e32 v5, v11, v18
	v_exp_f32_e32 v5, v5
	v_mul_f32_e32 v2, v15, v19
	v_add_f32_e32 v4, 1.0, v4
	v_rcp_f32_e32 v4, v4
	v_add_f32_e32 v5, 1.0, v5
	v_rcp_f32_e32 v5, v5
	v_mul_f32_e32 v2, v2, v4
	v_mul_f32_e32 v4, v11, v19
	v_mul_f32_e32 v4, v4, v5
	v_mul_f32_e32 v2, v7, v2
	v_mul_f32_e32 v3, v3, v4
	v_lshl_add_u64 v[4:5], v[16:17], 0, v[112:113]
	v_cvt_pk_bf16_f32 v1, v1, v2
	v_cvt_pk_bf16_f32 v2, v8, v9
	v_cvt_pk_bf16_f32 v3, v6, v3
	global_store_dwordx4 v[4:5], v[0:3], off
	s_cbranch_vccz .LBB0_200
	s_waitcnt vmcnt(0)
	s_cmpk_gt_u32 s3, 0xff
	s_cbranch_scc1 .LBB0_207
	s_barrier

; #define PG8_STAGE(bufoff, gbase, voff) do { _Pragma("unroll") for (int _i = 0; _i < 2; ++_i) \
;         __builtin_amdgcn_global_load_lds((const unsigned*)((const char*)(gbase) + (voff)[_i]), (LAS unsigned*)(lds + (bufoff) + ldsw + _i * 8192), 16, 0, 0); } while (0)
; #define PG8_LDA(dst, b, h) do { _Pragma("unroll") for (int m = 0; m < 4; ++m) _Pragma("unroll") for (int k = 0; k < 2; ++k) dst[m][k] = *(const LAS bf16x8*)(lds + PG8_SA(b, h) + aoff + m * 2048 + k * 1024); } while (0)
; #define PG8_LDB(dst, b, h) do { _Pragma("unroll") for (int n = 0; n < 2; ++n) _Pragma("unroll") for (int k = 0; k < 2; ++k) dst[n][k] = *(const LAS bf16x8*)(lds + PG8_SB(b, h) + boff + n * 2048 + k * 1024); } while (0)
; #define PG8_MMA(ai, bj, At, Bt) do { __builtin_amdgcn_s_setprio(1); _Pragma("unroll") for (int m = 0; m < 4; ++m) _Pragma("unroll") for (int n = 0; n < 2; ++n) _Pragma("unroll") for (int k = 0; k < 2; ++k) \
;         acc[ai][bj][m][n] = __builtin_amdgcn_mfma_f32_16x16x32_bf16(Bt[n][k], At[m][k], acc[ai][bj][m][n], 0, 0, 0); __builtin_amdgcn_s_setprio(0); } while (0)
; #define PG8_WAIT_V(n) asm volatile("s_waitcnt vmcnt(" #n ")" ::: "memory")
; #define PG8_WAIT_L(n) asm volatile("s_waitcnt lgkmcnt(" #n ")" ::: "memory")
; #define PG8_BAR __builtin_amdgcn_s_barrier()
; #define PG8_SCHED __builtin_amdgcn_sched_barrier(0)
; template <class Epi>
; __device__ __forceinline__ void gemm_phase(LAS unsigned char* lds, const Gemm g, const StaticOrder& S, const Epi& E) {
;     ...
;             PG8_LDB(B0, 0, 0); PG8_SCHED; PG8_LDA(At, 0, 0); PG8_STAGE(PG8_SA(1, 1), a1 + hstep, voffA);
;             PG8_WAIT_L(8); PG8_BAR; PG8_WAIT_L(0); PG8_MMA(0, 0, At, B0); PG8_BAR; PG8_SCHED;
;             PG8_LDB(B1, 0, 1); PG8_STAGE(PG8_SB(0, 0), b2, voffB);
;             PG8_BAR; PG8_WAIT_L(0); PG8_MMA(0, 1, At, B1); PG8_BAR;
;             PG8_LDA(At, 0, 1); PG8_STAGE(PG8_SA(0, 0), a2, voffA);
;             PG8_BAR; PG8_WAIT_L(0); PG8_MMA(1, 0, At, B0); PG8_BAR; PG8_SCHED;
;             PG8_STAGE(PG8_SB(0, 1), b2 + hstep, voffB);
;             PG8_WAIT_V(6); PG8_BAR; PG8_MMA(1, 1, At, B1); PG8_BAR;
.LBB0_283:
	ds_read_b128 v[148:151], v145
	ds_read_b128 v[152:155], v145 offset:1024
	ds_read_b128 v[160:163], v145 offset:2048
	ds_read_b128 v[164:167], v145 offset:3072
	s_add_u32 s50, s48, 0x100
	s_addc_u32 s51, s49, 0
	s_cmpk_eq_i32 s65, 0x54
	s_cselect_b32 s55, s47, s51
	s_cselect_b32 s54, s46, s50
	s_cselect_b32 s53, s5, s64
	s_cselect_b32 s52, s4, s63
	s_add_i32 m0, s23, 0xc000
	ds_read_b128 v[168:171], v146
	ds_read_b128 v[172:175], v146 offset:1024
	ds_read_b128 v[176:179], v146 offset:2048
	ds_read_b128 v[180:183], v146 offset:3072
	ds_read_b128 v[184:187], v146 offset:4096
	ds_read_b128 v[188:191], v146 offset:5120
	ds_read_b128 v[192:195], v146 offset:6144
	ds_read_b128 v[196:199], v146 offset:7168
	global_load_lds_dwordx4 v136, s[48:49]
	s_add_i32 m0, s23, 0xe000
	s_nop 0
	global_load_lds_dwordx4 v138, s[48:49]
	s_waitcnt lgkmcnt(8)
	s_barrier
	s_waitcnt lgkmcnt(0)
	s_setprio 1
	s_waitcnt lgkmcnt(0)
	v_mfma_f32_16x16x32_bf16 v[124:127], v[148:151], v[168:171], v[124:127]
	v_mfma_f32_16x16x32_bf16 v[120:123], v[160:163], v[168:171], v[120:123]
	v_mfma_f32_16x16x32_bf16 v[112:115], v[148:151], v[176:179], v[112:115]
	v_mfma_f32_16x16x32_bf16 v[104:107], v[160:163], v[176:179], v[104:107]
	v_mfma_f32_16x16x32_bf16 v[96:99], v[148:151], v[184:187], v[96:99]
	v_mfma_f32_16x16x32_bf16 v[88:91], v[160:163], v[184:187], v[88:91]
	v_mfma_f32_16x16x32_bf16 v[80:83], v[148:151], v[192:195], v[80:83]
	v_mfma_f32_16x16x32_bf16 v[72:75], v[160:163], v[192:195], v[72:75]
	v_mfma_f32_16x16x32_bf16 v[124:127], v[152:155], v[172:175], v[124:127]
	v_mfma_f32_16x16x32_bf16 v[120:123], v[164:167], v[172:175], v[120:123]
	v_mfma_f32_16x16x32_bf16 v[112:115], v[152:155], v[180:183], v[112:115]
	v_mfma_f32_16x16x32_bf16 v[104:107], v[164:167], v[180:183], v[104:107]
	v_mfma_f32_16x16x32_bf16 v[96:99], v[152:155], v[188:191], v[96:99]
	v_mfma_f32_16x16x32_bf16 v[88:91], v[164:167], v[188:191], v[88:91]
	v_mfma_f32_16x16x32_bf16 v[80:83], v[152:155], v[196:199], v[80:83]
	v_mfma_f32_16x16x32_bf16 v[72:75], v[164:167], v[196:199], v[72:75]
	s_setprio 0
	s_barrier
	s_add_i32 s48, s39, s13
	v_lshl_add_u64 v[140:141], s[52:53], 0, v[132:133]
	s_mov_b32 m0, s48
	ds_read_b128 v[200:203], v147
	ds_read_b128 v[204:207], v147 offset:1024
	ds_read_b128 v[208:211], v147 offset:2048
	ds_read_b128 v[212:215], v147 offset:3072
	global_load_lds_dwordx4 v132, s[52:53]
	v_lshl_add_u64 v[156:157], s[52:53], 0, v[128:129]
	s_add_i32 m0, s48, 0x2000
	s_nop 0
	global_load_lds_dwordx4 v128, s[52:53]
	s_barrier
	s_waitcnt lgkmcnt(0)
	s_setprio 1
	s_waitcnt lgkmcnt(0)
	v_mfma_f32_16x16x32_bf16 v[116:119], v[200:203], v[168:171], v[116:119]
	v_mfma_f32_16x16x32_bf16 v[108:111], v[208:211], v[168:171], v[108:111]
	v_mfma_f32_16x16x32_bf16 v[100:103], v[200:203], v[176:179], v[100:103]
	v_mfma_f32_16x16x32_bf16 v[92:95], v[208:211], v[176:179], v[92:95]
	v_mfma_f32_16x16x32_bf16 v[84:87], v[200:203], v[184:187], v[84:87]
	v_mfma_f32_16x16x32_bf16 v[76:79], v[208:211], v[184:187], v[76:79]
	v_mfma_f32_16x16x32_bf16 v[68:71], v[200:203], v[192:195], v[68:71]
	v_mfma_f32_16x16x32_bf16 v[64:67], v[208:211], v[192:195], v[64:67]
	v_mfma_f32_16x16x32_bf16 v[116:119], v[204:207], v[172:175], v[116:119]
	v_mfma_f32_16x16x32_bf16 v[108:111], v[212:215], v[172:175], v[108:111]
	v_mfma_f32_16x16x32_bf16 v[100:103], v[204:207], v[180:183], v[100:103]
	v_mfma_f32_16x16x32_bf16 v[92:95], v[212:215], v[180:183], v[92:95]
	v_mfma_f32_16x16x32_bf16 v[84:87], v[204:207], v[188:191], v[84:87]
	v_mfma_f32_16x16x32_bf16 v[76:79], v[212:215], v[188:191], v[76:79]
	v_mfma_f32_16x16x32_bf16 v[68:71], v[204:207], v[196:199], v[68:71]
	v_mfma_f32_16x16x32_bf16 v[64:67], v[212:215], v[196:199], v[64:67]
	s_setprio 0
	s_mov_b32 m0, s23
	v_lshl_add_u64 v[216:217], s[54:55], 0, v[134:135]
	s_barrier
	ds_read_b128 v[168:171], v146 offset:16384
	ds_read_b128 v[172:175], v146 offset:17408
	ds_read_b128 v[176:179], v146 offset:18432
	ds_read_b128 v[180:183], v146 offset:19456
	ds_read_b128 v[184:187], v146 offset:20480
	ds_read_b128 v[188:191], v146 offset:21504
	ds_read_b128 v[192:195], v146 offset:22528
	ds_read_b128 v[196:199], v146 offset:23552
	global_load_lds_dwordx4 v134, s[54:55]
	v_lshl_add_u64 v[218:219], s[54:55], 0, v[130:131]
	s_mov_b32 m0, s30
	s_nop 0
	global_load_lds_dwordx4 v130, s[54:55]
	s_barrier
	s_waitcnt lgkmcnt(0)
	s_setprio 1
	s_waitcnt lgkmcnt(0)
	v_mfma_f32_16x16x32_bf16 v[60:63], v[148:151], v[168:171], v[60:63]
	v_mfma_f32_16x16x32_bf16 v[56:59], v[160:163], v[168:171], v[56:59]
	v_mfma_f32_16x16x32_bf16 v[52:55], v[148:151], v[176:179], v[52:55]
	v_mfma_f32_16x16x32_bf16 v[44:47], v[160:163], v[176:179], v[44:47]
	v_mfma_f32_16x16x32_bf16 v[36:39], v[148:151], v[184:187], v[36:39]
	v_mfma_f32_16x16x32_bf16 v[28:31], v[160:163], v[184:187], v[28:31]
	v_mfma_f32_16x16x32_bf16 v[20:23], v[148:151], v[192:195], v[20:23]
	v_mfma_f32_16x16x32_bf16 v[12:15], v[160:163], v[192:195], v[12:15]
	v_mfma_f32_16x16x32_bf16 v[60:63], v[152:155], v[172:175], v[60:63]
	v_mfma_f32_16x16x32_bf16 v[56:59], v[164:167], v[172:175], v[56:59]
	v_mfma_f32_16x16x32_bf16 v[52:55], v[152:155], v[180:183], v[52:55]
	v_mfma_f32_16x16x32_bf16 v[44:47], v[164:167], v[180:183], v[44:47]
	v_mfma_f32_16x16x32_bf16 v[36:39], v[152:155], v[188:191], v[36:39]
	v_mfma_f32_16x16x32_bf16 v[28:31], v[164:167], v[188:191], v[28:31]
	v_mfma_f32_16x16x32_bf16 v[20:23], v[152:155], v[196:199], v[20:23]
	v_mfma_f32_16x16x32_bf16 v[12:15], v[164:167], v[196:199], v[12:15]
	s_setprio 0
	s_barrier
	s_add_u32 s48, s52, 0x160000
	s_addc_u32 s49, s53, 0
	s_add_i32 s66, s40, s13
	s_mov_b32 m0, s66
	s_nop 0
	global_load_lds_dwordx4 v132, s[48:49]
	s_add_i32 m0, s66, 0x2000
	s_nop 0
	global_load_lds_dwordx4 v128, s[48:49]
	s_waitcnt vmcnt(6)
	s_barrier
; #define PG8_STAGE(bufoff, gbase, voff) do { _Pragma("unroll") for (int _i = 0; _i < 2; ++_i) \
;         __builtin_amdgcn_global_load_lds((const unsigned*)((const char*)(gbase) + (voff)[_i]), (LAS unsigned*)(lds + (bufoff) + ldsw + _i * 8192), 16, 0, 0); } while (0)
; #define PG8_LDA(dst, b, h) do { _Pragma("unroll") for (int m = 0; m < 4; ++m) _Pragma("unroll") for (int k = 0; k < 2; ++k) dst[m][k] = *(const LAS bf16x8*)(lds + PG8_SA(b, h) + aoff + m * 2048 + k * 1024); } while (0)
; #define PG8_LDB(dst, b, h) do { _Pragma("unroll") for (int n = 0; n < 2; ++n) _Pragma("unroll") for (int k = 0; k < 2; ++k) dst[n][k] = *(const LAS bf16x8*)(lds + PG8_SB(b, h) + boff + n * 2048 + k * 1024); } while (0)
; #define PG8_MMA(ai, bj, At, Bt) do { __builtin_amdgcn_s_setprio(1); _Pragma("unroll") for (int m = 0; m < 4; ++m) _Pragma("unroll") for (int n = 0; n < 2; ++n) _Pragma("unroll") for (int k = 0; k < 2; ++k) \
;         acc[ai][bj][m][n] = __builtin_amdgcn_mfma_f32_16x16x32_bf16(Bt[n][k], At[m][k], acc[ai][bj][m][n], 0, 0, 0); __builtin_amdgcn_s_setprio(0); } while (0)
; #define PG8_WAIT_L(n) asm volatile("s_waitcnt lgkmcnt(" #n ")" ::: "memory")
; #define PG8_BAR __builtin_amdgcn_s_barrier()
; #define PG8_SCHED __builtin_amdgcn_sched_barrier(0)
; template <class Epi>
; __device__ __forceinline__ void gemm_phase(LAS unsigned char* lds, const Gemm g, const StaticOrder& S, const Epi& E) {
;     ...
;             PG8_LDB(B0, 1, 0); PG8_SCHED; PG8_LDA(At, 1, 0); PG8_STAGE(PG8_SA(0, 1), a2 + hstep, voffA);
;             PG8_WAIT_L(8); PG8_BAR; PG8_WAIT_L(0); PG8_MMA(0, 0, At, B0); PG8_BAR; PG8_SCHED;
;             PG8_LDB(B1, 1, 1); PG8_STAGE(PG8_SB(1, 0), b3, voffB);
;             PG8_BAR; PG8_WAIT_L(0); PG8_MMA(0, 1, At, B1); PG8_BAR;
;             PG8_LDA(At, 1, 1); PG8_STAGE(PG8_SA(1, 0), a3, voffA);
;             PG8_BAR; PG8_WAIT_L(0); PG8_MMA(1, 0, At, B0); PG8_BAR; PG8_SCHED;
	s_setprio 1
	v_mfma_f32_16x16x32_bf16 v[48:51], v[200:203], v[168:171], v[48:51]
	v_mfma_f32_16x16x32_bf16 v[40:43], v[208:211], v[168:171], v[40:43]
	v_mfma_f32_16x16x32_bf16 v[32:35], v[200:203], v[176:179], v[32:35]
	v_mfma_f32_16x16x32_bf16 v[24:27], v[208:211], v[176:179], v[24:27]
	v_mfma_f32_16x16x32_bf16 v[16:19], v[200:203], v[184:187], v[16:19]
	v_mfma_f32_16x16x32_bf16 v[8:11], v[208:211], v[184:187], v[8:11]
	v_mfma_f32_16x16x32_bf16 v[4:7], v[200:203], v[192:195], v[4:7]
	v_mfma_f32_16x16x32_bf16 v[0:3], v[208:211], v[192:195], v[0:3]
	v_mfma_f32_16x16x32_bf16 v[48:51], v[204:207], v[172:175], v[48:51]
	v_mfma_f32_16x16x32_bf16 v[40:43], v[212:215], v[172:175], v[40:43]
	v_mfma_f32_16x16x32_bf16 v[32:35], v[204:207], v[180:183], v[32:35]
	v_mfma_f32_16x16x32_bf16 v[24:27], v[212:215], v[180:183], v[24:27]
	v_mfma_f32_16x16x32_bf16 v[16:19], v[204:207], v[188:191], v[16:19]
	v_mfma_f32_16x16x32_bf16 v[8:11], v[212:215], v[188:191], v[8:11]
	v_mfma_f32_16x16x32_bf16 v[4:7], v[204:207], v[196:199], v[4:7]
	v_mfma_f32_16x16x32_bf16 v[0:3], v[212:215], v[196:199], v[0:3]
	s_setprio 0
	s_add_i32 s66, 0, 0x18000
	v_add_u32_e32 v164, s66, v143
	s_barrier
	ds_read_b128 v[148:151], v164
	ds_read_b128 v[152:155], v164 offset:1024
	ds_read_b128 v[160:163], v164 offset:2048
	ds_read_b128 v[164:167], v164 offset:3072
	s_add_u32 s48, s54, 0x160000
	s_addc_u32 s49, s55, 0
	s_mov_b32 m0, s31
	ds_read_b128 v[168:171], v146 offset:32768
	ds_read_b128 v[172:175], v146 offset:33792
	ds_read_b128 v[176:179], v146 offset:34816
	ds_read_b128 v[180:183], v146 offset:35840
	ds_read_b128 v[184:187], v146 offset:36864
	ds_read_b128 v[188:191], v146 offset:37888
	ds_read_b128 v[192:195], v146 offset:38912
	ds_read_b128 v[196:199], v146 offset:39936
	global_load_lds_dwordx4 v134, s[48:49]
	s_mov_b32 m0, s33
	s_nop 0
	global_load_lds_dwordx4 v130, s[48:49]
	s_waitcnt lgkmcnt(8)
	s_barrier
	s_waitcnt lgkmcnt(0)
	s_setprio 1
	s_waitcnt lgkmcnt(0)
	v_mfma_f32_16x16x32_bf16 v[124:127], v[148:151], v[168:171], v[124:127]
	v_mfma_f32_16x16x32_bf16 v[120:123], v[160:163], v[168:171], v[120:123]
	v_mfma_f32_16x16x32_bf16 v[112:115], v[148:151], v[176:179], v[112:115]
	v_mfma_f32_16x16x32_bf16 v[104:107], v[160:163], v[176:179], v[104:107]
	v_mfma_f32_16x16x32_bf16 v[96:99], v[148:151], v[184:187], v[96:99]
	v_mfma_f32_16x16x32_bf16 v[88:91], v[160:163], v[184:187], v[88:91]
	v_mfma_f32_16x16x32_bf16 v[80:83], v[148:151], v[192:195], v[80:83]
	v_mfma_f32_16x16x32_bf16 v[72:75], v[160:163], v[192:195], v[72:75]
	v_mfma_f32_16x16x32_bf16 v[124:127], v[152:155], v[172:175], v[124:127]
	v_mfma_f32_16x16x32_bf16 v[120:123], v[164:167], v[172:175], v[120:123]
	v_mfma_f32_16x16x32_bf16 v[112:115], v[152:155], v[180:183], v[112:115]
	v_mfma_f32_16x16x32_bf16 v[104:107], v[164:167], v[180:183], v[104:107]
	v_mfma_f32_16x16x32_bf16 v[96:99], v[152:155], v[188:191], v[96:99]
	v_mfma_f32_16x16x32_bf16 v[88:91], v[164:167], v[188:191], v[88:91]
	v_mfma_f32_16x16x32_bf16 v[80:83], v[152:155], v[196:199], v[80:83]
	v_mfma_f32_16x16x32_bf16 v[72:75], v[164:167], v[196:199], v[72:75]
	s_setprio 0
	s_barrier
	s_add_i32 s54, 0, 0x1c000
	s_add_i32 s48, s66, s13
	v_add_u32_e32 v212, s54, v143
	v_lshl_add_u64 v[140:141], v[140:141], 0, s[6:7]
	s_mov_b32 m0, s48
	ds_read_b128 v[200:203], v212
	ds_read_b128 v[204:207], v212 offset:1024
	ds_read_b128 v[208:211], v212 offset:2048
	ds_read_b128 v[212:215], v212 offset:3072
	global_load_lds_dwordx4 v[140:141], off
	v_lshl_add_u64 v[140:141], v[156:157], 0, s[6:7]
	s_add_i32 m0, s48, 0x2000
	s_nop 0
	global_load_lds_dwordx4 v[140:141], off
	s_barrier
	s_waitcnt lgkmcnt(0)
	s_setprio 1
	s_waitcnt lgkmcnt(0)
	v_mfma_f32_16x16x32_bf16 v[116:119], v[200:203], v[168:171], v[116:119]
	v_mfma_f32_16x16x32_bf16 v[108:111], v[208:211], v[168:171], v[108:111]
	v_mfma_f32_16x16x32_bf16 v[100:103], v[200:203], v[176:179], v[100:103]
	v_mfma_f32_16x16x32_bf16 v[92:95], v[208:211], v[176:179], v[92:95]
	v_mfma_f32_16x16x32_bf16 v[84:87], v[200:203], v[184:187], v[84:87]
	v_mfma_f32_16x16x32_bf16 v[76:79], v[208:211], v[184:187], v[76:79]
	v_mfma_f32_16x16x32_bf16 v[68:71], v[200:203], v[192:195], v[68:71]
	v_mfma_f32_16x16x32_bf16 v[64:67], v[208:211], v[192:195], v[64:67]
	v_mfma_f32_16x16x32_bf16 v[116:119], v[204:207], v[172:175], v[116:119]
	v_mfma_f32_16x16x32_bf16 v[108:111], v[212:215], v[172:175], v[108:111]
	v_mfma_f32_16x16x32_bf16 v[100:103], v[204:207], v[180:183], v[100:103]
	v_mfma_f32_16x16x32_bf16 v[92:95], v[212:215], v[180:183], v[92:95]
	v_mfma_f32_16x16x32_bf16 v[84:87], v[204:207], v[188:191], v[84:87]
	v_mfma_f32_16x16x32_bf16 v[76:79], v[212:215], v[188:191], v[76:79]
	v_mfma_f32_16x16x32_bf16 v[68:71], v[204:207], v[196:199], v[68:71]
	v_mfma_f32_16x16x32_bf16 v[64:67], v[212:215], v[196:199], v[64:67]
	s_setprio 0
	s_mov_b32 m0, s34
	v_lshl_add_u64 v[140:141], v[216:217], 0, s[6:7]
	s_barrier
	ds_read_b128 v[168:171], v146 offset:49152
	ds_read_b128 v[172:175], v146 offset:50176
	ds_read_b128 v[176:179], v146 offset:51200
	ds_read_b128 v[180:183], v146 offset:52224
	ds_read_b128 v[184:187], v146 offset:53248
	ds_read_b128 v[188:191], v146 offset:54272
	ds_read_b128 v[192:195], v146 offset:55296
	ds_read_b128 v[196:199], v146 offset:56320
	global_load_lds_dwordx4 v[140:141], off
	v_lshl_add_u64 v[140:141], v[218:219], 0, s[6:7]
	s_mov_b32 m0, s36
	s_nop 0
	global_load_lds_dwordx4 v[140:141], off
	s_barrier
; #define PG8_STAGE(bufoff, gbase, voff) do { _Pragma("unroll") for (int _i = 0; _i < 2; ++_i) \
;         __builtin_amdgcn_global_load_lds((const unsigned*)((const char*)(gbase) + (voff)[_i]), (LAS unsigned*)(lds + (bufoff) + ldsw + _i * 8192), 16, 0, 0); } while (0)
; #define PG8_MMA(ai, bj, At, Bt) do { __builtin_amdgcn_s_setprio(1); _Pragma("unroll") for (int m = 0; m < 4; ++m) _Pragma("unroll") for (int n = 0; n < 2; ++n) _Pragma("unroll") for (int k = 0; k < 2; ++k) \
;         acc[ai][bj][m][n] = __builtin_amdgcn_mfma_f32_16x16x32_bf16(Bt[n][k], At[m][k], acc[ai][bj][m][n], 0, 0, 0); __builtin_amdgcn_s_setprio(0); } while (0)
; #define PG8_WAIT_V(n) asm volatile("s_waitcnt vmcnt(" #n ")" ::: "memory")
; #define PG8_BAR __builtin_amdgcn_s_barrier()
; template <class Epi>
; __device__ __forceinline__ void gemm_phase(LAS unsigned char* lds, const Gemm g, const StaticOrder& S, const Epi& E) {
;     ...
;             PG8_STAGE(PG8_SB(1, 1), b3 + hstep, voffB);
;             PG8_WAIT_V(6); PG8_BAR; PG8_MMA(1, 1, At, B1); PG8_BAR;
	s_waitcnt lgkmcnt(0)
	s_setprio 1
	s_waitcnt lgkmcnt(0)
	v_mfma_f32_16x16x32_bf16 v[60:63], v[148:151], v[168:171], v[60:63]
	v_mfma_f32_16x16x32_bf16 v[56:59], v[160:163], v[168:171], v[56:59]
	v_mfma_f32_16x16x32_bf16 v[52:55], v[148:151], v[176:179], v[52:55]
	v_mfma_f32_16x16x32_bf16 v[44:47], v[160:163], v[176:179], v[44:47]
	v_mfma_f32_16x16x32_bf16 v[36:39], v[148:151], v[184:187], v[36:39]
	v_mfma_f32_16x16x32_bf16 v[28:31], v[160:163], v[184:187], v[28:31]
	v_mfma_f32_16x16x32_bf16 v[20:23], v[148:151], v[192:195], v[20:23]
	v_mfma_f32_16x16x32_bf16 v[12:15], v[160:163], v[192:195], v[12:15]
	v_mfma_f32_16x16x32_bf16 v[60:63], v[152:155], v[172:175], v[60:63]
	v_mfma_f32_16x16x32_bf16 v[56:59], v[164:167], v[172:175], v[56:59]
	v_mfma_f32_16x16x32_bf16 v[52:55], v[152:155], v[180:183], v[52:55]
	v_mfma_f32_16x16x32_bf16 v[44:47], v[164:167], v[180:183], v[44:47]
	v_mfma_f32_16x16x32_bf16 v[36:39], v[152:155], v[188:191], v[36:39]
	v_mfma_f32_16x16x32_bf16 v[28:31], v[164:167], v[188:191], v[28:31]
	v_mfma_f32_16x16x32_bf16 v[20:23], v[152:155], v[196:199], v[20:23]
	v_mfma_f32_16x16x32_bf16 v[12:15], v[164:167], v[196:199], v[12:15]
	s_setprio 0
	s_barrier
	s_add_u32 s48, s52, 0x160080
	s_addc_u32 s49, s53, 0
	s_add_i32 s52, s54, s13
	s_mov_b32 m0, s52
	s_nop 0
	global_load_lds_dwordx4 v132, s[48:49]
	s_add_i32 m0, s52, 0x2000
	s_nop 0
	global_load_lds_dwordx4 v128, s[48:49]
	s_waitcnt vmcnt(6)
	s_barrier
	s_setprio 1
	v_mfma_f32_16x16x32_bf16 v[48:51], v[200:203], v[168:171], v[48:51]
	v_mfma_f32_16x16x32_bf16 v[40:43], v[208:211], v[168:171], v[40:43]
	v_mfma_f32_16x16x32_bf16 v[32:35], v[200:203], v[176:179], v[32:35]
	v_mfma_f32_16x16x32_bf16 v[24:27], v[208:211], v[176:179], v[24:27]
	v_mfma_f32_16x16x32_bf16 v[16:19], v[200:203], v[184:187], v[16:19]
	v_mfma_f32_16x16x32_bf16 v[8:11], v[208:211], v[184:187], v[8:11]
	v_mfma_f32_16x16x32_bf16 v[4:7], v[200:203], v[192:195], v[4:7]
	v_mfma_f32_16x16x32_bf16 v[0:3], v[208:211], v[192:195], v[0:3]
	v_mfma_f32_16x16x32_bf16 v[48:51], v[204:207], v[172:175], v[48:51]
	v_mfma_f32_16x16x32_bf16 v[40:43], v[212:215], v[172:175], v[40:43]
	v_mfma_f32_16x16x32_bf16 v[32:35], v[204:207], v[180:183], v[32:35]
	v_mfma_f32_16x16x32_bf16 v[24:27], v[212:215], v[180:183], v[24:27]
	v_mfma_f32_16x16x32_bf16 v[16:19], v[204:207], v[188:191], v[16:19]
	v_mfma_f32_16x16x32_bf16 v[8:11], v[212:215], v[188:191], v[8:11]
	v_mfma_f32_16x16x32_bf16 v[4:7], v[204:207], v[196:199], v[4:7]
	v_mfma_f32_16x16x32_bf16 v[0:3], v[212:215], v[196:199], v[0:3]
	s_setprio 0
	s_add_i32 s65, s65, 2
	s_add_u32 s63, s63, 0x100
	s_addc_u32 s64, s64, 0
	s_cmpk_gt_u32 s65, 0x55
	s_mov_b64 s[48:49], s[50:51]
	s_barrier
	s_cbranch_scc0 .LBB0_283
; #define PG8_WAIT_V(n) asm volatile("s_waitcnt vmcnt(" #n ")" ::: "memory")
; #define PG8_BAR __builtin_amdgcn_s_barrier()
; __device__ __forceinline__ u32x4 pack8(f32x4 v0, f32x4 v1) { u32x4 w; w.x = cvt_pk_bf16(v0[0], v0[1]); w.y = cvt_pk_bf16(v0[2], v0[3]); w.z = cvt_pk_bf16(v1[0], v1[1]); w.w = cvt_pk_bf16(v1[2], v1[3]); return w; }
; template <class Epi>
; __device__ __forceinline__ void gemm_phase(LAS unsigned char* lds, const Gemm g, const StaticOrder& S, const Epi& E) {
;     ...
;     PG8_WAIT_V(0);
;     if (wr == 0) PG8_BAR;
;     PG8_BAR;
;     __device__ __forceinline__ void operator()(const f32x4 (&acc)[2][2][4][2], const Unit& u, int wr, int wc, int fr, int fq) const {
;         const int row0 = u.pm * BM + wr * 64 + fr, col0 = u.pn * BM + wc * 32 + 8 * fq;
; #pragma unroll
;         for (int ai = 0; ai < 2; ++ai)
; #pragma unroll
;             for (int m = 0; m < 4; ++m) { bf16_t* rowp = O + (size_t)(row0 + ai * HALF + m * 16) * ldc + col0;
; #pragma unroll
;                 for (int bj = 0; bj < 2; ++bj) *(u32x4*)(rowp + bj * HALF) = pack8(acc[ai][bj][m][0], acc[ai][bj][m][1]); }
;     }
	v_lshl_add_u32 v148, s61, 8, v142
	v_lshl_or_b32 v140, s62, 8, v144
	v_ashrrev_i32_e32 v149, 31, v148
	v_ashrrev_i32_e32 v141, 31, v140
	v_lshlrev_b64 v[150:151], 12, v[148:149]
	v_lshl_add_u64 v[150:151], s[24:25], 0, v[150:151]
	v_lshlrev_b64 v[152:153], 1, v[140:141]
	v_lshl_add_u64 v[140:141], v[150:151], 0, v[152:153]
	v_cvt_pk_bf16_f32 v124, v124, v125
	v_cvt_pk_bf16_f32 v125, v126, v127
	v_cvt_pk_bf16_f32 v126, v120, v121
	v_cvt_pk_bf16_f32 v127, v122, v123
	global_store_dwordx4 v[140:141], v[124:127], off
	v_cvt_pk_bf16_f32 v116, v116, v117
	v_cvt_pk_bf16_f32 v117, v118, v119
	v_cvt_pk_bf16_f32 v118, v108, v109
	v_or_b32_e32 v108, 16, v148
	v_ashrrev_i32_e32 v109, 31, v108
	v_lshlrev_b64 v[108:109], 12, v[108:109]
	v_lshl_add_u64 v[108:109], s[24:25], 0, v[108:109]
	v_cvt_pk_bf16_f32 v119, v110, v111
	global_store_dwordx4 v[140:141], v[116:119], off offset:256
	s_mov_b32 s62, s59
	s_mov_b32 s61, s60
	v_lshl_add_u64 v[116:117], v[108:109], 0, v[152:153]
	v_cvt_pk_bf16_f32 v108, v112, v113
	v_cvt_pk_bf16_f32 v109, v114, v115
	v_cvt_pk_bf16_f32 v110, v104, v105
	v_cvt_pk_bf16_f32 v111, v106, v107
	global_store_dwordx4 v[116:117], v[108:111], off
	v_cvt_pk_bf16_f32 v100, v100, v101
	v_cvt_pk_bf16_f32 v101, v102, v103
	v_cvt_pk_bf16_f32 v102, v92, v93
	v_or_b32_e32 v92, 32, v148
	v_ashrrev_i32_e32 v93, 31, v92
	v_lshlrev_b64 v[92:93], 12, v[92:93]
	v_lshl_add_u64 v[92:93], s[24:25], 0, v[92:93]
	v_cvt_pk_bf16_f32 v103, v94, v95
	global_store_dwordx4 v[116:117], v[100:103], off offset:256
	s_mov_b64 s[50:51], s[4:5]
	s_mov_b64 s[48:49], s[46:47]
	v_lshl_add_u64 v[100:101], v[92:93], 0, v[152:153]
	v_cvt_pk_bf16_f32 v92, v96, v97
	v_cvt_pk_bf16_f32 v93, v98, v99
	v_cvt_pk_bf16_f32 v94, v88, v89
	v_cvt_pk_bf16_f32 v95, v90, v91
	global_store_dwordx4 v[100:101], v[92:95], off
	v_cvt_pk_bf16_f32 v84, v84, v85
	v_cvt_pk_bf16_f32 v85, v86, v87
	v_cvt_pk_bf16_f32 v86, v76, v77
	v_or_b32_e32 v76, 48, v148
	v_ashrrev_i32_e32 v77, 31, v76
	v_lshlrev_b64 v[76:77], 12, v[76:77]
	v_lshl_add_u64 v[76:77], s[24:25], 0, v[76:77]
	v_cvt_pk_bf16_f32 v87, v78, v79
	global_store_dwordx4 v[100:101], v[84:87], off offset:256
	s_nop 1
	v_lshl_add_u64 v[84:85], v[76:77], 0, v[152:153]
	v_cvt_pk_bf16_f32 v76, v80, v81
	v_cvt_pk_bf16_f32 v77, v82, v83
	v_cvt_pk_bf16_f32 v78, v72, v73
	v_cvt_pk_bf16_f32 v79, v74, v75
	global_store_dwordx4 v[84:85], v[76:79], off
	v_cvt_pk_bf16_f32 v68, v68, v69
	v_cvt_pk_bf16_f32 v69, v70, v71
	v_cvt_pk_bf16_f32 v70, v64, v65
	v_cvt_pk_bf16_f32 v71, v66, v67
	global_store_dwordx4 v[84:85], v[68:71], off offset:256
	v_cvt_pk_bf16_f32 v60, v60, v61
	v_cvt_pk_bf16_f32 v61, v62, v63
	v_cvt_pk_bf16_f32 v62, v56, v57
	v_add_co_u32_e32 v56, vcc, s41, v140
	v_lshl_add_u64 v[64:65], v[140:141], 0, s[8:9]
	s_nop 0
	v_addc_co_u32_e32 v57, vcc, 0, v141, vcc
	v_cvt_pk_bf16_f32 v63, v58, v59
	global_store_dwordx4 v[56:57], v[60:63], off
	v_cvt_pk_bf16_f32 v48, v48, v49
	v_cvt_pk_bf16_f32 v49, v50, v51
	v_cvt_pk_bf16_f32 v50, v40, v41
	v_cvt_pk_bf16_f32 v51, v42, v43
	global_store_dwordx4 v[64:65], v[48:51], off offset:256
	v_cvt_pk_bf16_f32 v40, v52, v53
	v_cvt_pk_bf16_f32 v41, v54, v55
	v_cvt_pk_bf16_f32 v42, v44, v45
	v_add_co_u32_e32 v44, vcc, s56, v140
	s_nop 0
	v_lshl_add_u64 v[48:49], v[140:141], 0, s[26:27]
	v_addc_co_u32_e32 v45, vcc, 0, v141, vcc
	v_cvt_pk_bf16_f32 v43, v46, v47
	global_store_dwordx4 v[44:45], v[40:43], off
	v_cvt_pk_bf16_f32 v32, v32, v33
	v_cvt_pk_bf16_f32 v33, v34, v35
	v_cvt_pk_bf16_f32 v34, v24, v25
	v_cvt_pk_bf16_f32 v35, v26, v27
	global_store_dwordx4 v[48:49], v[32:35], off offset:256
	v_cvt_pk_bf16_f32 v24, v36, v37
	v_cvt_pk_bf16_f32 v25, v38, v39
	v_cvt_pk_bf16_f32 v26, v28, v29
	v_add_co_u32_e32 v28, vcc, s57, v140
	s_nop 0
	v_lshl_add_u64 v[32:33], v[140:141], 0, s[28:29]
	v_addc_co_u32_e32 v29, vcc, 0, v141, vcc
	v_cvt_pk_bf16_f32 v27, v30, v31
	global_store_dwordx4 v[28:29], v[24:27], off
	v_cvt_pk_bf16_f32 v16, v16, v17
	v_cvt_pk_bf16_f32 v17, v18, v19
	v_cvt_pk_bf16_f32 v18, v8, v9
	v_cvt_pk_bf16_f32 v19, v10, v11
	global_store_dwordx4 v[32:33], v[16:19], off offset:256
	v_cvt_pk_bf16_f32 v8, v20, v21
	v_cvt_pk_bf16_f32 v9, v22, v23
	v_cvt_pk_bf16_f32 v10, v12, v13
	v_add_co_u32_e32 v12, vcc, s58, v140
	s_nop 0
	v_lshl_add_u64 v[16:17], v[140:141], 0, s[42:43]
	v_addc_co_u32_e32 v13, vcc, 0, v141, vcc
	s_and_b64 vcc, exec, s[44:45]
	v_cvt_pk_bf16_f32 v11, v14, v15
	global_store_dwordx4 v[12:13], v[8:11], off
	v_cvt_pk_bf16_f32 v4, v4, v5
	v_cvt_pk_bf16_f32 v5, v6, v7
	v_cvt_pk_bf16_f32 v6, v0, v1
	v_cvt_pk_bf16_f32 v7, v2, v3
	global_store_dwordx4 v[16:17], v[4:7], off offset:256
	s_cbranch_vccz .LBB0_276
	s_waitcnt vmcnt(0)
	s_cmpk_gt_u32 s3, 0xff
	v_readlane_b32 s62, v232, 20
	s_cbranch_scc1 .LBB0_287
	s_barrier

; #define PG8_STAGE(bufoff, gbase, voff) do { _Pragma("unroll") for (int _i = 0; _i < 2; ++_i) \
;         __builtin_amdgcn_global_load_lds((const unsigned*)((const char*)(gbase) + (voff)[_i]), (LAS unsigned*)(lds + (bufoff) + ldsw + _i * 8192), 16, 0, 0); } while (0)
; #define PG8_LDA(dst, b, h) do { _Pragma("unroll") for (int m = 0; m < 4; ++m) _Pragma("unroll") for (int k = 0; k < 2; ++k) dst[m][k] = *(const LAS bf16x8*)(lds + PG8_SA(b, h) + aoff + m * 2048 + k * 1024); } while (0)
; #define PG8_LDB(dst, b, h) do { _Pragma("unroll") for (int n = 0; n < 2; ++n) _Pragma("unroll") for (int k = 0; k < 2; ++k) dst[n][k] = *(const LAS bf16x8*)(lds + PG8_SB(b, h) + boff + n * 2048 + k * 1024); } while (0)
; #define PG8_MMA(ai, bj, At, Bt) do { __builtin_amdgcn_s_setprio(1); _Pragma("unroll") for (int m = 0; m < 4; ++m) _Pragma("unroll") for (int n = 0; n < 2; ++n) _Pragma("unroll") for (int k = 0; k < 2; ++k) \
;         acc[ai][bj][m][n] = __builtin_amdgcn_mfma_f32_16x16x32_bf16(Bt[n][k], At[m][k], acc[ai][bj][m][n], 0, 0, 0); __builtin_amdgcn_s_setprio(0); } while (0)
; #define PG8_WAIT_V(n) asm volatile("s_waitcnt vmcnt(" #n ")" ::: "memory")
; #define PG8_WAIT_L(n) asm volatile("s_waitcnt lgkmcnt(" #n ")" ::: "memory")
; #define PG8_BAR __builtin_amdgcn_s_barrier()
; #define PG8_SCHED __builtin_amdgcn_sched_barrier(0)
; template <class Epi>
; __device__ __forceinline__ void gemm_phase(LAS unsigned char* lds, const Gemm g, const StaticOrder& S, const Epi& E) {
;     ...
;             PG8_LDB(B0, 0, 0); PG8_SCHED; PG8_LDA(At, 0, 0); PG8_STAGE(PG8_SA(1, 1), a1 + hstep, voffA);
;             PG8_WAIT_L(8); PG8_BAR; PG8_WAIT_L(0); PG8_MMA(0, 0, At, B0); PG8_BAR; PG8_SCHED;
;             PG8_LDB(B1, 0, 1); PG8_STAGE(PG8_SB(0, 0), b2, voffB);
;             PG8_BAR; PG8_WAIT_L(0); PG8_MMA(0, 1, At, B1); PG8_BAR;
;             PG8_LDA(At, 0, 1); PG8_STAGE(PG8_SA(0, 0), a2, voffA);
;             PG8_BAR; PG8_WAIT_L(0); PG8_MMA(1, 0, At, B0); PG8_BAR; PG8_SCHED;
;             PG8_STAGE(PG8_SB(0, 1), b2 + hstep, voffB);
;             PG8_WAIT_V(6); PG8_BAR; PG8_MMA(1, 1, At, B1); PG8_BAR;
.LBB0_407:
	ds_read_b128 v[150:153], v164
	ds_read_b128 v[154:157], v164 offset:1024
	ds_read_b128 v[168:171], v164 offset:2048
	ds_read_b128 v[172:175], v164 offset:3072
	s_add_u32 s48, s46, 0xfff80080
	s_addc_u32 s49, s47, -1
	s_cmp_eq_u32 s57, 28
	s_cselect_b32 s51, s9, s49
	s_cselect_b32 s50, s45, s48
	s_cselect_b32 s49, s7, s56
	s_cselect_b32 s48, s54, s55
	s_add_i32 m0, s27, 0xc000
	ds_read_b128 v[176:179], v165
	ds_read_b128 v[180:183], v165 offset:1024
	ds_read_b128 v[184:187], v165 offset:2048
	ds_read_b128 v[188:191], v165 offset:3072
	ds_read_b128 v[192:195], v165 offset:4096
	ds_read_b128 v[196:199], v165 offset:5120
	ds_read_b128 v[200:203], v165 offset:6144
	ds_read_b128 v[204:207], v165 offset:7168
	global_load_lds_dwordx4 v142, s[46:47]
	s_add_i32 m0, s27, 0xe000
	s_nop 0
	global_load_lds_dwordx4 v144, s[46:47]
	s_waitcnt lgkmcnt(8)
	s_barrier
	s_waitcnt lgkmcnt(0)
	s_setprio 1
	s_waitcnt lgkmcnt(0)
	v_mfma_f32_16x16x32_bf16 v[124:127], v[150:153], v[176:179], v[124:127]
	v_mfma_f32_16x16x32_bf16 v[120:123], v[168:171], v[176:179], v[120:123]
	v_mfma_f32_16x16x32_bf16 v[108:111], v[150:153], v[184:187], v[108:111]
	v_mfma_f32_16x16x32_bf16 v[104:107], v[168:171], v[184:187], v[104:107]
	v_mfma_f32_16x16x32_bf16 v[92:95], v[150:153], v[192:195], v[92:95]
	v_mfma_f32_16x16x32_bf16 v[88:91], v[168:171], v[192:195], v[88:91]
	v_mfma_f32_16x16x32_bf16 v[76:79], v[150:153], v[200:203], v[76:79]
	v_mfma_f32_16x16x32_bf16 v[72:75], v[168:171], v[200:203], v[72:75]
	v_mfma_f32_16x16x32_bf16 v[124:127], v[154:157], v[180:183], v[124:127]
	v_mfma_f32_16x16x32_bf16 v[120:123], v[172:175], v[180:183], v[120:123]
	v_mfma_f32_16x16x32_bf16 v[108:111], v[154:157], v[188:191], v[108:111]
	v_mfma_f32_16x16x32_bf16 v[104:107], v[172:175], v[188:191], v[104:107]
	v_mfma_f32_16x16x32_bf16 v[92:95], v[154:157], v[196:199], v[92:95]
	v_mfma_f32_16x16x32_bf16 v[88:91], v[172:175], v[196:199], v[88:91]
	v_mfma_f32_16x16x32_bf16 v[76:79], v[154:157], v[204:207], v[76:79]
	v_mfma_f32_16x16x32_bf16 v[72:75], v[172:175], v[204:207], v[72:75]
	s_setprio 0
	s_barrier
	s_add_i32 s58, s41, s23
	v_lshl_add_u64 v[224:225], s[48:49], 0, v[132:133]
	s_mov_b32 m0, s58
	ds_read_b128 v[208:211], v166
	ds_read_b128 v[212:215], v166 offset:1024
	ds_read_b128 v[216:219], v166 offset:2048
	ds_read_b128 v[220:223], v166 offset:3072
	global_load_lds_dwordx4 v132, s[48:49]
	v_lshl_add_u64 v[226:227], s[48:49], 0, v[128:129]
	s_add_i32 m0, s58, 0x2000
	s_nop 0
	global_load_lds_dwordx4 v128, s[48:49]
	s_barrier
	s_waitcnt lgkmcnt(0)
	s_setprio 1
	s_waitcnt lgkmcnt(0)
	v_mfma_f32_16x16x32_bf16 v[116:119], v[208:211], v[176:179], v[116:119]
	v_mfma_f32_16x16x32_bf16 v[112:115], v[216:219], v[176:179], v[112:115]
	v_mfma_f32_16x16x32_bf16 v[100:103], v[208:211], v[184:187], v[100:103]
	v_mfma_f32_16x16x32_bf16 v[96:99], v[216:219], v[184:187], v[96:99]
	v_mfma_f32_16x16x32_bf16 v[84:87], v[208:211], v[192:195], v[84:87]
	v_mfma_f32_16x16x32_bf16 v[80:83], v[216:219], v[192:195], v[80:83]
	v_mfma_f32_16x16x32_bf16 v[68:71], v[208:211], v[200:203], v[68:71]
	v_mfma_f32_16x16x32_bf16 v[64:67], v[216:219], v[200:203], v[64:67]
	v_mfma_f32_16x16x32_bf16 v[116:119], v[212:215], v[180:183], v[116:119]
	v_mfma_f32_16x16x32_bf16 v[112:115], v[220:223], v[180:183], v[112:115]
	v_mfma_f32_16x16x32_bf16 v[100:103], v[212:215], v[188:191], v[100:103]
	v_mfma_f32_16x16x32_bf16 v[96:99], v[220:223], v[188:191], v[96:99]
	v_mfma_f32_16x16x32_bf16 v[84:87], v[212:215], v[196:199], v[84:87]
	v_mfma_f32_16x16x32_bf16 v[80:83], v[220:223], v[196:199], v[80:83]
	v_mfma_f32_16x16x32_bf16 v[68:71], v[212:215], v[204:207], v[68:71]
	v_mfma_f32_16x16x32_bf16 v[64:67], v[220:223], v[204:207], v[64:67]
	s_setprio 0
	s_mov_b32 m0, s27
	v_lshl_add_u64 v[228:229], s[50:51], 0, v[134:135]
	s_barrier
	ds_read_b128 v[176:179], v165 offset:16384
	ds_read_b128 v[180:183], v165 offset:17408
	ds_read_b128 v[184:187], v165 offset:18432
	ds_read_b128 v[188:191], v165 offset:19456
	ds_read_b128 v[192:195], v165 offset:20480
	ds_read_b128 v[196:199], v165 offset:21504
	ds_read_b128 v[200:203], v165 offset:22528
	ds_read_b128 v[204:207], v165 offset:23552
	global_load_lds_dwordx4 v134, s[50:51]
	v_lshl_add_u64 v[230:231], s[50:51], 0, v[130:131]
	s_mov_b32 m0, s30
	s_nop 0
	global_load_lds_dwordx4 v130, s[50:51]
	s_barrier
	s_waitcnt lgkmcnt(0)
	s_setprio 1
	s_waitcnt lgkmcnt(0)
	v_mfma_f32_16x16x32_bf16 v[60:63], v[150:153], v[176:179], v[60:63]
	v_mfma_f32_16x16x32_bf16 v[56:59], v[168:171], v[176:179], v[56:59]
	v_mfma_f32_16x16x32_bf16 v[44:47], v[150:153], v[184:187], v[44:47]
	v_mfma_f32_16x16x32_bf16 v[40:43], v[168:171], v[184:187], v[40:43]
	v_mfma_f32_16x16x32_bf16 v[28:31], v[150:153], v[192:195], v[28:31]
	v_mfma_f32_16x16x32_bf16 v[24:27], v[168:171], v[192:195], v[24:27]
	v_mfma_f32_16x16x32_bf16 v[12:15], v[150:153], v[200:203], v[12:15]
	v_mfma_f32_16x16x32_bf16 v[8:11], v[168:171], v[200:203], v[8:11]
	v_mfma_f32_16x16x32_bf16 v[60:63], v[154:157], v[180:183], v[60:63]
	v_mfma_f32_16x16x32_bf16 v[56:59], v[172:175], v[180:183], v[56:59]
	v_mfma_f32_16x16x32_bf16 v[44:47], v[154:157], v[188:191], v[44:47]
	v_mfma_f32_16x16x32_bf16 v[40:43], v[172:175], v[188:191], v[40:43]
	v_mfma_f32_16x16x32_bf16 v[28:31], v[154:157], v[196:199], v[28:31]
	v_mfma_f32_16x16x32_bf16 v[24:27], v[172:175], v[196:199], v[24:27]
	v_mfma_f32_16x16x32_bf16 v[12:15], v[154:157], v[204:207], v[12:15]
	v_mfma_f32_16x16x32_bf16 v[8:11], v[172:175], v[204:207], v[8:11]
	s_setprio 0
	s_barrier
	s_add_u32 s58, s48, 0x80000
	s_addc_u32 s59, s49, 0
	s_add_i32 s60, s52, s23
	s_mov_b32 m0, s60
	s_nop 0
	global_load_lds_dwordx4 v132, s[58:59]
	s_add_i32 m0, s60, 0x2000
	s_nop 0
	global_load_lds_dwordx4 v128, s[58:59]
	s_waitcnt vmcnt(6)
	s_barrier
; #define PG8_STAGE(bufoff, gbase, voff) do { _Pragma("unroll") for (int _i = 0; _i < 2; ++_i) \
;         __builtin_amdgcn_global_load_lds((const unsigned*)((const char*)(gbase) + (voff)[_i]), (LAS unsigned*)(lds + (bufoff) + ldsw + _i * 8192), 16, 0, 0); } while (0)
; #define PG8_LDA(dst, b, h) do { _Pragma("unroll") for (int m = 0; m < 4; ++m) _Pragma("unroll") for (int k = 0; k < 2; ++k) dst[m][k] = *(const LAS bf16x8*)(lds + PG8_SA(b, h) + aoff + m * 2048 + k * 1024); } while (0)
; #define PG8_LDB(dst, b, h) do { _Pragma("unroll") for (int n = 0; n < 2; ++n) _Pragma("unroll") for (int k = 0; k < 2; ++k) dst[n][k] = *(const LAS bf16x8*)(lds + PG8_SB(b, h) + boff + n * 2048 + k * 1024); } while (0)
; #define PG8_MMA(ai, bj, At, Bt) do { __builtin_amdgcn_s_setprio(1); _Pragma("unroll") for (int m = 0; m < 4; ++m) _Pragma("unroll") for (int n = 0; n < 2; ++n) _Pragma("unroll") for (int k = 0; k < 2; ++k) \
;         acc[ai][bj][m][n] = __builtin_amdgcn_mfma_f32_16x16x32_bf16(Bt[n][k], At[m][k], acc[ai][bj][m][n], 0, 0, 0); __builtin_amdgcn_s_setprio(0); } while (0)
; #define PG8_WAIT_L(n) asm volatile("s_waitcnt lgkmcnt(" #n ")" ::: "memory")
; #define PG8_BAR __builtin_amdgcn_s_barrier()
; #define PG8_SCHED __builtin_amdgcn_sched_barrier(0)
; template <class Epi>
; __device__ __forceinline__ void gemm_phase(LAS unsigned char* lds, const Gemm g, const StaticOrder& S, const Epi& E) {
;     ...
;             PG8_LDB(B0, 1, 0); PG8_SCHED; PG8_LDA(At, 1, 0); PG8_STAGE(PG8_SA(0, 1), a2 + hstep, voffA);
;             PG8_WAIT_L(8); PG8_BAR; PG8_WAIT_L(0); PG8_MMA(0, 0, At, B0); PG8_BAR; PG8_SCHED;
;             PG8_LDB(B1, 1, 1); PG8_STAGE(PG8_SB(1, 0), b3, voffB);
;             PG8_BAR; PG8_WAIT_L(0); PG8_MMA(0, 1, At, B1); PG8_BAR;
;             PG8_LDA(At, 1, 1); PG8_STAGE(PG8_SA(1, 0), a3, voffA);
;             PG8_BAR; PG8_WAIT_L(0); PG8_MMA(1, 0, At, B0); PG8_BAR; PG8_SCHED;
	s_setprio 1
	v_mfma_f32_16x16x32_bf16 v[52:55], v[208:211], v[176:179], v[52:55]
	v_mfma_f32_16x16x32_bf16 v[48:51], v[216:219], v[176:179], v[48:51]
	v_mfma_f32_16x16x32_bf16 v[36:39], v[208:211], v[184:187], v[36:39]
	v_mfma_f32_16x16x32_bf16 v[32:35], v[216:219], v[184:187], v[32:35]
	v_mfma_f32_16x16x32_bf16 v[20:23], v[208:211], v[192:195], v[20:23]
	v_mfma_f32_16x16x32_bf16 v[16:19], v[216:219], v[192:195], v[16:19]
	v_mfma_f32_16x16x32_bf16 v[4:7], v[208:211], v[200:203], v[4:7]
	v_mfma_f32_16x16x32_bf16 v[0:3], v[216:219], v[200:203], v[0:3]
	v_mfma_f32_16x16x32_bf16 v[52:55], v[212:215], v[180:183], v[52:55]
	v_mfma_f32_16x16x32_bf16 v[48:51], v[220:223], v[180:183], v[48:51]
	v_mfma_f32_16x16x32_bf16 v[36:39], v[212:215], v[188:191], v[36:39]
	v_mfma_f32_16x16x32_bf16 v[32:35], v[220:223], v[188:191], v[32:35]
	v_mfma_f32_16x16x32_bf16 v[20:23], v[212:215], v[196:199], v[20:23]
	v_mfma_f32_16x16x32_bf16 v[16:19], v[220:223], v[196:199], v[16:19]
	v_mfma_f32_16x16x32_bf16 v[4:7], v[212:215], v[204:207], v[4:7]
	v_mfma_f32_16x16x32_bf16 v[0:3], v[220:223], v[204:207], v[0:3]
	s_setprio 0
	s_add_i32 s58, 0, 0x18000
	v_add_u32_e32 v136, s58, v161
	s_barrier
	ds_read_b128 v[150:153], v136
	ds_read_b128 v[154:157], v136 offset:1024
	ds_read_b128 v[168:171], v136 offset:2048
	ds_read_b128 v[172:175], v136 offset:3072
	s_add_u32 s50, s50, 0x80000
	s_addc_u32 s51, s51, 0
	s_mov_b32 m0, s31
	ds_read_b128 v[176:179], v165 offset:32768
	ds_read_b128 v[180:183], v165 offset:33792
	ds_read_b128 v[184:187], v165 offset:34816
	ds_read_b128 v[188:191], v165 offset:35840
	ds_read_b128 v[192:195], v165 offset:36864
	ds_read_b128 v[196:199], v165 offset:37888
	ds_read_b128 v[200:203], v165 offset:38912
	ds_read_b128 v[204:207], v165 offset:39936
	global_load_lds_dwordx4 v134, s[50:51]
	s_mov_b32 m0, s33
	s_nop 0
	global_load_lds_dwordx4 v130, s[50:51]
	s_waitcnt lgkmcnt(8)
	s_barrier
	s_waitcnt lgkmcnt(0)
	s_setprio 1
	s_waitcnt lgkmcnt(0)
	v_mfma_f32_16x16x32_bf16 v[124:127], v[150:153], v[176:179], v[124:127]
	v_mfma_f32_16x16x32_bf16 v[120:123], v[168:171], v[176:179], v[120:123]
	v_mfma_f32_16x16x32_bf16 v[108:111], v[150:153], v[184:187], v[108:111]
	v_mfma_f32_16x16x32_bf16 v[104:107], v[168:171], v[184:187], v[104:107]
	v_mfma_f32_16x16x32_bf16 v[92:95], v[150:153], v[192:195], v[92:95]
	v_mfma_f32_16x16x32_bf16 v[88:91], v[168:171], v[192:195], v[88:91]
	v_mfma_f32_16x16x32_bf16 v[76:79], v[150:153], v[200:203], v[76:79]
	v_mfma_f32_16x16x32_bf16 v[72:75], v[168:171], v[200:203], v[72:75]
	v_mfma_f32_16x16x32_bf16 v[124:127], v[154:157], v[180:183], v[124:127]
	v_mfma_f32_16x16x32_bf16 v[120:123], v[172:175], v[180:183], v[120:123]
	v_mfma_f32_16x16x32_bf16 v[108:111], v[154:157], v[188:191], v[108:111]
	v_mfma_f32_16x16x32_bf16 v[104:107], v[172:175], v[188:191], v[104:107]
	v_mfma_f32_16x16x32_bf16 v[92:95], v[154:157], v[196:199], v[92:95]
	v_mfma_f32_16x16x32_bf16 v[88:91], v[172:175], v[196:199], v[88:91]
	v_mfma_f32_16x16x32_bf16 v[76:79], v[154:157], v[204:207], v[76:79]
	v_mfma_f32_16x16x32_bf16 v[72:75], v[172:175], v[204:207], v[72:75]
	s_setprio 0
	s_barrier
	s_add_i32 s50, 0, 0x1c000
	s_add_i32 s51, s58, s23
	v_add_u32_e32 v136, s50, v161
	v_lshl_add_u64 v[224:225], v[224:225], 0, s[2:3]
	s_mov_b32 m0, s51
	ds_read_b128 v[208:211], v136
	ds_read_b128 v[212:215], v136 offset:1024
	ds_read_b128 v[216:219], v136 offset:2048
	ds_read_b128 v[220:223], v136 offset:3072
	global_load_lds_dwordx4 v[224:225], off
	v_lshl_add_u64 v[224:225], v[226:227], 0, s[2:3]
	s_add_i32 m0, s51, 0x2000
	s_nop 0
	global_load_lds_dwordx4 v[224:225], off
	s_barrier
	s_waitcnt lgkmcnt(0)
	s_setprio 1
	s_waitcnt lgkmcnt(0)
	v_mfma_f32_16x16x32_bf16 v[116:119], v[208:211], v[176:179], v[116:119]
	v_mfma_f32_16x16x32_bf16 v[112:115], v[216:219], v[176:179], v[112:115]
	v_mfma_f32_16x16x32_bf16 v[100:103], v[208:211], v[184:187], v[100:103]
	v_mfma_f32_16x16x32_bf16 v[96:99], v[216:219], v[184:187], v[96:99]
	v_mfma_f32_16x16x32_bf16 v[84:87], v[208:211], v[192:195], v[84:87]
	v_mfma_f32_16x16x32_bf16 v[80:83], v[216:219], v[192:195], v[80:83]
	v_mfma_f32_16x16x32_bf16 v[68:71], v[208:211], v[200:203], v[68:71]
	v_mfma_f32_16x16x32_bf16 v[64:67], v[216:219], v[200:203], v[64:67]
	v_mfma_f32_16x16x32_bf16 v[116:119], v[212:215], v[180:183], v[116:119]
	v_mfma_f32_16x16x32_bf16 v[112:115], v[220:223], v[180:183], v[112:115]
	v_mfma_f32_16x16x32_bf16 v[100:103], v[212:215], v[188:191], v[100:103]
	v_mfma_f32_16x16x32_bf16 v[96:99], v[220:223], v[188:191], v[96:99]
	v_mfma_f32_16x16x32_bf16 v[84:87], v[212:215], v[196:199], v[84:87]
	v_mfma_f32_16x16x32_bf16 v[80:83], v[220:223], v[196:199], v[80:83]
	v_mfma_f32_16x16x32_bf16 v[68:71], v[212:215], v[204:207], v[68:71]
	v_mfma_f32_16x16x32_bf16 v[64:67], v[220:223], v[204:207], v[64:67]
	s_setprio 0
	s_mov_b32 m0, s37
	v_lshl_add_u64 v[224:225], v[228:229], 0, s[2:3]
	s_barrier
	ds_read_b128 v[176:179], v165 offset:49152
	ds_read_b128 v[180:183], v165 offset:50176
	ds_read_b128 v[184:187], v165 offset:51200
	ds_read_b128 v[188:191], v165 offset:52224
	ds_read_b128 v[192:195], v165 offset:53248
	ds_read_b128 v[196:199], v165 offset:54272
	ds_read_b128 v[200:203], v165 offset:55296
	ds_read_b128 v[204:207], v165 offset:56320
	global_load_lds_dwordx4 v[224:225], off
	v_lshl_add_u64 v[224:225], v[230:231], 0, s[2:3]
	s_mov_b32 m0, s38
	s_nop 0
	global_load_lds_dwordx4 v[224:225], off
	s_barrier
; #define PG8_STAGE(bufoff, gbase, voff) do { _Pragma("unroll") for (int _i = 0; _i < 2; ++_i) \
;         __builtin_amdgcn_global_load_lds((const unsigned*)((const char*)(gbase) + (voff)[_i]), (LAS unsigned*)(lds + (bufoff) + ldsw + _i * 8192), 16, 0, 0); } while (0)
; #define PG8_MMA(ai, bj, At, Bt) do { __builtin_amdgcn_s_setprio(1); _Pragma("unroll") for (int m = 0; m < 4; ++m) _Pragma("unroll") for (int n = 0; n < 2; ++n) _Pragma("unroll") for (int k = 0; k < 2; ++k) \
;         acc[ai][bj][m][n] = __builtin_amdgcn_mfma_f32_16x16x32_bf16(Bt[n][k], At[m][k], acc[ai][bj][m][n], 0, 0, 0); __builtin_amdgcn_s_setprio(0); } while (0)
; #define PG8_WAIT_V(n) asm volatile("s_waitcnt vmcnt(" #n ")" ::: "memory")
; #define PG8_BAR __builtin_amdgcn_s_barrier()
; __device__ __forceinline__ u32x4 pack8(f32x4 v0, f32x4 v1) { u32x4 w; w.x = cvt_pk_bf16(v0[0], v0[1]); w.y = cvt_pk_bf16(v0[2], v0[3]); w.z = cvt_pk_bf16(v1[0], v1[1]); w.w = cvt_pk_bf16(v1[2], v1[3]); return w; }
; template <class Epi>
; __device__ __forceinline__ void gemm_phase(LAS unsigned char* lds, const Gemm g, const StaticOrder& S, const Epi& E) {
;     ...
;             PG8_STAGE(PG8_SB(1, 1), b3 + hstep, voffB);
;             PG8_WAIT_V(6); PG8_BAR; PG8_MMA(1, 1, At, B1); PG8_BAR;
;     __device__ __forceinline__ void operator()(const f32x4 (&acc)[2][2][4][2], const Unit& u, int wr, int wc, int fr, int fq) const {
;     ...
;             const int col0 = u.pn * BM + wc * 32 + 8 * fq; const float sc = (u.pn < 2) ? QSCALE : 1.0f;
; #pragma unroll
;             for (int ai = 0; ai < 2; ++ai)
; #pragma unroll
;                 for (int m = 0; m < 4; ++m) { bf16_t* rowp = O + (size_t)(row0 + ai * HALF + m * 16) * NQKV + col0; const float scr_ = sc * rowsc[row0 + ai * HALF + m * 16];
; #pragma unroll
;                     for (int bj = 0; bj < 2; ++bj) *(u32x4*)(rowp + bj * HALF) = pack8(acc[ai][bj][m][0] * scr_, acc[ai][bj][m][1] * scr_); }
	s_waitcnt lgkmcnt(0)
	s_setprio 1
	s_waitcnt lgkmcnt(0)
	v_mfma_f32_16x16x32_bf16 v[60:63], v[150:153], v[176:179], v[60:63]
	v_mfma_f32_16x16x32_bf16 v[56:59], v[168:171], v[176:179], v[56:59]
	v_mfma_f32_16x16x32_bf16 v[44:47], v[150:153], v[184:187], v[44:47]
	v_mfma_f32_16x16x32_bf16 v[40:43], v[168:171], v[184:187], v[40:43]
	v_mfma_f32_16x16x32_bf16 v[28:31], v[150:153], v[192:195], v[28:31]
	v_mfma_f32_16x16x32_bf16 v[24:27], v[168:171], v[192:195], v[24:27]
	v_mfma_f32_16x16x32_bf16 v[12:15], v[150:153], v[200:203], v[12:15]
	v_mfma_f32_16x16x32_bf16 v[8:11], v[168:171], v[200:203], v[8:11]
	v_mfma_f32_16x16x32_bf16 v[60:63], v[154:157], v[180:183], v[60:63]
	v_mfma_f32_16x16x32_bf16 v[56:59], v[172:175], v[180:183], v[56:59]
	v_mfma_f32_16x16x32_bf16 v[44:47], v[154:157], v[188:191], v[44:47]
	v_mfma_f32_16x16x32_bf16 v[40:43], v[172:175], v[188:191], v[40:43]
	v_mfma_f32_16x16x32_bf16 v[28:31], v[154:157], v[196:199], v[28:31]
	v_mfma_f32_16x16x32_bf16 v[24:27], v[172:175], v[196:199], v[24:27]
	v_mfma_f32_16x16x32_bf16 v[12:15], v[154:157], v[204:207], v[12:15]
	v_mfma_f32_16x16x32_bf16 v[8:11], v[172:175], v[204:207], v[8:11]
	s_setprio 0
	s_barrier
	s_add_u32 s48, s48, 0x80080
	s_addc_u32 s49, s49, 0
	s_add_i32 s50, s50, s23
	s_mov_b32 m0, s50
	s_nop 0
	global_load_lds_dwordx4 v132, s[48:49]
	s_add_i32 m0, s50, 0x2000
	s_nop 0
	global_load_lds_dwordx4 v128, s[48:49]
	s_waitcnt vmcnt(6)
	s_barrier
	s_setprio 1
	v_mfma_f32_16x16x32_bf16 v[52:55], v[208:211], v[176:179], v[52:55]
	v_mfma_f32_16x16x32_bf16 v[48:51], v[216:219], v[176:179], v[48:51]
	v_mfma_f32_16x16x32_bf16 v[36:39], v[208:211], v[184:187], v[36:39]
	v_mfma_f32_16x16x32_bf16 v[32:35], v[216:219], v[184:187], v[32:35]
	v_mfma_f32_16x16x32_bf16 v[20:23], v[208:211], v[192:195], v[20:23]
	v_mfma_f32_16x16x32_bf16 v[16:19], v[216:219], v[192:195], v[16:19]
	v_mfma_f32_16x16x32_bf16 v[4:7], v[208:211], v[200:203], v[4:7]
	v_mfma_f32_16x16x32_bf16 v[0:3], v[216:219], v[200:203], v[0:3]
	v_mfma_f32_16x16x32_bf16 v[52:55], v[212:215], v[180:183], v[52:55]
	v_mfma_f32_16x16x32_bf16 v[48:51], v[220:223], v[180:183], v[48:51]
	v_mfma_f32_16x16x32_bf16 v[36:39], v[212:215], v[188:191], v[36:39]
	v_mfma_f32_16x16x32_bf16 v[32:35], v[220:223], v[188:191], v[32:35]
	v_mfma_f32_16x16x32_bf16 v[20:23], v[212:215], v[196:199], v[20:23]
	v_mfma_f32_16x16x32_bf16 v[16:19], v[220:223], v[196:199], v[16:19]
	v_mfma_f32_16x16x32_bf16 v[4:7], v[212:215], v[204:207], v[4:7]
	v_mfma_f32_16x16x32_bf16 v[0:3], v[220:223], v[204:207], v[0:3]
	s_setprio 0
	s_add_i32 s57, s57, 2
	s_add_u32 s46, s46, 0x100
	s_addc_u32 s47, s47, 0
	s_add_u32 s55, s55, 0x100
	s_addc_u32 s56, s56, 0
	s_cmp_gt_u32 s57, 29
	s_barrier
	s_cbranch_scc0 .LBB0_407
	v_lshl_add_u32 v154, s44, 8, v160
	s_add_i32 s9, s34, -6
	s_lshl_b32 s7, s34, 8
	s_cmp_gt_u32 s9, 11
	s_mov_b64 s[44:45], -1
	v_ashrrev_i32_e32 v155, 31, v154
	v_or_b32_e32 v174, 16, v154
	v_or_b32_e32 v173, 32, v154
	v_or_b32_e32 v172, 48, v154
	v_add_u32_e32 v171, 0x80, v154
	v_add_u32_e32 v170, 0x90, v154
	v_add_u32_e32 v169, 0xa0, v154
	v_add_u32_e32 v168, 0xb0, v154
	s_cbranch_scc0 .LBB0_410
	v_lshl_add_u64 v[150:151], v[154:155], 2, s[14:15]
	global_load_dword v136, v[150:151], off
	global_load_dword v204, v[150:151], off offset:64
	global_load_dword v205, v[150:151], off offset:128
	global_load_dword v206, v[150:151], off offset:192
	global_load_dword v207, v[150:151], off offset:512
	global_load_dword v208, v[150:151], off offset:576
	global_load_dword v209, v[150:151], off offset:640
	global_load_dword v210, v[150:151], off offset:704
	s_cmp_lt_i32 s34, 2
	v_or_b32_e32 v156, s7, v162
	s_cselect_b64 vcc, -1, 0
	v_mov_b64_e32 v[152:153], s[20:21]
	v_cndmask_b32_e32 v175, 1.0, v167, vcc
	v_ashrrev_i32_e32 v157, 31, v156
	v_mad_i64_i32 v[176:177], s[44:45], v154, s53, v[152:153]
	v_lshlrev_b64 v[156:157], 1, v[156:157]
	v_lshl_add_u64 v[180:181], v[176:177], 0, v[156:157]
	s_waitcnt vmcnt(0)
	v_mul_f32_e32 v136, v175, v136
	v_pk_mul_f32 v[178:179], v[126:127], v[136:137] op_sel_hi:[1,0]
	v_pk_mul_f32 v[176:177], v[124:125], v[136:137] op_sel_hi:[1,0]
	v_pk_mul_f32 v[182:183], v[122:123], v[136:137] op_sel_hi:[1,0]
	v_pk_mul_f32 v[184:185], v[120:121], v[136:137] op_sel_hi:[1,0]
	v_cvt_pk_bf16_f32 v176, v176, v177
	v_cvt_pk_bf16_f32 v177, v178, v179
	v_pk_mul_f32 v[186:187], v[118:119], v[136:137] op_sel_hi:[1,0]
	v_cvt_pk_bf16_f32 v178, v184, v185
	v_cvt_pk_bf16_f32 v179, v182, v183
	v_pk_mul_f32 v[188:189], v[116:117], v[136:137] op_sel_hi:[1,0]
	v_pk_mul_f32 v[190:191], v[114:115], v[136:137] op_sel_hi:[1,0]
	v_pk_mul_f32 v[192:193], v[112:113], v[136:137] op_sel_hi:[1,0]
	global_store_dwordx4 v[180:181], v[176:179], off
	s_nop 1
	v_cvt_pk_bf16_f32 v176, v188, v189
	v_cvt_pk_bf16_f32 v177, v186, v187
	v_cvt_pk_bf16_f32 v178, v192, v193
	v_cvt_pk_bf16_f32 v179, v190, v191
	global_store_dwordx4 v[180:181], v[176:179], off offset:256
	s_nop 1
	v_mov_b32_e32 v136, v204
	v_mul_f32_e32 v136, v175, v136
	v_mad_i64_i32 v[176:177], s[44:45], v174, s53, v[152:153]
	v_lshl_add_u64 v[180:181], v[176:177], 0, v[156:157]
	v_pk_mul_f32 v[178:179], v[110:111], v[136:137] op_sel_hi:[1,0]
	v_pk_mul_f32 v[176:177], v[108:109], v[136:137] op_sel_hi:[1,0]
	v_pk_mul_f32 v[182:183], v[106:107], v[136:137] op_sel_hi:[1,0]
	v_pk_mul_f32 v[184:185], v[104:105], v[136:137] op_sel_hi:[1,0]
	v_cvt_pk_bf16_f32 v176, v176, v177
	v_cvt_pk_bf16_f32 v177, v178, v179
	v_pk_mul_f32 v[186:187], v[102:103], v[136:137] op_sel_hi:[1,0]
	v_cvt_pk_bf16_f32 v178, v184, v185
	v_cvt_pk_bf16_f32 v179, v182, v183
	v_pk_mul_f32 v[188:189], v[100:101], v[136:137] op_sel_hi:[1,0]
; __device__ __forceinline__ u32x4 pack8(f32x4 v0, f32x4 v1) { u32x4 w; w.x = cvt_pk_bf16(v0[0], v0[1]); w.y = cvt_pk_bf16(v0[2], v0[3]); w.z = cvt_pk_bf16(v1[0], v1[1]); w.w = cvt_pk_bf16(v1[2], v1[3]); return w; }
;     __device__ __forceinline__ void operator()(const f32x4 (&acc)[2][2][4][2], const Unit& u, int wr, int wc, int fr, int fq) const {
;     ...
;             const int col0 = u.pn * BM + wc * 32 + 8 * fq; const float sc = (u.pn < 2) ? QSCALE : 1.0f;
; #pragma unroll
;             for (int ai = 0; ai < 2; ++ai)
; #pragma unroll
;                 for (int m = 0; m < 4; ++m) { bf16_t* rowp = O + (size_t)(row0 + ai * HALF + m * 16) * NQKV + col0; const float scr_ = sc * rowsc[row0 + ai * HALF + m * 16];
; #pragma unroll
;                     for (int bj = 0; bj < 2; ++bj) *(u32x4*)(rowp + bj * HALF) = pack8(acc[ai][bj][m][0] * scr_, acc[ai][bj][m][1] * scr_); }
	v_pk_mul_f32 v[190:191], v[98:99], v[136:137] op_sel_hi:[1,0]
	v_pk_mul_f32 v[192:193], v[96:97], v[136:137] op_sel_hi:[1,0]
	global_store_dwordx4 v[180:181], v[176:179], off
	s_nop 1
	v_cvt_pk_bf16_f32 v176, v188, v189
	v_cvt_pk_bf16_f32 v177, v186, v187
	v_cvt_pk_bf16_f32 v178, v192, v193
	v_cvt_pk_bf16_f32 v179, v190, v191
	global_store_dwordx4 v[180:181], v[176:179], off offset:256
	s_nop 1
	v_mov_b32_e32 v136, v205
	v_mul_f32_e32 v136, v175, v136
	v_mad_i64_i32 v[176:177], s[44:45], v173, s53, v[152:153]
	v_lshl_add_u64 v[180:181], v[176:177], 0, v[156:157]
	v_pk_mul_f32 v[178:179], v[94:95], v[136:137] op_sel_hi:[1,0]
	v_pk_mul_f32 v[176:177], v[92:93], v[136:137] op_sel_hi:[1,0]
	v_pk_mul_f32 v[182:183], v[90:91], v[136:137] op_sel_hi:[1,0]
	v_pk_mul_f32 v[184:185], v[88:89], v[136:137] op_sel_hi:[1,0]
	v_cvt_pk_bf16_f32 v176, v176, v177
	v_cvt_pk_bf16_f32 v177, v178, v179
	v_pk_mul_f32 v[186:187], v[86:87], v[136:137] op_sel_hi:[1,0]
	v_cvt_pk_bf16_f32 v178, v184, v185
	v_cvt_pk_bf16_f32 v179, v182, v183
	v_pk_mul_f32 v[188:189], v[84:85], v[136:137] op_sel_hi:[1,0]
	v_pk_mul_f32 v[190:191], v[82:83], v[136:137] op_sel_hi:[1,0]
	v_pk_mul_f32 v[192:193], v[80:81], v[136:137] op_sel_hi:[1,0]
	global_store_dwordx4 v[180:181], v[176:179], off
	s_nop 1
	v_cvt_pk_bf16_f32 v176, v188, v189
	v_cvt_pk_bf16_f32 v177, v186, v187
	v_cvt_pk_bf16_f32 v178, v192, v193
	v_cvt_pk_bf16_f32 v179, v190, v191
	global_store_dwordx4 v[180:181], v[176:179], off offset:256
	s_nop 1
	v_mov_b32_e32 v136, v206
	v_mul_f32_e32 v136, v175, v136
	v_mad_i64_i32 v[176:177], s[44:45], v172, s53, v[152:153]
	v_lshl_add_u64 v[180:181], v[176:177], 0, v[156:157]
	v_pk_mul_f32 v[178:179], v[78:79], v[136:137] op_sel_hi:[1,0]
	v_pk_mul_f32 v[176:177], v[76:77], v[136:137] op_sel_hi:[1,0]
	v_pk_mul_f32 v[182:183], v[74:75], v[136:137] op_sel_hi:[1,0]
	v_pk_mul_f32 v[184:185], v[72:73], v[136:137] op_sel_hi:[1,0]
	v_cvt_pk_bf16_f32 v176, v176, v177
	v_cvt_pk_bf16_f32 v177, v178, v179
	v_pk_mul_f32 v[186:187], v[70:71], v[136:137] op_sel_hi:[1,0]
	v_cvt_pk_bf16_f32 v178, v184, v185
	v_cvt_pk_bf16_f32 v179, v182, v183
	v_pk_mul_f32 v[188:189], v[68:69], v[136:137] op_sel_hi:[1,0]
	v_pk_mul_f32 v[190:191], v[66:67], v[136:137] op_sel_hi:[1,0]
	v_pk_mul_f32 v[192:193], v[64:65], v[136:137] op_sel_hi:[1,0]
	global_store_dwordx4 v[180:181], v[176:179], off
	s_nop 1
	v_cvt_pk_bf16_f32 v176, v188, v189
	v_cvt_pk_bf16_f32 v177, v186, v187
	v_cvt_pk_bf16_f32 v178, v192, v193
	v_cvt_pk_bf16_f32 v179, v190, v191
	global_store_dwordx4 v[180:181], v[176:179], off offset:256
	s_nop 1
	v_mov_b32_e32 v136, v207
	v_mul_f32_e32 v136, v175, v136
	v_mad_i64_i32 v[176:177], s[44:45], v171, s53, v[152:153]
	v_lshl_add_u64 v[180:181], v[176:177], 0, v[156:157]
	v_pk_mul_f32 v[178:179], v[62:63], v[136:137] op_sel_hi:[1,0]
	v_pk_mul_f32 v[176:177], v[60:61], v[136:137] op_sel_hi:[1,0]
	v_pk_mul_f32 v[182:183], v[58:59], v[136:137] op_sel_hi:[1,0]
	v_pk_mul_f32 v[184:185], v[56:57], v[136:137] op_sel_hi:[1,0]
	v_cvt_pk_bf16_f32 v176, v176, v177
	v_cvt_pk_bf16_f32 v177, v178, v179
	v_pk_mul_f32 v[186:187], v[54:55], v[136:137] op_sel_hi:[1,0]
	v_cvt_pk_bf16_f32 v178, v184, v185
	v_cvt_pk_bf16_f32 v179, v182, v183
	v_pk_mul_f32 v[188:189], v[52:53], v[136:137] op_sel_hi:[1,0]
	v_pk_mul_f32 v[190:191], v[50:51], v[136:137] op_sel_hi:[1,0]
	v_pk_mul_f32 v[192:193], v[48:49], v[136:137] op_sel_hi:[1,0]
	global_store_dwordx4 v[180:181], v[176:179], off
	s_nop 1
	v_cvt_pk_bf16_f32 v176, v188, v189
	v_cvt_pk_bf16_f32 v177, v186, v187
	v_cvt_pk_bf16_f32 v178, v192, v193
	v_cvt_pk_bf16_f32 v179, v190, v191
	global_store_dwordx4 v[180:181], v[176:179], off offset:256
	s_nop 1
	v_mov_b32_e32 v136, v208
	v_mul_f32_e32 v136, v175, v136
	v_mad_i64_i32 v[176:177], s[44:45], v170, s53, v[152:153]
	v_lshl_add_u64 v[180:181], v[176:177], 0, v[156:157]
	v_pk_mul_f32 v[178:179], v[46:47], v[136:137] op_sel_hi:[1,0]
	v_pk_mul_f32 v[176:177], v[44:45], v[136:137] op_sel_hi:[1,0]
	v_pk_mul_f32 v[182:183], v[42:43], v[136:137] op_sel_hi:[1,0]
	v_pk_mul_f32 v[184:185], v[40:41], v[136:137] op_sel_hi:[1,0]
	v_cvt_pk_bf16_f32 v176, v176, v177
	v_cvt_pk_bf16_f32 v177, v178, v179
	v_pk_mul_f32 v[186:187], v[38:39], v[136:137] op_sel_hi:[1,0]
	v_cvt_pk_bf16_f32 v178, v184, v185
	v_cvt_pk_bf16_f32 v179, v182, v183
	v_pk_mul_f32 v[188:189], v[36:37], v[136:137] op_sel_hi:[1,0]
	v_pk_mul_f32 v[190:191], v[34:35], v[136:137] op_sel_hi:[1,0]
	v_pk_mul_f32 v[192:193], v[32:33], v[136:137] op_sel_hi:[1,0]
	global_store_dwordx4 v[180:181], v[176:179], off
	s_nop 1
	v_cvt_pk_bf16_f32 v176, v188, v189
	v_cvt_pk_bf16_f32 v177, v186, v187
	v_cvt_pk_bf16_f32 v178, v192, v193
	v_cvt_pk_bf16_f32 v179, v190, v191
	global_store_dwordx4 v[180:181], v[176:179], off offset:256
	s_nop 1
	v_mov_b32_e32 v136, v209
	v_mul_f32_e32 v136, v175, v136
	v_mad_i64_i32 v[176:177], s[44:45], v169, s53, v[152:153]
	v_lshl_add_u64 v[180:181], v[176:177], 0, v[156:157]
	v_pk_mul_f32 v[178:179], v[30:31], v[136:137] op_sel_hi:[1,0]
	v_pk_mul_f32 v[176:177], v[28:29], v[136:137] op_sel_hi:[1,0]
	v_pk_mul_f32 v[182:183], v[26:27], v[136:137] op_sel_hi:[1,0]
	v_pk_mul_f32 v[184:185], v[24:25], v[136:137] op_sel_hi:[1,0]
	v_cvt_pk_bf16_f32 v176, v176, v177
	v_cvt_pk_bf16_f32 v177, v178, v179
	v_pk_mul_f32 v[186:187], v[22:23], v[136:137] op_sel_hi:[1,0]
	v_cvt_pk_bf16_f32 v178, v184, v185
	v_cvt_pk_bf16_f32 v179, v182, v183
	v_pk_mul_f32 v[188:189], v[20:21], v[136:137] op_sel_hi:[1,0]
	v_pk_mul_f32 v[190:191], v[18:19], v[136:137] op_sel_hi:[1,0]
	v_pk_mul_f32 v[192:193], v[16:17], v[136:137] op_sel_hi:[1,0]
	global_store_dwordx4 v[180:181], v[176:179], off
	s_nop 1
	v_cvt_pk_bf16_f32 v176, v188, v189
	v_cvt_pk_bf16_f32 v177, v186, v187
	v_cvt_pk_bf16_f32 v178, v192, v193
	v_cvt_pk_bf16_f32 v179, v190, v191
	global_store_dwordx4 v[180:181], v[176:179], off offset:256
	s_nop 1
	v_mov_b32_e32 v136, v210
	v_mad_i64_i32 v[150:151], s[44:45], v168, s53, v[152:153]
	v_lshl_add_u64 v[156:157], v[150:151], 0, v[156:157]
	s_mov_b64 s[44:45], 0
	v_mul_f32_e32 v136, v175, v136
	v_pk_mul_f32 v[152:153], v[14:15], v[136:137] op_sel_hi:[1,0]
	v_pk_mul_f32 v[150:151], v[12:13], v[136:137] op_sel_hi:[1,0]
	v_pk_mul_f32 v[176:177], v[10:11], v[136:137] op_sel_hi:[1,0]
	v_pk_mul_f32 v[178:179], v[8:9], v[136:137] op_sel_hi:[1,0]
	v_cvt_pk_bf16_f32 v150, v150, v151
	v_cvt_pk_bf16_f32 v151, v152, v153
	v_pk_mul_f32 v[180:181], v[6:7], v[136:137] op_sel_hi:[1,0]
	v_cvt_pk_bf16_f32 v152, v178, v179
	v_cvt_pk_bf16_f32 v153, v176, v177
	v_pk_mul_f32 v[182:183], v[4:5], v[136:137] op_sel_hi:[1,0]
	v_pk_mul_f32 v[184:185], v[2:3], v[136:137] op_sel_hi:[1,0]
	v_pk_mul_f32 v[186:187], v[0:1], v[136:137] op_sel_hi:[1,0]
	global_store_dwordx4 v[156:157], v[150:153], off
	s_nop 1
	v_cvt_pk_bf16_f32 v150, v182, v183
	v_cvt_pk_bf16_f32 v151, v180, v181
	v_cvt_pk_bf16_f32 v152, v186, v187
	v_cvt_pk_bf16_f32 v153, v184, v185
	global_store_dwordx4 v[156:157], v[150:153], off offset:256

; #define PG8_STAGE(bufoff, gbase, voff) do { _Pragma("unroll") for (int _i = 0; _i < 2; ++_i) \
;         __builtin_amdgcn_global_load_lds((const unsigned*)((const char*)(gbase) + (voff)[_i]), (LAS unsigned*)(lds + (bufoff) + ldsw + _i * 8192), 16, 0, 0); } while (0)
; #define PG8_LDA(dst, b, h) do { _Pragma("unroll") for (int m = 0; m < 4; ++m) _Pragma("unroll") for (int k = 0; k < 2; ++k) dst[m][k] = *(const LAS bf16x8*)(lds + PG8_SA(b, h) + aoff + m * 2048 + k * 1024); } while (0)
; #define PG8_LDB(dst, b, h) do { _Pragma("unroll") for (int n = 0; n < 2; ++n) _Pragma("unroll") for (int k = 0; k < 2; ++k) dst[n][k] = *(const LAS bf16x8*)(lds + PG8_SB(b, h) + boff + n * 2048 + k * 1024); } while (0)
; #define PG8_MMA(ai, bj, At, Bt) do { __builtin_amdgcn_s_setprio(1); _Pragma("unroll") for (int m = 0; m < 4; ++m) _Pragma("unroll") for (int n = 0; n < 2; ++n) _Pragma("unroll") for (int k = 0; k < 2; ++k) \
;         acc[ai][bj][m][n] = __builtin_amdgcn_mfma_f32_16x16x32_bf16(Bt[n][k], At[m][k], acc[ai][bj][m][n], 0, 0, 0); __builtin_amdgcn_s_setprio(0); } while (0)
; #define PG8_WAIT_V(n) asm volatile("s_waitcnt vmcnt(" #n ")" ::: "memory")
; #define PG8_WAIT_L(n) asm volatile("s_waitcnt lgkmcnt(" #n ")" ::: "memory")
; #define PG8_BAR __builtin_amdgcn_s_barrier()
; #define PG8_SCHED __builtin_amdgcn_sched_barrier(0)
; template <class Epi>
; __device__ __forceinline__ void gemm_phase(LAS unsigned char* lds, const Gemm g, const StaticOrder& S, const Epi& E) {
;     ...
;             PG8_LDB(B0, 0, 0); PG8_SCHED; PG8_LDA(At, 0, 0); PG8_STAGE(PG8_SA(1, 1), a1 + hstep, voffA);
;             PG8_WAIT_L(8); PG8_BAR; PG8_WAIT_L(0); PG8_MMA(0, 0, At, B0); PG8_BAR; PG8_SCHED;
;             PG8_LDB(B1, 0, 1); PG8_STAGE(PG8_SB(0, 0), b2, voffB);
;             PG8_BAR; PG8_WAIT_L(0); PG8_MMA(0, 1, At, B1); PG8_BAR;
;             PG8_LDA(At, 0, 1); PG8_STAGE(PG8_SA(0, 0), a2, voffA);
;             PG8_BAR; PG8_WAIT_L(0); PG8_MMA(1, 0, At, B0); PG8_BAR; PG8_SCHED;
;             PG8_STAGE(PG8_SB(0, 1), b2 + hstep, voffB);
;             PG8_WAIT_V(6); PG8_BAR; PG8_MMA(1, 1, At, B1); PG8_BAR;
.LBB0_673:
	ds_read_b128 v[148:151], v145
	ds_read_b128 v[152:155], v145 offset:1024
	ds_read_b128 v[160:163], v145 offset:2048
	ds_read_b128 v[164:167], v145 offset:3072
	s_add_u32 s52, s50, 0xfff80080
	s_addc_u32 s53, s51, -1
	s_cmp_eq_u32 s69, 28
	s_cselect_b32 s55, s43, s53
	s_cselect_b32 s54, s65, s52
	s_cselect_b32 s53, s41, s68
	s_cselect_b32 s52, s66, s67
	s_add_i32 m0, s28, 0xc000
	ds_read_b128 v[168:171], v146
	ds_read_b128 v[172:175], v146 offset:1024
	ds_read_b128 v[176:179], v146 offset:2048
	ds_read_b128 v[180:183], v146 offset:3072
	ds_read_b128 v[184:187], v146 offset:4096
	ds_read_b128 v[188:191], v146 offset:5120
	ds_read_b128 v[192:195], v146 offset:6144
	ds_read_b128 v[196:199], v146 offset:7168
	global_load_lds_dwordx4 v136, s[50:51]
	s_add_i32 m0, s28, 0xe000
	s_nop 0
	global_load_lds_dwordx4 v138, s[50:51]
	s_waitcnt lgkmcnt(8)
	s_barrier
	s_waitcnt lgkmcnt(0)
	s_setprio 1
	s_waitcnt lgkmcnt(0)
	v_mfma_f32_16x16x32_bf16 v[124:127], v[148:151], v[168:171], v[124:127]
	v_mfma_f32_16x16x32_bf16 v[120:123], v[160:163], v[168:171], v[120:123]
	v_mfma_f32_16x16x32_bf16 v[112:115], v[148:151], v[176:179], v[112:115]
	v_mfma_f32_16x16x32_bf16 v[104:107], v[160:163], v[176:179], v[104:107]
	v_mfma_f32_16x16x32_bf16 v[96:99], v[148:151], v[184:187], v[96:99]
	v_mfma_f32_16x16x32_bf16 v[88:91], v[160:163], v[184:187], v[88:91]
	v_mfma_f32_16x16x32_bf16 v[80:83], v[148:151], v[192:195], v[80:83]
	v_mfma_f32_16x16x32_bf16 v[72:75], v[160:163], v[192:195], v[72:75]
	v_mfma_f32_16x16x32_bf16 v[124:127], v[152:155], v[172:175], v[124:127]
	v_mfma_f32_16x16x32_bf16 v[120:123], v[164:167], v[172:175], v[120:123]
	v_mfma_f32_16x16x32_bf16 v[112:115], v[152:155], v[180:183], v[112:115]
	v_mfma_f32_16x16x32_bf16 v[104:107], v[164:167], v[180:183], v[104:107]
	v_mfma_f32_16x16x32_bf16 v[96:99], v[152:155], v[188:191], v[96:99]
	v_mfma_f32_16x16x32_bf16 v[88:91], v[164:167], v[188:191], v[88:91]
	v_mfma_f32_16x16x32_bf16 v[80:83], v[152:155], v[196:199], v[80:83]
	v_mfma_f32_16x16x32_bf16 v[72:75], v[164:167], v[196:199], v[72:75]
	s_setprio 0
	s_barrier
	s_add_i32 s70, s58, s23
	v_lshl_add_u64 v[140:141], s[52:53], 0, v[132:133]
	s_mov_b32 m0, s70
	ds_read_b128 v[200:203], v147
	ds_read_b128 v[204:207], v147 offset:1024
	ds_read_b128 v[208:211], v147 offset:2048
	ds_read_b128 v[212:215], v147 offset:3072
	global_load_lds_dwordx4 v132, s[52:53]
	v_lshl_add_u64 v[156:157], s[52:53], 0, v[128:129]
	s_add_i32 m0, s70, 0x2000
	s_nop 0
	global_load_lds_dwordx4 v128, s[52:53]
	s_barrier
	s_waitcnt lgkmcnt(0)
	s_setprio 1
	s_waitcnt lgkmcnt(0)
	v_mfma_f32_16x16x32_bf16 v[116:119], v[200:203], v[168:171], v[116:119]
	v_mfma_f32_16x16x32_bf16 v[108:111], v[208:211], v[168:171], v[108:111]
	v_mfma_f32_16x16x32_bf16 v[100:103], v[200:203], v[176:179], v[100:103]
	v_mfma_f32_16x16x32_bf16 v[92:95], v[208:211], v[176:179], v[92:95]
	v_mfma_f32_16x16x32_bf16 v[84:87], v[200:203], v[184:187], v[84:87]
	v_mfma_f32_16x16x32_bf16 v[76:79], v[208:211], v[184:187], v[76:79]
	v_mfma_f32_16x16x32_bf16 v[68:71], v[200:203], v[192:195], v[68:71]
	v_mfma_f32_16x16x32_bf16 v[64:67], v[208:211], v[192:195], v[64:67]
	v_mfma_f32_16x16x32_bf16 v[116:119], v[204:207], v[172:175], v[116:119]
	v_mfma_f32_16x16x32_bf16 v[108:111], v[212:215], v[172:175], v[108:111]
	v_mfma_f32_16x16x32_bf16 v[100:103], v[204:207], v[180:183], v[100:103]
	v_mfma_f32_16x16x32_bf16 v[92:95], v[212:215], v[180:183], v[92:95]
	v_mfma_f32_16x16x32_bf16 v[84:87], v[204:207], v[188:191], v[84:87]
	v_mfma_f32_16x16x32_bf16 v[76:79], v[212:215], v[188:191], v[76:79]
	v_mfma_f32_16x16x32_bf16 v[68:71], v[204:207], v[196:199], v[68:71]
	v_mfma_f32_16x16x32_bf16 v[64:67], v[212:215], v[196:199], v[64:67]
	s_setprio 0
	s_mov_b32 m0, s28
	v_lshl_add_u64 v[216:217], s[54:55], 0, v[134:135]
	s_barrier
	ds_read_b128 v[168:171], v146 offset:16384
	ds_read_b128 v[172:175], v146 offset:17408
	ds_read_b128 v[176:179], v146 offset:18432
	ds_read_b128 v[180:183], v146 offset:19456
	ds_read_b128 v[184:187], v146 offset:20480
	ds_read_b128 v[188:191], v146 offset:21504
	ds_read_b128 v[192:195], v146 offset:22528
	ds_read_b128 v[196:199], v146 offset:23552
	global_load_lds_dwordx4 v134, s[54:55]
	v_lshl_add_u64 v[218:219], s[54:55], 0, v[130:131]
	s_mov_b32 m0, s29
	s_nop 0
	global_load_lds_dwordx4 v130, s[54:55]
	s_barrier
	s_waitcnt lgkmcnt(0)
	s_setprio 1
	s_waitcnt lgkmcnt(0)
	v_mfma_f32_16x16x32_bf16 v[60:63], v[148:151], v[168:171], v[60:63]
	v_mfma_f32_16x16x32_bf16 v[56:59], v[160:163], v[168:171], v[56:59]
	v_mfma_f32_16x16x32_bf16 v[52:55], v[148:151], v[176:179], v[52:55]
	v_mfma_f32_16x16x32_bf16 v[44:47], v[160:163], v[176:179], v[44:47]
	v_mfma_f32_16x16x32_bf16 v[36:39], v[148:151], v[184:187], v[36:39]
	v_mfma_f32_16x16x32_bf16 v[28:31], v[160:163], v[184:187], v[28:31]
	v_mfma_f32_16x16x32_bf16 v[20:23], v[148:151], v[192:195], v[20:23]
	v_mfma_f32_16x16x32_bf16 v[12:15], v[160:163], v[192:195], v[12:15]
	v_mfma_f32_16x16x32_bf16 v[60:63], v[152:155], v[172:175], v[60:63]
	v_mfma_f32_16x16x32_bf16 v[56:59], v[164:167], v[172:175], v[56:59]
	v_mfma_f32_16x16x32_bf16 v[52:55], v[152:155], v[180:183], v[52:55]
	v_mfma_f32_16x16x32_bf16 v[44:47], v[164:167], v[180:183], v[44:47]
	v_mfma_f32_16x16x32_bf16 v[36:39], v[152:155], v[188:191], v[36:39]
	v_mfma_f32_16x16x32_bf16 v[28:31], v[164:167], v[188:191], v[28:31]
	v_mfma_f32_16x16x32_bf16 v[20:23], v[152:155], v[196:199], v[20:23]
	v_mfma_f32_16x16x32_bf16 v[12:15], v[164:167], v[196:199], v[12:15]
	s_setprio 0
	s_barrier
; #define PG8_STAGE(bufoff, gbase, voff) do { _Pragma("unroll") for (int _i = 0; _i < 2; ++_i) \
;         __builtin_amdgcn_global_load_lds((const unsigned*)((const char*)(gbase) + (voff)[_i]), (LAS unsigned*)(lds + (bufoff) + ldsw + _i * 8192), 16, 0, 0); } while (0)
; #define PG8_LDA(dst, b, h) do { _Pragma("unroll") for (int m = 0; m < 4; ++m) _Pragma("unroll") for (int k = 0; k < 2; ++k) dst[m][k] = *(const LAS bf16x8*)(lds + PG8_SA(b, h) + aoff + m * 2048 + k * 1024); } while (0)
; #define PG8_LDB(dst, b, h) do { _Pragma("unroll") for (int n = 0; n < 2; ++n) _Pragma("unroll") for (int k = 0; k < 2; ++k) dst[n][k] = *(const LAS bf16x8*)(lds + PG8_SB(b, h) + boff + n * 2048 + k * 1024); } while (0)
; #define PG8_MMA(ai, bj, At, Bt) do { __builtin_amdgcn_s_setprio(1); _Pragma("unroll") for (int m = 0; m < 4; ++m) _Pragma("unroll") for (int n = 0; n < 2; ++n) _Pragma("unroll") for (int k = 0; k < 2; ++k) \
;         acc[ai][bj][m][n] = __builtin_amdgcn_mfma_f32_16x16x32_bf16(Bt[n][k], At[m][k], acc[ai][bj][m][n], 0, 0, 0); __builtin_amdgcn_s_setprio(0); } while (0)
; #define PG8_WAIT_V(n) asm volatile("s_waitcnt vmcnt(" #n ")" ::: "memory")
; #define PG8_WAIT_L(n) asm volatile("s_waitcnt lgkmcnt(" #n ")" ::: "memory")
; #define PG8_BAR __builtin_amdgcn_s_barrier()
; #define PG8_SCHED __builtin_amdgcn_sched_barrier(0)
; template <class Epi>
; __device__ __forceinline__ void gemm_phase(LAS unsigned char* lds, const Gemm g, const StaticOrder& S, const Epi& E) {
;     ...
;             PG8_WAIT_V(6); PG8_BAR; PG8_MMA(1, 1, At, B1); PG8_BAR;
;             PG8_LDB(B0, 1, 0); PG8_SCHED; PG8_LDA(At, 1, 0); PG8_STAGE(PG8_SA(0, 1), a2 + hstep, voffA);
;             PG8_WAIT_L(8); PG8_BAR; PG8_WAIT_L(0); PG8_MMA(0, 0, At, B0); PG8_BAR; PG8_SCHED;
;             PG8_LDB(B1, 1, 1); PG8_STAGE(PG8_SB(1, 0), b3, voffB);
;             PG8_BAR; PG8_WAIT_L(0); PG8_MMA(0, 1, At, B1); PG8_BAR;
;             PG8_LDA(At, 1, 1); PG8_STAGE(PG8_SA(1, 0), a3, voffA);
;             PG8_BAR; PG8_WAIT_L(0); PG8_MMA(1, 0, At, B0); PG8_BAR; PG8_SCHED;
	s_add_u32 s70, s52, 0x80000
	s_addc_u32 s71, s53, 0
	s_add_i32 s72, s59, s23
	s_mov_b32 m0, s72
	s_nop 0
	global_load_lds_dwordx4 v132, s[70:71]
	s_add_i32 m0, s72, 0x2000
	s_nop 0
	global_load_lds_dwordx4 v128, s[70:71]
	s_waitcnt vmcnt(6)
	s_barrier
	s_setprio 1
	v_mfma_f32_16x16x32_bf16 v[48:51], v[200:203], v[168:171], v[48:51]
	v_mfma_f32_16x16x32_bf16 v[40:43], v[208:211], v[168:171], v[40:43]
	v_mfma_f32_16x16x32_bf16 v[32:35], v[200:203], v[176:179], v[32:35]
	v_mfma_f32_16x16x32_bf16 v[24:27], v[208:211], v[176:179], v[24:27]
	v_mfma_f32_16x16x32_bf16 v[16:19], v[200:203], v[184:187], v[16:19]
	v_mfma_f32_16x16x32_bf16 v[8:11], v[208:211], v[184:187], v[8:11]
	v_mfma_f32_16x16x32_bf16 v[4:7], v[200:203], v[192:195], v[4:7]
	v_mfma_f32_16x16x32_bf16 v[0:3], v[208:211], v[192:195], v[0:3]
	v_mfma_f32_16x16x32_bf16 v[48:51], v[204:207], v[172:175], v[48:51]
	v_mfma_f32_16x16x32_bf16 v[40:43], v[212:215], v[172:175], v[40:43]
	v_mfma_f32_16x16x32_bf16 v[32:35], v[204:207], v[180:183], v[32:35]
	v_mfma_f32_16x16x32_bf16 v[24:27], v[212:215], v[180:183], v[24:27]
	v_mfma_f32_16x16x32_bf16 v[16:19], v[204:207], v[188:191], v[16:19]
	v_mfma_f32_16x16x32_bf16 v[8:11], v[212:215], v[188:191], v[8:11]
	v_mfma_f32_16x16x32_bf16 v[4:7], v[204:207], v[196:199], v[4:7]
	v_mfma_f32_16x16x32_bf16 v[0:3], v[212:215], v[196:199], v[0:3]
	s_setprio 0
	s_add_i32 s70, 0, 0x18000
	v_add_u32_e32 v164, s70, v143
	s_barrier
	ds_read_b128 v[148:151], v164
	ds_read_b128 v[152:155], v164 offset:1024
	ds_read_b128 v[160:163], v164 offset:2048
	ds_read_b128 v[164:167], v164 offset:3072
	s_add_u32 s54, s54, 0x80000
	s_addc_u32 s55, s55, 0
	s_mov_b32 m0, s33
	ds_read_b128 v[168:171], v146 offset:32768
	ds_read_b128 v[172:175], v146 offset:33792
	ds_read_b128 v[176:179], v146 offset:34816
	ds_read_b128 v[180:183], v146 offset:35840
	ds_read_b128 v[184:187], v146 offset:36864
	ds_read_b128 v[188:191], v146 offset:37888
	ds_read_b128 v[192:195], v146 offset:38912
	ds_read_b128 v[196:199], v146 offset:39936
	global_load_lds_dwordx4 v134, s[54:55]
	s_mov_b32 m0, s36
	s_nop 0
	global_load_lds_dwordx4 v130, s[54:55]
	s_waitcnt lgkmcnt(8)
	s_barrier
	s_waitcnt lgkmcnt(0)
	s_setprio 1
	s_waitcnt lgkmcnt(0)
	v_mfma_f32_16x16x32_bf16 v[124:127], v[148:151], v[168:171], v[124:127]
	v_mfma_f32_16x16x32_bf16 v[120:123], v[160:163], v[168:171], v[120:123]
	v_mfma_f32_16x16x32_bf16 v[112:115], v[148:151], v[176:179], v[112:115]
	v_mfma_f32_16x16x32_bf16 v[104:107], v[160:163], v[176:179], v[104:107]
	v_mfma_f32_16x16x32_bf16 v[96:99], v[148:151], v[184:187], v[96:99]
	v_mfma_f32_16x16x32_bf16 v[88:91], v[160:163], v[184:187], v[88:91]
	v_mfma_f32_16x16x32_bf16 v[80:83], v[148:151], v[192:195], v[80:83]
	v_mfma_f32_16x16x32_bf16 v[72:75], v[160:163], v[192:195], v[72:75]
	v_mfma_f32_16x16x32_bf16 v[124:127], v[152:155], v[172:175], v[124:127]
	v_mfma_f32_16x16x32_bf16 v[120:123], v[164:167], v[172:175], v[120:123]
	v_mfma_f32_16x16x32_bf16 v[112:115], v[152:155], v[180:183], v[112:115]
	v_mfma_f32_16x16x32_bf16 v[104:107], v[164:167], v[180:183], v[104:107]
	v_mfma_f32_16x16x32_bf16 v[96:99], v[152:155], v[188:191], v[96:99]
	v_mfma_f32_16x16x32_bf16 v[88:91], v[164:167], v[188:191], v[88:91]
	v_mfma_f32_16x16x32_bf16 v[80:83], v[152:155], v[196:199], v[80:83]
	v_mfma_f32_16x16x32_bf16 v[72:75], v[164:167], v[196:199], v[72:75]
	s_setprio 0
	s_barrier
	s_add_i32 s54, 0, 0x1c000
	s_add_i32 s55, s70, s23
	v_add_u32_e32 v212, s54, v143
	v_lshl_add_u64 v[140:141], v[140:141], 0, s[6:7]
	s_mov_b32 m0, s55
	ds_read_b128 v[200:203], v212
	ds_read_b128 v[204:207], v212 offset:1024
	ds_read_b128 v[208:211], v212 offset:2048
	ds_read_b128 v[212:215], v212 offset:3072
	global_load_lds_dwordx4 v[140:141], off
	v_lshl_add_u64 v[140:141], v[156:157], 0, s[6:7]
	s_add_i32 m0, s55, 0x2000
	s_nop 0
	global_load_lds_dwordx4 v[140:141], off
	s_barrier
	s_waitcnt lgkmcnt(0)
	s_setprio 1
	s_waitcnt lgkmcnt(0)
	v_mfma_f32_16x16x32_bf16 v[116:119], v[200:203], v[168:171], v[116:119]
	v_mfma_f32_16x16x32_bf16 v[108:111], v[208:211], v[168:171], v[108:111]
	v_mfma_f32_16x16x32_bf16 v[100:103], v[200:203], v[176:179], v[100:103]
	v_mfma_f32_16x16x32_bf16 v[92:95], v[208:211], v[176:179], v[92:95]
	v_mfma_f32_16x16x32_bf16 v[84:87], v[200:203], v[184:187], v[84:87]
	v_mfma_f32_16x16x32_bf16 v[76:79], v[208:211], v[184:187], v[76:79]
	v_mfma_f32_16x16x32_bf16 v[68:71], v[200:203], v[192:195], v[68:71]
	v_mfma_f32_16x16x32_bf16 v[64:67], v[208:211], v[192:195], v[64:67]
	v_mfma_f32_16x16x32_bf16 v[116:119], v[204:207], v[172:175], v[116:119]
	v_mfma_f32_16x16x32_bf16 v[108:111], v[212:215], v[172:175], v[108:111]
	v_mfma_f32_16x16x32_bf16 v[100:103], v[204:207], v[180:183], v[100:103]
	v_mfma_f32_16x16x32_bf16 v[92:95], v[212:215], v[180:183], v[92:95]
	v_mfma_f32_16x16x32_bf16 v[84:87], v[204:207], v[188:191], v[84:87]
	v_mfma_f32_16x16x32_bf16 v[76:79], v[212:215], v[188:191], v[76:79]
	v_mfma_f32_16x16x32_bf16 v[68:71], v[204:207], v[196:199], v[68:71]
	v_mfma_f32_16x16x32_bf16 v[64:67], v[212:215], v[196:199], v[64:67]
	s_setprio 0
	s_mov_b32 m0, s49
	v_lshl_add_u64 v[140:141], v[216:217], 0, s[6:7]
	s_barrier
	ds_read_b128 v[168:171], v146 offset:49152
	ds_read_b128 v[172:175], v146 offset:50176
	ds_read_b128 v[176:179], v146 offset:51200
	ds_read_b128 v[180:183], v146 offset:52224
	ds_read_b128 v[184:187], v146 offset:53248
	ds_read_b128 v[188:191], v146 offset:54272
	ds_read_b128 v[192:195], v146 offset:55296
	ds_read_b128 v[196:199], v146 offset:56320
	global_load_lds_dwordx4 v[140:141], off
	v_lshl_add_u64 v[140:141], v[218:219], 0, s[6:7]
	s_mov_b32 m0, s56
	s_nop 0
	global_load_lds_dwordx4 v[140:141], off
	s_barrier
; #define PG8_STAGE(bufoff, gbase, voff) do { _Pragma("unroll") for (int _i = 0; _i < 2; ++_i) \
;         __builtin_amdgcn_global_load_lds((const unsigned*)((const char*)(gbase) + (voff)[_i]), (LAS unsigned*)(lds + (bufoff) + ldsw + _i * 8192), 16, 0, 0); } while (0)
; #define PG8_MMA(ai, bj, At, Bt) do { __builtin_amdgcn_s_setprio(1); _Pragma("unroll") for (int m = 0; m < 4; ++m) _Pragma("unroll") for (int n = 0; n < 2; ++n) _Pragma("unroll") for (int k = 0; k < 2; ++k) \
;         acc[ai][bj][m][n] = __builtin_amdgcn_mfma_f32_16x16x32_bf16(Bt[n][k], At[m][k], acc[ai][bj][m][n], 0, 0, 0); __builtin_amdgcn_s_setprio(0); } while (0)
; #define PG8_WAIT_V(n) asm volatile("s_waitcnt vmcnt(" #n ")" ::: "memory")
; #define PG8_WAIT_L(n) asm volatile("s_waitcnt lgkmcnt(" #n ")" ::: "memory")
; #define PG8_BAR __builtin_amdgcn_s_barrier()
; #define PG8_SCHED __builtin_amdgcn_sched_barrier(0)
; template <class Epi>
; __device__ __forceinline__ void gemm_phase(LAS unsigned char* lds, const Gemm g, const StaticOrder& S, const Epi& E) {
;     ...
;         for (int t = 0; t < nt; t += 2) {
;     ...
;             PG8_BAR; PG8_WAIT_L(0); PG8_MMA(1, 0, At, B0); PG8_BAR; PG8_SCHED;
;             PG8_STAGE(PG8_SB(1, 1), b3 + hstep, voffB);
;             PG8_WAIT_V(6); PG8_BAR; PG8_MMA(1, 1, At, B1); PG8_BAR;
	s_waitcnt lgkmcnt(0)
	s_setprio 1
	s_waitcnt lgkmcnt(0)
	v_mfma_f32_16x16x32_bf16 v[60:63], v[148:151], v[168:171], v[60:63]
	v_mfma_f32_16x16x32_bf16 v[56:59], v[160:163], v[168:171], v[56:59]
	v_mfma_f32_16x16x32_bf16 v[52:55], v[148:151], v[176:179], v[52:55]
	v_mfma_f32_16x16x32_bf16 v[44:47], v[160:163], v[176:179], v[44:47]
	v_mfma_f32_16x16x32_bf16 v[36:39], v[148:151], v[184:187], v[36:39]
	v_mfma_f32_16x16x32_bf16 v[28:31], v[160:163], v[184:187], v[28:31]
	v_mfma_f32_16x16x32_bf16 v[20:23], v[148:151], v[192:195], v[20:23]
	v_mfma_f32_16x16x32_bf16 v[12:15], v[160:163], v[192:195], v[12:15]
	v_mfma_f32_16x16x32_bf16 v[60:63], v[152:155], v[172:175], v[60:63]
	v_mfma_f32_16x16x32_bf16 v[56:59], v[164:167], v[172:175], v[56:59]
	v_mfma_f32_16x16x32_bf16 v[52:55], v[152:155], v[180:183], v[52:55]
	v_mfma_f32_16x16x32_bf16 v[44:47], v[164:167], v[180:183], v[44:47]
	v_mfma_f32_16x16x32_bf16 v[36:39], v[152:155], v[188:191], v[36:39]
	v_mfma_f32_16x16x32_bf16 v[28:31], v[164:167], v[188:191], v[28:31]
	v_mfma_f32_16x16x32_bf16 v[20:23], v[152:155], v[196:199], v[20:23]
	v_mfma_f32_16x16x32_bf16 v[12:15], v[164:167], v[196:199], v[12:15]
	s_setprio 0
	s_barrier
	s_add_u32 s52, s52, 0x80080
	s_addc_u32 s53, s53, 0
	s_add_i32 s54, s54, s23
	s_mov_b32 m0, s54
	s_nop 0
	global_load_lds_dwordx4 v132, s[52:53]
	s_add_i32 m0, s54, 0x2000
	s_nop 0
	global_load_lds_dwordx4 v128, s[52:53]
	s_waitcnt vmcnt(6)
	s_barrier
	s_setprio 1
	v_mfma_f32_16x16x32_bf16 v[48:51], v[200:203], v[168:171], v[48:51]
	v_mfma_f32_16x16x32_bf16 v[40:43], v[208:211], v[168:171], v[40:43]
	v_mfma_f32_16x16x32_bf16 v[32:35], v[200:203], v[176:179], v[32:35]
	v_mfma_f32_16x16x32_bf16 v[24:27], v[208:211], v[176:179], v[24:27]
	v_mfma_f32_16x16x32_bf16 v[16:19], v[200:203], v[184:187], v[16:19]
	v_mfma_f32_16x16x32_bf16 v[8:11], v[208:211], v[184:187], v[8:11]
	v_mfma_f32_16x16x32_bf16 v[4:7], v[200:203], v[192:195], v[4:7]
	v_mfma_f32_16x16x32_bf16 v[0:3], v[208:211], v[192:195], v[0:3]
	v_mfma_f32_16x16x32_bf16 v[48:51], v[204:207], v[172:175], v[48:51]
	v_mfma_f32_16x16x32_bf16 v[40:43], v[212:215], v[172:175], v[40:43]
	v_mfma_f32_16x16x32_bf16 v[32:35], v[204:207], v[180:183], v[32:35]
	v_mfma_f32_16x16x32_bf16 v[24:27], v[212:215], v[180:183], v[24:27]
	v_mfma_f32_16x16x32_bf16 v[16:19], v[204:207], v[188:191], v[16:19]
	v_mfma_f32_16x16x32_bf16 v[8:11], v[212:215], v[188:191], v[8:11]
	v_mfma_f32_16x16x32_bf16 v[4:7], v[204:207], v[196:199], v[4:7]
	v_mfma_f32_16x16x32_bf16 v[0:3], v[212:215], v[196:199], v[0:3]
	s_setprio 0
	s_add_i32 s69, s69, 2
	s_add_u32 s50, s50, 0x100
	s_addc_u32 s51, s51, 0
	s_add_u32 s67, s67, 0x100
	s_addc_u32 s68, s68, 0
	s_cmp_gt_u32 s69, 29
	s_barrier
	s_cbranch_scc0 .LBB0_673
; #define PG8_WAIT_V(n) asm volatile("s_waitcnt vmcnt(" #n ")" ::: "memory")
; #define PG8_BAR __builtin_amdgcn_s_barrier()
; __device__ __forceinline__ u32x4 pack8(f32x4 v0, f32x4 v1) { u32x4 w; w.x = cvt_pk_bf16(v0[0], v0[1]); w.y = cvt_pk_bf16(v0[2], v0[3]); w.z = cvt_pk_bf16(v1[0], v1[1]); w.w = cvt_pk_bf16(v1[2], v1[3]); return w; }
; template <class Epi>
; __device__ __forceinline__ void gemm_phase(LAS unsigned char* lds, const Gemm g, const StaticOrder& S, const Epi& E) {
;     ...
;         if (!has_next) break;
; #pragma unroll
;         for (int a = 0; a < 2; ++a)
; #pragma unroll
;             for (int b = 0; b < 2; ++b)
; #pragma unroll
;                 for (int m = 0; m < 4; ++m)
; #pragma unroll
;                     for (int n = 0; n < 2; ++n) acc[a][b][m][n] = (f32x4){0.f, 0.f, 0.f, 0.f};
;         cur = nxt; cA = nA; cB = nB; ++ui;
;     }
;     PG8_WAIT_V(0);
;     if (wr == 0) PG8_BAR;
;     __device__ __forceinline__ void operator()(const f32x4 (&acc)[2][2][4][2], const Unit& u, int wr, int wc, int fr, int fq) const {
;         const int row0 = u.pm * BM + wr * 64 + fr, col0 = u.pn * BM + wc * 32 + 8 * fq;
; #pragma unroll
;         for (int ai = 0; ai < 2; ++ai)
; #pragma unroll
;             for (int m = 0; m < 4; ++m) { bf16_t* rowp = O + (size_t)(row0 + ai * HALF + m * 16) * ldc + col0;
; #pragma unroll
;                 for (int bj = 0; bj < 2; ++bj) *(u32x4*)(rowp + bj * HALF) = pack8(acc[ai][bj][m][0], acc[ai][bj][m][1]); }
	v_lshl_add_u32 v148, s48, 8, v142
	v_lshl_or_b32 v140, s64, 8, v144
	v_ashrrev_i32_e32 v149, 31, v148
	v_ashrrev_i32_e32 v141, 31, v140
	v_lshlrev_b64 v[150:151], 12, v[148:149]
	v_lshl_add_u64 v[150:151], s[24:25], 0, v[150:151]
	v_lshlrev_b64 v[152:153], 1, v[140:141]
	v_lshl_add_u64 v[140:141], v[150:151], 0, v[152:153]
	v_cvt_pk_bf16_f32 v124, v124, v125
	v_cvt_pk_bf16_f32 v125, v126, v127
	v_cvt_pk_bf16_f32 v126, v120, v121
	v_cvt_pk_bf16_f32 v127, v122, v123
	global_store_dwordx4 v[140:141], v[124:127], off
	v_cvt_pk_bf16_f32 v116, v116, v117
	v_cvt_pk_bf16_f32 v117, v118, v119
	v_cvt_pk_bf16_f32 v118, v108, v109
	v_or_b32_e32 v108, 16, v148
	v_ashrrev_i32_e32 v109, 31, v108
	v_lshlrev_b64 v[108:109], 12, v[108:109]
	v_lshl_add_u64 v[108:109], s[24:25], 0, v[108:109]
	v_cvt_pk_bf16_f32 v119, v110, v111
	global_store_dwordx4 v[140:141], v[116:119], off offset:256
	s_mov_b32 s64, s40
	s_mov_b32 s48, s42
	v_lshl_add_u64 v[116:117], v[108:109], 0, v[152:153]
	v_cvt_pk_bf16_f32 v108, v112, v113
	v_cvt_pk_bf16_f32 v109, v114, v115
	v_cvt_pk_bf16_f32 v110, v104, v105
	v_cvt_pk_bf16_f32 v111, v106, v107
	global_store_dwordx4 v[116:117], v[108:111], off
	v_cvt_pk_bf16_f32 v100, v100, v101
	v_cvt_pk_bf16_f32 v101, v102, v103
	v_cvt_pk_bf16_f32 v102, v92, v93
	v_or_b32_e32 v92, 32, v148
	v_ashrrev_i32_e32 v93, 31, v92
	v_lshlrev_b64 v[92:93], 12, v[92:93]
	v_lshl_add_u64 v[92:93], s[24:25], 0, v[92:93]
	v_cvt_pk_bf16_f32 v103, v94, v95
	global_store_dwordx4 v[116:117], v[100:103], off offset:256
	s_mov_b64 s[52:53], s[46:47]
	s_mov_b64 s[50:51], s[44:45]
	v_lshl_add_u64 v[100:101], v[92:93], 0, v[152:153]
	v_cvt_pk_bf16_f32 v92, v96, v97
	v_cvt_pk_bf16_f32 v93, v98, v99
	v_cvt_pk_bf16_f32 v94, v88, v89
	v_cvt_pk_bf16_f32 v95, v90, v91
	global_store_dwordx4 v[100:101], v[92:95], off
	v_cvt_pk_bf16_f32 v84, v84, v85
	v_cvt_pk_bf16_f32 v85, v86, v87
	v_cvt_pk_bf16_f32 v86, v76, v77
	v_or_b32_e32 v76, 48, v148
	v_ashrrev_i32_e32 v77, 31, v76
	v_lshlrev_b64 v[76:77], 12, v[76:77]
	v_lshl_add_u64 v[76:77], s[24:25], 0, v[76:77]
	v_cvt_pk_bf16_f32 v87, v78, v79
	global_store_dwordx4 v[100:101], v[84:87], off offset:256
	s_nop 1
	v_lshl_add_u64 v[84:85], v[76:77], 0, v[152:153]
	v_cvt_pk_bf16_f32 v76, v80, v81
	v_cvt_pk_bf16_f32 v77, v82, v83
	v_cvt_pk_bf16_f32 v78, v72, v73
	v_cvt_pk_bf16_f32 v79, v74, v75
	global_store_dwordx4 v[84:85], v[76:79], off
	v_cvt_pk_bf16_f32 v68, v68, v69
	v_cvt_pk_bf16_f32 v69, v70, v71
	v_cvt_pk_bf16_f32 v70, v64, v65
	v_cvt_pk_bf16_f32 v71, v66, v67
	global_store_dwordx4 v[84:85], v[68:71], off offset:256
	v_cvt_pk_bf16_f32 v60, v60, v61
	v_cvt_pk_bf16_f32 v61, v62, v63
	v_cvt_pk_bf16_f32 v62, v56, v57
	v_add_co_u32_e32 v56, vcc, s60, v140
	v_lshl_add_u64 v[64:65], v[140:141], 0, s[2:3]
	s_nop 0
	v_addc_co_u32_e32 v57, vcc, 0, v141, vcc
	v_cvt_pk_bf16_f32 v63, v58, v59
	global_store_dwordx4 v[56:57], v[60:63], off
	v_cvt_pk_bf16_f32 v48, v48, v49
	v_cvt_pk_bf16_f32 v49, v50, v51
	v_cvt_pk_bf16_f32 v50, v40, v41
	v_cvt_pk_bf16_f32 v51, v42, v43
	global_store_dwordx4 v[64:65], v[48:51], off offset:256
	v_cvt_pk_bf16_f32 v40, v52, v53
	v_cvt_pk_bf16_f32 v41, v54, v55
	v_cvt_pk_bf16_f32 v42, v44, v45
	v_add_co_u32_e32 v44, vcc, s61, v140
	s_nop 0
	v_lshl_add_u64 v[48:49], v[140:141], 0, s[8:9]
	v_addc_co_u32_e32 v45, vcc, 0, v141, vcc
	v_cvt_pk_bf16_f32 v43, v46, v47
	global_store_dwordx4 v[44:45], v[40:43], off
	v_cvt_pk_bf16_f32 v32, v32, v33
	v_cvt_pk_bf16_f32 v33, v34, v35
	v_cvt_pk_bf16_f32 v34, v24, v25
	v_cvt_pk_bf16_f32 v35, v26, v27
	global_store_dwordx4 v[48:49], v[32:35], off offset:256
	v_cvt_pk_bf16_f32 v24, v36, v37
	v_cvt_pk_bf16_f32 v25, v38, v39
	v_cvt_pk_bf16_f32 v26, v28, v29
	v_add_co_u32_e32 v28, vcc, s62, v140
	s_nop 0
	v_lshl_add_u64 v[32:33], v[140:141], 0, s[30:31]
	v_addc_co_u32_e32 v29, vcc, 0, v141, vcc
	v_cvt_pk_bf16_f32 v27, v30, v31
	global_store_dwordx4 v[28:29], v[24:27], off
	v_cvt_pk_bf16_f32 v16, v16, v17
	v_cvt_pk_bf16_f32 v17, v18, v19
	v_cvt_pk_bf16_f32 v18, v8, v9
	v_cvt_pk_bf16_f32 v19, v10, v11
	global_store_dwordx4 v[32:33], v[16:19], off offset:256
	v_cvt_pk_bf16_f32 v8, v20, v21
	v_cvt_pk_bf16_f32 v9, v22, v23
	v_cvt_pk_bf16_f32 v10, v12, v13
	v_add_co_u32_e32 v12, vcc, s63, v140
	s_nop 0
	v_lshl_add_u64 v[16:17], v[140:141], 0, s[34:35]
	v_addc_co_u32_e32 v13, vcc, 0, v141, vcc
	s_and_b64 vcc, exec, s[38:39]
	v_cvt_pk_bf16_f32 v11, v14, v15
	global_store_dwordx4 v[12:13], v[8:11], off
	v_cvt_pk_bf16_f32 v4, v4, v5
	v_cvt_pk_bf16_f32 v5, v6, v7
	v_cvt_pk_bf16_f32 v6, v0, v1
	v_cvt_pk_bf16_f32 v7, v2, v3
	global_store_dwordx4 v[16:17], v[4:7], off offset:256
	s_cbranch_vccz .LBB0_670
	s_waitcnt vmcnt(0)
	s_cmpk_gt_u32 s10, 0xff
	v_readlane_b32 s62, v232, 20
	v_readlane_b32 s61, v232, 21
	s_cbranch_scc1 .LBB0_677
	s_barrier

; #define PG8_STAGE(bufoff, gbase, voff) do { _Pragma("unroll") for (int _i = 0; _i < 2; ++_i) \
;         __builtin_amdgcn_global_load_lds((const unsigned*)((const char*)(gbase) + (voff)[_i]), (LAS unsigned*)(lds + (bufoff) + ldsw + _i * 8192), 16, 0, 0); } while (0)
; #define PG8_LDA(dst, b, h) do { _Pragma("unroll") for (int m = 0; m < 4; ++m) _Pragma("unroll") for (int k = 0; k < 2; ++k) dst[m][k] = *(const LAS bf16x8*)(lds + PG8_SA(b, h) + aoff + m * 2048 + k * 1024); } while (0)
; #define PG8_LDB(dst, b, h) do { _Pragma("unroll") for (int n = 0; n < 2; ++n) _Pragma("unroll") for (int k = 0; k < 2; ++k) dst[n][k] = *(const LAS bf16x8*)(lds + PG8_SB(b, h) + boff + n * 2048 + k * 1024); } while (0)
; #define PG8_MMA(ai, bj, At, Bt) do { __builtin_amdgcn_s_setprio(1); _Pragma("unroll") for (int m = 0; m < 4; ++m) _Pragma("unroll") for (int n = 0; n < 2; ++n) _Pragma("unroll") for (int k = 0; k < 2; ++k) \
;         acc[ai][bj][m][n] = __builtin_amdgcn_mfma_f32_16x16x32_bf16(Bt[n][k], At[m][k], acc[ai][bj][m][n], 0, 0, 0); __builtin_amdgcn_s_setprio(0); } while (0)
; #define PG8_WAIT_V(n) asm volatile("s_waitcnt vmcnt(" #n ")" ::: "memory")
; #define PG8_WAIT_L(n) asm volatile("s_waitcnt lgkmcnt(" #n ")" ::: "memory")
; #define PG8_BAR __builtin_amdgcn_s_barrier()
; #define PG8_SCHED __builtin_amdgcn_sched_barrier(0)
; template <class Epi>
; __device__ __forceinline__ void gemm_phase(LAS unsigned char* lds, const Gemm g, const StaticOrder& S, const Epi& E) {
;     ...
;             PG8_LDB(B0, 0, 0); PG8_SCHED; PG8_LDA(At, 0, 0); PG8_STAGE(PG8_SA(1, 1), a1 + hstep, voffA);
;             PG8_WAIT_L(8); PG8_BAR; PG8_WAIT_L(0); PG8_MMA(0, 0, At, B0); PG8_BAR; PG8_SCHED;
;             PG8_LDB(B1, 0, 1); PG8_STAGE(PG8_SB(0, 0), b2, voffB);
;             PG8_BAR; PG8_WAIT_L(0); PG8_MMA(0, 1, At, B1); PG8_BAR;
;             PG8_LDA(At, 0, 1); PG8_STAGE(PG8_SA(0, 0), a2, voffA);
;             PG8_BAR; PG8_WAIT_L(0); PG8_MMA(1, 0, At, B0); PG8_BAR; PG8_SCHED;
;             PG8_STAGE(PG8_SB(0, 1), b2 + hstep, voffB);
;             PG8_WAIT_V(6); PG8_BAR; PG8_MMA(1, 1, At, B1); PG8_BAR;
.LBB0_796:
	ds_read_b128 v[144:147], v155
	ds_read_b128 v[148:151], v155 offset:1024
	ds_read_b128 v[160:163], v155 offset:2048
	ds_read_b128 v[164:167], v155 offset:3072
	s_add_u32 s42, s40, 0xfff80080
	s_addc_u32 s43, s41, -1
	s_cmp_eq_u32 s58, 28
	s_cselect_b32 s45, s31, s43
	s_cselect_b32 s44, s54, s42
	s_cselect_b32 s43, s9, s57
	s_cselect_b32 s42, s55, s56
	s_add_i32 m0, s27, 0xc000
	ds_read_b128 v[168:171], v156
	ds_read_b128 v[172:175], v156 offset:1024
	ds_read_b128 v[176:179], v156 offset:2048
	ds_read_b128 v[180:183], v156 offset:3072
	ds_read_b128 v[184:187], v156 offset:4096
	ds_read_b128 v[188:191], v156 offset:5120
	ds_read_b128 v[192:195], v156 offset:6144
	ds_read_b128 v[196:199], v156 offset:7168
	global_load_lds_dwordx4 v136, s[40:41]
	s_add_i32 m0, s27, 0xe000
	s_nop 0
	global_load_lds_dwordx4 v138, s[40:41]
	s_waitcnt lgkmcnt(8)
	s_barrier
	s_waitcnt lgkmcnt(0)
	s_setprio 1
	s_waitcnt lgkmcnt(0)
	v_mfma_f32_16x16x32_bf16 v[124:127], v[144:147], v[168:171], v[124:127]
	v_mfma_f32_16x16x32_bf16 v[120:123], v[160:163], v[168:171], v[120:123]
	v_mfma_f32_16x16x32_bf16 v[108:111], v[144:147], v[176:179], v[108:111]
	v_mfma_f32_16x16x32_bf16 v[104:107], v[160:163], v[176:179], v[104:107]
	v_mfma_f32_16x16x32_bf16 v[92:95], v[144:147], v[184:187], v[92:95]
	v_mfma_f32_16x16x32_bf16 v[88:91], v[160:163], v[184:187], v[88:91]
	v_mfma_f32_16x16x32_bf16 v[76:79], v[144:147], v[192:195], v[76:79]
	v_mfma_f32_16x16x32_bf16 v[72:75], v[160:163], v[192:195], v[72:75]
	v_mfma_f32_16x16x32_bf16 v[124:127], v[148:151], v[172:175], v[124:127]
	v_mfma_f32_16x16x32_bf16 v[120:123], v[164:167], v[172:175], v[120:123]
	v_mfma_f32_16x16x32_bf16 v[108:111], v[148:151], v[180:183], v[108:111]
	v_mfma_f32_16x16x32_bf16 v[104:107], v[164:167], v[180:183], v[104:107]
	v_mfma_f32_16x16x32_bf16 v[92:95], v[148:151], v[188:191], v[92:95]
	v_mfma_f32_16x16x32_bf16 v[88:91], v[164:167], v[188:191], v[88:91]
	v_mfma_f32_16x16x32_bf16 v[76:79], v[148:151], v[196:199], v[76:79]
	v_mfma_f32_16x16x32_bf16 v[72:75], v[164:167], v[196:199], v[72:75]
	s_setprio 0
	s_barrier
	s_add_i32 s59, s50, s23
	v_lshl_add_u64 v[216:217], s[42:43], 0, v[132:133]
	s_mov_b32 m0, s59
	ds_read_b128 v[200:203], v157
	ds_read_b128 v[204:207], v157 offset:1024
	ds_read_b128 v[208:211], v157 offset:2048
	ds_read_b128 v[212:215], v157 offset:3072
	global_load_lds_dwordx4 v132, s[42:43]
	v_lshl_add_u64 v[218:219], s[42:43], 0, v[128:129]
	s_add_i32 m0, s59, 0x2000
	s_nop 0
	global_load_lds_dwordx4 v128, s[42:43]
	s_barrier
	s_waitcnt lgkmcnt(0)
	s_setprio 1
	s_waitcnt lgkmcnt(0)
	v_mfma_f32_16x16x32_bf16 v[116:119], v[200:203], v[168:171], v[116:119]
	v_mfma_f32_16x16x32_bf16 v[112:115], v[208:211], v[168:171], v[112:115]
	v_mfma_f32_16x16x32_bf16 v[100:103], v[200:203], v[176:179], v[100:103]
	v_mfma_f32_16x16x32_bf16 v[96:99], v[208:211], v[176:179], v[96:99]
	v_mfma_f32_16x16x32_bf16 v[84:87], v[200:203], v[184:187], v[84:87]
	v_mfma_f32_16x16x32_bf16 v[80:83], v[208:211], v[184:187], v[80:83]
	v_mfma_f32_16x16x32_bf16 v[68:71], v[200:203], v[192:195], v[68:71]
	v_mfma_f32_16x16x32_bf16 v[64:67], v[208:211], v[192:195], v[64:67]
	v_mfma_f32_16x16x32_bf16 v[116:119], v[204:207], v[172:175], v[116:119]
	v_mfma_f32_16x16x32_bf16 v[112:115], v[212:215], v[172:175], v[112:115]
	v_mfma_f32_16x16x32_bf16 v[100:103], v[204:207], v[180:183], v[100:103]
	v_mfma_f32_16x16x32_bf16 v[96:99], v[212:215], v[180:183], v[96:99]
	v_mfma_f32_16x16x32_bf16 v[84:87], v[204:207], v[188:191], v[84:87]
	v_mfma_f32_16x16x32_bf16 v[80:83], v[212:215], v[188:191], v[80:83]
	v_mfma_f32_16x16x32_bf16 v[68:71], v[204:207], v[196:199], v[68:71]
	v_mfma_f32_16x16x32_bf16 v[64:67], v[212:215], v[196:199], v[64:67]
	s_setprio 0
	s_mov_b32 m0, s27
	v_lshl_add_u64 v[220:221], s[44:45], 0, v[134:135]
	s_barrier
	ds_read_b128 v[168:171], v156 offset:16384
	ds_read_b128 v[172:175], v156 offset:17408
	ds_read_b128 v[176:179], v156 offset:18432
	ds_read_b128 v[180:183], v156 offset:19456
	ds_read_b128 v[184:187], v156 offset:20480
	ds_read_b128 v[188:191], v156 offset:21504
	ds_read_b128 v[192:195], v156 offset:22528
	ds_read_b128 v[196:199], v156 offset:23552
	global_load_lds_dwordx4 v134, s[44:45]
	v_lshl_add_u64 v[222:223], s[44:45], 0, v[130:131]
	s_mov_b32 m0, s28
	s_nop 0
	global_load_lds_dwordx4 v130, s[44:45]
	s_barrier
	s_waitcnt lgkmcnt(0)
	s_setprio 1
	s_waitcnt lgkmcnt(0)
	v_mfma_f32_16x16x32_bf16 v[60:63], v[144:147], v[168:171], v[60:63]
	v_mfma_f32_16x16x32_bf16 v[56:59], v[160:163], v[168:171], v[56:59]
	v_mfma_f32_16x16x32_bf16 v[44:47], v[144:147], v[176:179], v[44:47]
	v_mfma_f32_16x16x32_bf16 v[40:43], v[160:163], v[176:179], v[40:43]
	v_mfma_f32_16x16x32_bf16 v[28:31], v[144:147], v[184:187], v[28:31]
	v_mfma_f32_16x16x32_bf16 v[24:27], v[160:163], v[184:187], v[24:27]
	v_mfma_f32_16x16x32_bf16 v[12:15], v[144:147], v[192:195], v[12:15]
	v_mfma_f32_16x16x32_bf16 v[8:11], v[160:163], v[192:195], v[8:11]
	v_mfma_f32_16x16x32_bf16 v[60:63], v[148:151], v[172:175], v[60:63]
	v_mfma_f32_16x16x32_bf16 v[56:59], v[164:167], v[172:175], v[56:59]
	v_mfma_f32_16x16x32_bf16 v[44:47], v[148:151], v[180:183], v[44:47]
	v_mfma_f32_16x16x32_bf16 v[40:43], v[164:167], v[180:183], v[40:43]
	v_mfma_f32_16x16x32_bf16 v[28:31], v[148:151], v[188:191], v[28:31]
	v_mfma_f32_16x16x32_bf16 v[24:27], v[164:167], v[188:191], v[24:27]
	v_mfma_f32_16x16x32_bf16 v[12:15], v[148:151], v[196:199], v[12:15]
	v_mfma_f32_16x16x32_bf16 v[8:11], v[164:167], v[196:199], v[8:11]
	s_setprio 0
	s_barrier
	s_add_u32 s60, s42, 0x80000
	s_addc_u32 s61, s43, 0
	s_add_i32 s59, s51, s23
	s_mov_b32 m0, s59
	s_nop 0
	global_load_lds_dwordx4 v132, s[60:61]
	s_add_i32 m0, s59, 0x2000
	s_nop 0
	global_load_lds_dwordx4 v128, s[60:61]
	s_waitcnt vmcnt(6)
	s_barrier
; #define PG8_STAGE(bufoff, gbase, voff) do { _Pragma("unroll") for (int _i = 0; _i < 2; ++_i) \
;         __builtin_amdgcn_global_load_lds((const unsigned*)((const char*)(gbase) + (voff)[_i]), (LAS unsigned*)(lds + (bufoff) + ldsw + _i * 8192), 16, 0, 0); } while (0)
; #define PG8_LDA(dst, b, h) do { _Pragma("unroll") for (int m = 0; m < 4; ++m) _Pragma("unroll") for (int k = 0; k < 2; ++k) dst[m][k] = *(const LAS bf16x8*)(lds + PG8_SA(b, h) + aoff + m * 2048 + k * 1024); } while (0)
; #define PG8_LDB(dst, b, h) do { _Pragma("unroll") for (int n = 0; n < 2; ++n) _Pragma("unroll") for (int k = 0; k < 2; ++k) dst[n][k] = *(const LAS bf16x8*)(lds + PG8_SB(b, h) + boff + n * 2048 + k * 1024); } while (0)
; #define PG8_MMA(ai, bj, At, Bt) do { __builtin_amdgcn_s_setprio(1); _Pragma("unroll") for (int m = 0; m < 4; ++m) _Pragma("unroll") for (int n = 0; n < 2; ++n) _Pragma("unroll") for (int k = 0; k < 2; ++k) \
;         acc[ai][bj][m][n] = __builtin_amdgcn_mfma_f32_16x16x32_bf16(Bt[n][k], At[m][k], acc[ai][bj][m][n], 0, 0, 0); __builtin_amdgcn_s_setprio(0); } while (0)
; #define PG8_WAIT_V(n) asm volatile("s_waitcnt vmcnt(" #n ")" ::: "memory")
; #define PG8_WAIT_L(n) asm volatile("s_waitcnt lgkmcnt(" #n ")" ::: "memory")
; #define PG8_BAR __builtin_amdgcn_s_barrier()
; #define PG8_SCHED __builtin_amdgcn_sched_barrier(0)
; template <class Epi>
; __device__ __forceinline__ void gemm_phase(LAS unsigned char* lds, const Gemm g, const StaticOrder& S, const Epi& E) {
;     ...
;             PG8_WAIT_V(6); PG8_BAR; PG8_MMA(1, 1, At, B1); PG8_BAR;
;             PG8_LDB(B0, 1, 0); PG8_SCHED; PG8_LDA(At, 1, 0); PG8_STAGE(PG8_SA(0, 1), a2 + hstep, voffA);
;             PG8_WAIT_L(8); PG8_BAR; PG8_WAIT_L(0); PG8_MMA(0, 0, At, B0); PG8_BAR; PG8_SCHED;
;             PG8_LDB(B1, 1, 1); PG8_STAGE(PG8_SB(1, 0), b3, voffB);
;             PG8_BAR; PG8_WAIT_L(0); PG8_MMA(0, 1, At, B1); PG8_BAR;
;             PG8_LDA(At, 1, 1); PG8_STAGE(PG8_SA(1, 0), a3, voffA);
	s_setprio 1
	v_mfma_f32_16x16x32_bf16 v[52:55], v[200:203], v[168:171], v[52:55]
	v_mfma_f32_16x16x32_bf16 v[48:51], v[208:211], v[168:171], v[48:51]
	v_mfma_f32_16x16x32_bf16 v[36:39], v[200:203], v[176:179], v[36:39]
	v_mfma_f32_16x16x32_bf16 v[32:35], v[208:211], v[176:179], v[32:35]
	v_mfma_f32_16x16x32_bf16 v[20:23], v[200:203], v[184:187], v[20:23]
	v_mfma_f32_16x16x32_bf16 v[16:19], v[208:211], v[184:187], v[16:19]
	v_mfma_f32_16x16x32_bf16 v[4:7], v[200:203], v[192:195], v[4:7]
	v_mfma_f32_16x16x32_bf16 v[0:3], v[208:211], v[192:195], v[0:3]
	v_mfma_f32_16x16x32_bf16 v[52:55], v[204:207], v[172:175], v[52:55]
	v_mfma_f32_16x16x32_bf16 v[48:51], v[212:215], v[172:175], v[48:51]
	v_mfma_f32_16x16x32_bf16 v[36:39], v[204:207], v[180:183], v[36:39]
	v_mfma_f32_16x16x32_bf16 v[32:35], v[212:215], v[180:183], v[32:35]
	v_mfma_f32_16x16x32_bf16 v[20:23], v[204:207], v[188:191], v[20:23]
	v_mfma_f32_16x16x32_bf16 v[16:19], v[212:215], v[188:191], v[16:19]
	v_mfma_f32_16x16x32_bf16 v[4:7], v[204:207], v[196:199], v[4:7]
	v_mfma_f32_16x16x32_bf16 v[0:3], v[212:215], v[196:199], v[0:3]
	s_setprio 0
	s_add_i32 s59, 0, 0x18000
	v_add_u32_e32 v164, s59, v153
	s_barrier
	ds_read_b128 v[144:147], v164
	ds_read_b128 v[148:151], v164 offset:1024
	ds_read_b128 v[160:163], v164 offset:2048
	ds_read_b128 v[164:167], v164 offset:3072
	s_add_u32 s44, s44, 0x80000
	s_addc_u32 s45, s45, 0
	s_mov_b32 m0, s29
	ds_read_b128 v[168:171], v156 offset:32768
	ds_read_b128 v[172:175], v156 offset:33792
	ds_read_b128 v[176:179], v156 offset:34816
	ds_read_b128 v[180:183], v156 offset:35840
	ds_read_b128 v[184:187], v156 offset:36864
	ds_read_b128 v[188:191], v156 offset:37888
	ds_read_b128 v[192:195], v156 offset:38912
	ds_read_b128 v[196:199], v156 offset:39936
	global_load_lds_dwordx4 v134, s[44:45]
	s_mov_b32 m0, s33
	s_nop 0
	global_load_lds_dwordx4 v130, s[44:45]
	s_waitcnt lgkmcnt(8)
	s_barrier
	s_waitcnt lgkmcnt(0)
	s_setprio 1
	s_waitcnt lgkmcnt(0)
	v_mfma_f32_16x16x32_bf16 v[124:127], v[144:147], v[168:171], v[124:127]
	v_mfma_f32_16x16x32_bf16 v[120:123], v[160:163], v[168:171], v[120:123]
	v_mfma_f32_16x16x32_bf16 v[108:111], v[144:147], v[176:179], v[108:111]
	v_mfma_f32_16x16x32_bf16 v[104:107], v[160:163], v[176:179], v[104:107]
	v_mfma_f32_16x16x32_bf16 v[92:95], v[144:147], v[184:187], v[92:95]
	v_mfma_f32_16x16x32_bf16 v[88:91], v[160:163], v[184:187], v[88:91]
	v_mfma_f32_16x16x32_bf16 v[76:79], v[144:147], v[192:195], v[76:79]
	v_mfma_f32_16x16x32_bf16 v[72:75], v[160:163], v[192:195], v[72:75]
	v_mfma_f32_16x16x32_bf16 v[124:127], v[148:151], v[172:175], v[124:127]
	v_mfma_f32_16x16x32_bf16 v[120:123], v[164:167], v[172:175], v[120:123]
	v_mfma_f32_16x16x32_bf16 v[108:111], v[148:151], v[180:183], v[108:111]
	v_mfma_f32_16x16x32_bf16 v[104:107], v[164:167], v[180:183], v[104:107]
	v_mfma_f32_16x16x32_bf16 v[92:95], v[148:151], v[188:191], v[92:95]
	v_mfma_f32_16x16x32_bf16 v[88:91], v[164:167], v[188:191], v[88:91]
	v_mfma_f32_16x16x32_bf16 v[76:79], v[148:151], v[196:199], v[76:79]
	v_mfma_f32_16x16x32_bf16 v[72:75], v[164:167], v[196:199], v[72:75]
	s_setprio 0
	s_barrier
	s_add_i32 s44, 0, 0x1c000
	s_add_i32 s45, s59, s23
	v_add_u32_e32 v212, s44, v153
	v_lshl_add_u64 v[216:217], v[216:217], 0, s[2:3]
	s_mov_b32 m0, s45
	ds_read_b128 v[200:203], v212
	ds_read_b128 v[204:207], v212 offset:1024
	ds_read_b128 v[208:211], v212 offset:2048
	ds_read_b128 v[212:215], v212 offset:3072
	global_load_lds_dwordx4 v[216:217], off
	v_lshl_add_u64 v[216:217], v[218:219], 0, s[2:3]
	s_add_i32 m0, s45, 0x2000
	s_nop 0
	global_load_lds_dwordx4 v[216:217], off
	s_barrier
	s_waitcnt lgkmcnt(0)
	s_setprio 1
	s_waitcnt lgkmcnt(0)
	v_mfma_f32_16x16x32_bf16 v[116:119], v[200:203], v[168:171], v[116:119]
	v_mfma_f32_16x16x32_bf16 v[112:115], v[208:211], v[168:171], v[112:115]
	v_mfma_f32_16x16x32_bf16 v[100:103], v[200:203], v[176:179], v[100:103]
	v_mfma_f32_16x16x32_bf16 v[96:99], v[208:211], v[176:179], v[96:99]
	v_mfma_f32_16x16x32_bf16 v[84:87], v[200:203], v[184:187], v[84:87]
	v_mfma_f32_16x16x32_bf16 v[80:83], v[208:211], v[184:187], v[80:83]
	v_mfma_f32_16x16x32_bf16 v[68:71], v[200:203], v[192:195], v[68:71]
	v_mfma_f32_16x16x32_bf16 v[64:67], v[208:211], v[192:195], v[64:67]
	v_mfma_f32_16x16x32_bf16 v[116:119], v[204:207], v[172:175], v[116:119]
	v_mfma_f32_16x16x32_bf16 v[112:115], v[212:215], v[172:175], v[112:115]
	v_mfma_f32_16x16x32_bf16 v[100:103], v[204:207], v[180:183], v[100:103]
	v_mfma_f32_16x16x32_bf16 v[96:99], v[212:215], v[180:183], v[96:99]
	v_mfma_f32_16x16x32_bf16 v[84:87], v[204:207], v[188:191], v[84:87]
	v_mfma_f32_16x16x32_bf16 v[80:83], v[212:215], v[188:191], v[80:83]
	v_mfma_f32_16x16x32_bf16 v[68:71], v[204:207], v[196:199], v[68:71]
	v_mfma_f32_16x16x32_bf16 v[64:67], v[212:215], v[196:199], v[64:67]
	s_setprio 0
	s_mov_b32 m0, s46
	v_lshl_add_u64 v[216:217], v[220:221], 0, s[2:3]
	s_barrier
	ds_read_b128 v[168:171], v156 offset:49152
	ds_read_b128 v[172:175], v156 offset:50176
	ds_read_b128 v[176:179], v156 offset:51200
	ds_read_b128 v[180:183], v156 offset:52224
	ds_read_b128 v[184:187], v156 offset:53248
	ds_read_b128 v[188:191], v156 offset:54272
	ds_read_b128 v[192:195], v156 offset:55296
	ds_read_b128 v[196:199], v156 offset:56320
	global_load_lds_dwordx4 v[216:217], off
	v_lshl_add_u64 v[216:217], v[222:223], 0, s[2:3]
	s_mov_b32 m0, s47
	s_nop 0
	global_load_lds_dwordx4 v[216:217], off
	s_barrier
; __device__ __forceinline__ float fast_rcp(float x) { return __builtin_amdgcn_rcpf(x); }
; __device__ __forceinline__ float fast_exp2(float x) { return __builtin_amdgcn_exp2f(x); }
; #define PG8_STAGE(bufoff, gbase, voff) do { _Pragma("unroll") for (int _i = 0; _i < 2; ++_i) \
;         __builtin_amdgcn_global_load_lds((const unsigned*)((const char*)(gbase) + (voff)[_i]), (LAS unsigned*)(lds + (bufoff) + ldsw + _i * 8192), 16, 0, 0); } while (0)
; #define PG8_MMA(ai, bj, At, Bt) do { __builtin_amdgcn_s_setprio(1); _Pragma("unroll") for (int m = 0; m < 4; ++m) _Pragma("unroll") for (int n = 0; n < 2; ++n) _Pragma("unroll") for (int k = 0; k < 2; ++k) \
;         acc[ai][bj][m][n] = __builtin_amdgcn_mfma_f32_16x16x32_bf16(Bt[n][k], At[m][k], acc[ai][bj][m][n], 0, 0, 0); __builtin_amdgcn_s_setprio(0); } while (0)
; #define PG8_WAIT_V(n) asm volatile("s_waitcnt vmcnt(" #n ")" ::: "memory")
; #define PG8_WAIT_L(n) asm volatile("s_waitcnt lgkmcnt(" #n ")" ::: "memory")
; #define PG8_BAR __builtin_amdgcn_s_barrier()
; #define PG8_SCHED __builtin_amdgcn_sched_barrier(0)
; template <class Epi>
; __device__ __forceinline__ void gemm_phase(LAS unsigned char* lds, const Gemm g, const StaticOrder& S, const Epi& E) {
;     ...
;             PG8_BAR; PG8_WAIT_L(0); PG8_MMA(1, 0, At, B0); PG8_BAR; PG8_SCHED;
;             PG8_STAGE(PG8_SB(1, 1), b3 + hstep, voffB);
;             PG8_WAIT_V(6); PG8_BAR; PG8_MMA(1, 1, At, B1); PG8_BAR;
;     __device__ __forceinline__ void operator()(const f32x4 (&acc)[2][2][4][2], const Unit& u, int wr, int wc, int fr, int fq) const {
;         const int row0 = u.pm * BM + wr * 64 + fr, col0 = u.pn * HALF + wc * 32 + 8 * fq;
; #pragma unroll
;         for (int ai = 0; ai < 2; ++ai)
; #pragma unroll
;             for (int m = 0; m < 4; ++m) { bf16_t* rowp = O + (size_t)(row0 + ai * HALF + m * 16) * DFF + col0;
;                 const float r = rs[row0 + ai * HALF + m * 16], r2 = r * r;
;                 f32x4 h0, h1;
; #pragma unroll
;                 for (int j = 0; j < 4; ++j) {
;                     const float g0 = acc[ai][0][m][0][j], g1 = acc[ai][0][m][1][j];
;                     h0[j] = g0 * r2 * fast_rcp(1.0f + fast_exp2(g0 * (-LOG2E * r))) * acc[ai][1][m][0][j];
;                     h1[j] = g1 * r2 * fast_rcp(1.0f + fast_exp2(g1 * (-LOG2E * r))) * acc[ai][1][m][1][j]; }
;                 *(u32x4*)rowp = pack8(h0, h1); }
	s_waitcnt lgkmcnt(0)
	s_setprio 1
	s_waitcnt lgkmcnt(0)
	v_mfma_f32_16x16x32_bf16 v[60:63], v[144:147], v[168:171], v[60:63]
	v_mfma_f32_16x16x32_bf16 v[56:59], v[160:163], v[168:171], v[56:59]
	v_mfma_f32_16x16x32_bf16 v[44:47], v[144:147], v[176:179], v[44:47]
	v_mfma_f32_16x16x32_bf16 v[40:43], v[160:163], v[176:179], v[40:43]
	v_mfma_f32_16x16x32_bf16 v[28:31], v[144:147], v[184:187], v[28:31]
	v_mfma_f32_16x16x32_bf16 v[24:27], v[160:163], v[184:187], v[24:27]
	v_mfma_f32_16x16x32_bf16 v[12:15], v[144:147], v[192:195], v[12:15]
	v_mfma_f32_16x16x32_bf16 v[8:11], v[160:163], v[192:195], v[8:11]
	v_mfma_f32_16x16x32_bf16 v[60:63], v[148:151], v[172:175], v[60:63]
	v_mfma_f32_16x16x32_bf16 v[56:59], v[164:167], v[172:175], v[56:59]
	v_mfma_f32_16x16x32_bf16 v[44:47], v[148:151], v[180:183], v[44:47]
	v_mfma_f32_16x16x32_bf16 v[40:43], v[164:167], v[180:183], v[40:43]
	v_mfma_f32_16x16x32_bf16 v[28:31], v[148:151], v[188:191], v[28:31]
	v_mfma_f32_16x16x32_bf16 v[24:27], v[164:167], v[188:191], v[24:27]
	v_mfma_f32_16x16x32_bf16 v[12:15], v[148:151], v[196:199], v[12:15]
	v_mfma_f32_16x16x32_bf16 v[8:11], v[164:167], v[196:199], v[8:11]
	s_setprio 0
	s_barrier
	s_add_u32 s42, s42, 0x80080
	s_addc_u32 s43, s43, 0
	s_add_i32 s44, s44, s23
	s_mov_b32 m0, s44
	s_nop 0
	global_load_lds_dwordx4 v132, s[42:43]
	s_add_i32 m0, s44, 0x2000
	s_nop 0
	global_load_lds_dwordx4 v128, s[42:43]
	s_waitcnt vmcnt(6)
	s_barrier
	s_setprio 1
	v_mfma_f32_16x16x32_bf16 v[52:55], v[200:203], v[168:171], v[52:55]
	v_mfma_f32_16x16x32_bf16 v[48:51], v[208:211], v[168:171], v[48:51]
	v_mfma_f32_16x16x32_bf16 v[36:39], v[200:203], v[176:179], v[36:39]
	v_mfma_f32_16x16x32_bf16 v[32:35], v[208:211], v[176:179], v[32:35]
	v_mfma_f32_16x16x32_bf16 v[20:23], v[200:203], v[184:187], v[20:23]
	v_mfma_f32_16x16x32_bf16 v[16:19], v[208:211], v[184:187], v[16:19]
	v_mfma_f32_16x16x32_bf16 v[4:7], v[200:203], v[192:195], v[4:7]
	v_mfma_f32_16x16x32_bf16 v[0:3], v[208:211], v[192:195], v[0:3]
	v_mfma_f32_16x16x32_bf16 v[52:55], v[204:207], v[172:175], v[52:55]
	v_mfma_f32_16x16x32_bf16 v[48:51], v[212:215], v[172:175], v[48:51]
	v_mfma_f32_16x16x32_bf16 v[36:39], v[204:207], v[180:183], v[36:39]
	v_mfma_f32_16x16x32_bf16 v[32:35], v[212:215], v[180:183], v[32:35]
	v_mfma_f32_16x16x32_bf16 v[20:23], v[204:207], v[188:191], v[20:23]
	v_mfma_f32_16x16x32_bf16 v[16:19], v[212:215], v[188:191], v[16:19]
	v_mfma_f32_16x16x32_bf16 v[4:7], v[204:207], v[196:199], v[4:7]
	v_mfma_f32_16x16x32_bf16 v[0:3], v[212:215], v[196:199], v[0:3]
	s_setprio 0
	s_add_i32 s58, s58, 2
	s_add_u32 s40, s40, 0x100
	s_addc_u32 s41, s41, 0
	s_add_u32 s56, s56, 0x100
	s_addc_u32 s57, s57, 0
	s_cmp_gt_u32 s58, 29
	s_barrier
	s_cbranch_scc0 .LBB0_796
	v_lshl_add_u32 v144, s38, 8, v152
	v_ashrrev_i32_e32 v145, 31, v144
	v_lshl_add_u64 v[150:151], v[144:145], 2, s[14:15]
	v_mov_b32_e32 v145, v224
	v_mov_b32_e32 v204, v225
	v_mov_b32_e32 v205, v226
	v_mov_b32_e32 v206, v227
	v_mov_b32_e32 v207, v228
	v_mov_b32_e32 v208, v229
	v_mov_b32_e32 v209, v230
	v_mov_b32_e32 v210, v231
	v_lshl_or_b32 v148, s53, 7, v154
	v_mov_b64_e32 v[146:147], s[20:21]
	v_ashrrev_i32_e32 v149, 31, v148
	v_mad_i64_i32 v[160:161], s[40:41], v144, s52, v[146:147]
	v_lshlrev_b64 v[148:149], 1, v[148:149]
	v_lshl_add_u64 v[160:161], v[160:161], 0, v[148:149]
	s_and_b64 vcc, exec, s[6:7]
	s_mov_b32 s53, s8
	s_mov_b32 s38, s30
	s_mov_b64 s[42:43], s[36:37]
	v_mul_f32_e32 v162, v145, v145
	v_mul_f32_e32 v145, 0xbfb8aa3b, v145
	v_mul_f32_e32 v163, v124, v162
	v_mul_f32_e32 v164, v120, v162
	v_mul_f32_e32 v120, v120, v145
	v_mul_f32_e32 v165, v125, v162
	v_mul_f32_e32 v125, v125, v145
	v_mul_f32_e32 v166, v121, v162
	v_mul_f32_e32 v121, v121, v145
	v_mul_f32_e32 v167, v126, v162
	v_mul_f32_e32 v126, v126, v145
	v_mul_f32_e32 v168, v122, v162
	v_mul_f32_e32 v122, v122, v145
	v_mul_f32_e32 v169, v127, v162
	v_mul_f32_e32 v127, v127, v145
	v_mul_f32_e32 v162, v123, v162
	v_mul_f32_e32 v123, v123, v145
	v_mul_f32_e32 v124, v124, v145
	v_exp_f32_e32 v120, v120
	v_exp_f32_e32 v125, v125
	v_exp_f32_e32 v121, v121
	v_exp_f32_e32 v126, v126
	v_exp_f32_e32 v122, v122
	v_exp_f32_e32 v127, v127
	v_exp_f32_e32 v123, v123
	v_exp_f32_e32 v124, v124
	v_add_f32_e32 v120, 1.0, v120
	v_add_f32_e32 v125, 1.0, v125
	v_add_f32_e32 v121, 1.0, v121
	v_add_f32_e32 v126, 1.0, v126
	v_add_f32_e32 v122, 1.0, v122
	v_add_f32_e32 v127, 1.0, v127
	v_add_f32_e32 v123, 1.0, v123
	v_add_f32_e32 v124, 1.0, v124
	v_rcp_f32_e32 v120, v120
	v_rcp_f32_e32 v125, v125
	v_rcp_f32_e32 v121, v121
	v_rcp_f32_e32 v126, v126
	v_rcp_f32_e32 v122, v122
	v_rcp_f32_e32 v127, v127
	v_rcp_f32_e32 v123, v123
	v_rcp_f32_e32 v124, v124
	v_mul_f32_e32 v120, v164, v120
	v_mul_f32_e32 v125, v165, v125
	v_mul_f32_e32 v121, v166, v121
	v_mul_f32_e32 v126, v167, v126
	v_mul_f32_e32 v122, v168, v122
	v_mul_f32_e32 v127, v169, v127
	v_mul_f32_e32 v123, v162, v123
	v_mul_f32_e32 v124, v163, v124
	v_mul_f32_e32 v120, v112, v120
	v_mul_f32_e32 v112, v117, v125
	v_mul_f32_e32 v117, v113, v121
	v_mul_f32_e32 v113, v118, v126
	v_mul_f32_e32 v118, v114, v122
	v_mul_f32_e32 v114, v119, v127
	v_mul_f32_e32 v115, v115, v123
	v_mul_f32_e32 v116, v116, v124
	v_cvt_pk_bf16_f32 v112, v116, v112
	v_cvt_pk_bf16_f32 v113, v113, v114
	v_cvt_pk_bf16_f32 v114, v120, v117
	v_cvt_pk_bf16_f32 v115, v118, v115
	global_store_dwordx4 v[160:161], v[112:115], off
	s_nop 1
	v_mov_b32_e32 v114, v204
	s_nop 0
	v_or_b32_e32 v112, 16, v144
	v_mad_i64_i32 v[112:113], s[40:41], v112, s52, v[146:147]
	v_lshl_add_u64 v[112:113], v[112:113], 0, v[148:149]
	v_mul_f32_e32 v115, v114, v114
	v_mul_f32_e32 v114, 0xbfb8aa3b, v114
; __device__ __forceinline__ float fast_rcp(float x) { return __builtin_amdgcn_rcpf(x); }
; __device__ __forceinline__ float fast_exp2(float x) { return __builtin_amdgcn_exp2f(x); }
; __device__ __forceinline__ u32x4 pack8(f32x4 v0, f32x4 v1) { u32x4 w; w.x = cvt_pk_bf16(v0[0], v0[1]); w.y = cvt_pk_bf16(v0[2], v0[3]); w.z = cvt_pk_bf16(v1[0], v1[1]); w.w = cvt_pk_bf16(v1[2], v1[3]); return w; }
;     __device__ __forceinline__ void operator()(const f32x4 (&acc)[2][2][4][2], const Unit& u, int wr, int wc, int fr, int fq) const {
;         const int row0 = u.pm * BM + wr * 64 + fr, col0 = u.pn * HALF + wc * 32 + 8 * fq;
; #pragma unroll
;         for (int ai = 0; ai < 2; ++ai)
; #pragma unroll
;             for (int m = 0; m < 4; ++m) { bf16_t* rowp = O + (size_t)(row0 + ai * HALF + m * 16) * DFF + col0;
;                 const float r = rs[row0 + ai * HALF + m * 16], r2 = r * r;
;                 f32x4 h0, h1;
; #pragma unroll
;                 for (int j = 0; j < 4; ++j) {
;                     const float g0 = acc[ai][0][m][0][j], g1 = acc[ai][0][m][1][j];
;                     h0[j] = g0 * r2 * fast_rcp(1.0f + fast_exp2(g0 * (-LOG2E * r))) * acc[ai][1][m][0][j];
;                     h1[j] = g1 * r2 * fast_rcp(1.0f + fast_exp2(g1 * (-LOG2E * r))) * acc[ai][1][m][1][j]; }
;                 *(u32x4*)rowp = pack8(h0, h1); }
	v_mul_f32_e32 v116, v108, v115
	v_mul_f32_e32 v117, v104, v115
	v_mul_f32_e32 v104, v104, v114
	v_mul_f32_e32 v118, v109, v115
	v_mul_f32_e32 v109, v109, v114
	v_mul_f32_e32 v119, v105, v115
	v_mul_f32_e32 v105, v105, v114
	v_mul_f32_e32 v120, v110, v115
	v_mul_f32_e32 v110, v110, v114
	v_mul_f32_e32 v121, v106, v115
	v_mul_f32_e32 v106, v106, v114
	v_mul_f32_e32 v122, v111, v115
	v_mul_f32_e32 v111, v111, v114
	v_mul_f32_e32 v115, v107, v115
	v_mul_f32_e32 v107, v107, v114
	v_mul_f32_e32 v108, v108, v114
	v_exp_f32_e32 v104, v104
	v_exp_f32_e32 v109, v109
	v_exp_f32_e32 v105, v105
	v_exp_f32_e32 v110, v110
	v_exp_f32_e32 v106, v106
	v_exp_f32_e32 v111, v111
	v_exp_f32_e32 v107, v107
	v_exp_f32_e32 v108, v108
	v_add_f32_e32 v104, 1.0, v104
	v_add_f32_e32 v109, 1.0, v109
	v_add_f32_e32 v105, 1.0, v105
	v_add_f32_e32 v110, 1.0, v110
	v_add_f32_e32 v106, 1.0, v106
	v_add_f32_e32 v111, 1.0, v111
	v_add_f32_e32 v107, 1.0, v107
	v_add_f32_e32 v108, 1.0, v108
	v_rcp_f32_e32 v104, v104
	v_rcp_f32_e32 v109, v109
	v_rcp_f32_e32 v105, v105
	v_rcp_f32_e32 v110, v110
	v_rcp_f32_e32 v106, v106
	v_rcp_f32_e32 v111, v111
	v_rcp_f32_e32 v107, v107
	v_rcp_f32_e32 v108, v108
	v_mul_f32_e32 v104, v117, v104
	v_mul_f32_e32 v109, v118, v109
	v_mul_f32_e32 v105, v119, v105
	v_mul_f32_e32 v110, v120, v110
	v_mul_f32_e32 v106, v121, v106
	v_mul_f32_e32 v111, v122, v111
	v_mul_f32_e32 v107, v115, v107
	v_mul_f32_e32 v108, v116, v108
	v_mul_f32_e32 v104, v96, v104
	v_mul_f32_e32 v96, v101, v109
	v_mul_f32_e32 v101, v97, v105
	v_mul_f32_e32 v97, v102, v110
	v_mul_f32_e32 v102, v98, v106
	v_mul_f32_e32 v98, v103, v111
	v_mul_f32_e32 v99, v99, v107
	v_mul_f32_e32 v100, v100, v108
	v_cvt_pk_bf16_f32 v96, v100, v96
	v_cvt_pk_bf16_f32 v97, v97, v98
	v_cvt_pk_bf16_f32 v98, v104, v101
	v_cvt_pk_bf16_f32 v99, v102, v99
	global_store_dwordx4 v[112:113], v[96:99], off
	s_nop 1
	v_mov_b32_e32 v98, v205
	s_nop 0
	v_or_b32_e32 v96, 32, v144
	v_mad_i64_i32 v[96:97], s[40:41], v96, s52, v[146:147]
	v_lshl_add_u64 v[96:97], v[96:97], 0, v[148:149]
	v_mul_f32_e32 v99, v98, v98
	v_mul_f32_e32 v98, 0xbfb8aa3b, v98
	v_mul_f32_e32 v100, v92, v99
	v_mul_f32_e32 v101, v88, v99
	v_mul_f32_e32 v88, v88, v98
	v_mul_f32_e32 v102, v93, v99
	v_mul_f32_e32 v93, v93, v98
	v_mul_f32_e32 v103, v89, v99
	v_mul_f32_e32 v89, v89, v98
	v_mul_f32_e32 v104, v94, v99
	v_mul_f32_e32 v94, v94, v98
	v_mul_f32_e32 v105, v90, v99
	v_mul_f32_e32 v90, v90, v98
	v_mul_f32_e32 v106, v95, v99
	v_mul_f32_e32 v95, v95, v98
	v_mul_f32_e32 v99, v91, v99
	v_mul_f32_e32 v91, v91, v98
	v_mul_f32_e32 v92, v92, v98
	v_exp_f32_e32 v88, v88
	v_exp_f32_e32 v93, v93
	v_exp_f32_e32 v89, v89
	v_exp_f32_e32 v94, v94
	v_exp_f32_e32 v90, v90
	v_exp_f32_e32 v95, v95
	v_exp_f32_e32 v91, v91
	v_exp_f32_e32 v92, v92
	v_add_f32_e32 v88, 1.0, v88
	v_add_f32_e32 v93, 1.0, v93
	v_add_f32_e32 v89, 1.0, v89
	v_add_f32_e32 v94, 1.0, v94
	v_add_f32_e32 v90, 1.0, v90
	v_add_f32_e32 v95, 1.0, v95
	v_add_f32_e32 v91, 1.0, v91
	v_add_f32_e32 v92, 1.0, v92
	v_rcp_f32_e32 v88, v88
	v_rcp_f32_e32 v93, v93
	v_rcp_f32_e32 v89, v89
	v_rcp_f32_e32 v94, v94
	v_rcp_f32_e32 v90, v90
	v_rcp_f32_e32 v95, v95
	v_rcp_f32_e32 v91, v91
	v_rcp_f32_e32 v92, v92
	v_mul_f32_e32 v88, v101, v88
	v_mul_f32_e32 v93, v102, v93
	v_mul_f32_e32 v89, v103, v89
	v_mul_f32_e32 v94, v104, v94
	v_mul_f32_e32 v90, v105, v90
	v_mul_f32_e32 v95, v106, v95
	v_mul_f32_e32 v91, v99, v91
	v_mul_f32_e32 v92, v100, v92
	v_mul_f32_e32 v88, v80, v88
	v_mul_f32_e32 v80, v85, v93
	v_mul_f32_e32 v85, v81, v89
	v_mul_f32_e32 v81, v86, v94
	v_mul_f32_e32 v86, v82, v90
	v_mul_f32_e32 v82, v87, v95
	v_mul_f32_e32 v83, v83, v91
	v_mul_f32_e32 v84, v84, v92
	v_cvt_pk_bf16_f32 v80, v84, v80
	v_cvt_pk_bf16_f32 v81, v81, v82
	v_cvt_pk_bf16_f32 v82, v88, v85
	v_cvt_pk_bf16_f32 v83, v86, v83
	global_store_dwordx4 v[96:97], v[80:83], off
	s_nop 1
	v_mov_b32_e32 v82, v206
	s_nop 0
	v_or_b32_e32 v80, 48, v144
	v_mad_i64_i32 v[80:81], s[40:41], v80, s52, v[146:147]
	v_lshl_add_u64 v[80:81], v[80:81], 0, v[148:149]
	v_mul_f32_e32 v83, v82, v82
	v_mul_f32_e32 v82, 0xbfb8aa3b, v82
	v_mul_f32_e32 v84, v76, v83
	v_mul_f32_e32 v85, v72, v83
	v_mul_f32_e32 v72, v72, v82
	v_mul_f32_e32 v86, v77, v83
	v_mul_f32_e32 v77, v77, v82
	v_mul_f32_e32 v87, v73, v83
	v_mul_f32_e32 v73, v73, v82
	v_mul_f32_e32 v88, v78, v83
	v_mul_f32_e32 v78, v78, v82
	v_mul_f32_e32 v89, v74, v83
	v_mul_f32_e32 v74, v74, v82
	v_mul_f32_e32 v90, v79, v83
	v_mul_f32_e32 v79, v79, v82
	v_mul_f32_e32 v83, v75, v83
	v_mul_f32_e32 v75, v75, v82
	v_mul_f32_e32 v76, v76, v82
	v_exp_f32_e32 v72, v72
	v_exp_f32_e32 v77, v77
	v_exp_f32_e32 v73, v73
	v_exp_f32_e32 v78, v78
	v_exp_f32_e32 v74, v74
	v_exp_f32_e32 v79, v79
	v_exp_f32_e32 v75, v75
	v_exp_f32_e32 v76, v76
	v_add_f32_e32 v72, 1.0, v72
	v_add_f32_e32 v77, 1.0, v77
	v_add_f32_e32 v73, 1.0, v73
	v_add_f32_e32 v78, 1.0, v78
	v_add_f32_e32 v74, 1.0, v74
	v_add_f32_e32 v79, 1.0, v79
	v_add_f32_e32 v75, 1.0, v75
	v_add_f32_e32 v76, 1.0, v76
	v_rcp_f32_e32 v72, v72
	v_rcp_f32_e32 v77, v77
	v_rcp_f32_e32 v73, v73
	v_rcp_f32_e32 v78, v78
	v_rcp_f32_e32 v74, v74
	v_rcp_f32_e32 v79, v79
	v_rcp_f32_e32 v75, v75
	v_rcp_f32_e32 v76, v76
	v_mul_f32_e32 v72, v85, v72
	v_mul_f32_e32 v77, v86, v77
	v_mul_f32_e32 v73, v87, v73
	v_mul_f32_e32 v78, v88, v78
	v_mul_f32_e32 v74, v89, v74
	v_mul_f32_e32 v79, v90, v79
	v_mul_f32_e32 v75, v83, v75
	v_mul_f32_e32 v76, v84, v76
	v_mul_f32_e32 v72, v64, v72
	v_mul_f32_e32 v64, v69, v77
	v_mul_f32_e32 v69, v65, v73
	v_mul_f32_e32 v65, v70, v78
	v_mul_f32_e32 v70, v66, v74
	v_mul_f32_e32 v66, v71, v79
	v_mul_f32_e32 v67, v67, v75
	v_mul_f32_e32 v68, v68, v76
; __device__ __forceinline__ float fast_rcp(float x) { return __builtin_amdgcn_rcpf(x); }
; __device__ __forceinline__ float fast_exp2(float x) { return __builtin_amdgcn_exp2f(x); }
; __device__ __forceinline__ u32x4 pack8(f32x4 v0, f32x4 v1) { u32x4 w; w.x = cvt_pk_bf16(v0[0], v0[1]); w.y = cvt_pk_bf16(v0[2], v0[3]); w.z = cvt_pk_bf16(v1[0], v1[1]); w.w = cvt_pk_bf16(v1[2], v1[3]); return w; }
;     __device__ __forceinline__ void operator()(const f32x4 (&acc)[2][2][4][2], const Unit& u, int wr, int wc, int fr, int fq) const {
;         const int row0 = u.pm * BM + wr * 64 + fr, col0 = u.pn * HALF + wc * 32 + 8 * fq;
; #pragma unroll
;         for (int ai = 0; ai < 2; ++ai)
; #pragma unroll
;             for (int m = 0; m < 4; ++m) { bf16_t* rowp = O + (size_t)(row0 + ai * HALF + m * 16) * DFF + col0;
;                 const float r = rs[row0 + ai * HALF + m * 16], r2 = r * r;
;                 f32x4 h0, h1;
; #pragma unroll
;                 for (int j = 0; j < 4; ++j) {
;                     const float g0 = acc[ai][0][m][0][j], g1 = acc[ai][0][m][1][j];
;                     h0[j] = g0 * r2 * fast_rcp(1.0f + fast_exp2(g0 * (-LOG2E * r))) * acc[ai][1][m][0][j];
;                     h1[j] = g1 * r2 * fast_rcp(1.0f + fast_exp2(g1 * (-LOG2E * r))) * acc[ai][1][m][1][j]; }
;                 *(u32x4*)rowp = pack8(h0, h1); }
	v_cvt_pk_bf16_f32 v64, v68, v64
	v_cvt_pk_bf16_f32 v65, v65, v66
	v_cvt_pk_bf16_f32 v66, v72, v69
	v_cvt_pk_bf16_f32 v67, v70, v67
	global_store_dwordx4 v[80:81], v[64:67], off
	s_nop 1
	v_mov_b32_e32 v66, v207
	s_nop 0
	v_add_u32_e32 v64, 0x80, v144
	v_mad_i64_i32 v[64:65], s[40:41], v64, s52, v[146:147]
	v_lshl_add_u64 v[64:65], v[64:65], 0, v[148:149]
	v_mul_f32_e32 v67, v66, v66
	v_mul_f32_e32 v66, 0xbfb8aa3b, v66
	v_mul_f32_e32 v68, v60, v67
	v_mul_f32_e32 v69, v56, v67
	v_mul_f32_e32 v56, v56, v66
	v_mul_f32_e32 v70, v61, v67
	v_mul_f32_e32 v61, v61, v66
	v_mul_f32_e32 v71, v57, v67
	v_mul_f32_e32 v57, v57, v66
	v_mul_f32_e32 v72, v62, v67
	v_mul_f32_e32 v62, v62, v66
	v_mul_f32_e32 v73, v58, v67
	v_mul_f32_e32 v58, v58, v66
	v_mul_f32_e32 v74, v63, v67
	v_mul_f32_e32 v63, v63, v66
	v_mul_f32_e32 v67, v59, v67
	v_mul_f32_e32 v59, v59, v66
	v_mul_f32_e32 v60, v60, v66
	v_exp_f32_e32 v56, v56
	v_exp_f32_e32 v61, v61
	v_exp_f32_e32 v57, v57
	v_exp_f32_e32 v62, v62
	v_exp_f32_e32 v58, v58
	v_exp_f32_e32 v63, v63
	v_exp_f32_e32 v59, v59
	v_exp_f32_e32 v60, v60
	v_add_f32_e32 v56, 1.0, v56
	v_add_f32_e32 v61, 1.0, v61
	v_add_f32_e32 v57, 1.0, v57
	v_add_f32_e32 v62, 1.0, v62
	v_add_f32_e32 v58, 1.0, v58
	v_add_f32_e32 v63, 1.0, v63
	v_add_f32_e32 v59, 1.0, v59
	v_add_f32_e32 v60, 1.0, v60
	v_rcp_f32_e32 v56, v56
	v_rcp_f32_e32 v61, v61
	v_rcp_f32_e32 v57, v57
	v_rcp_f32_e32 v62, v62
	v_rcp_f32_e32 v58, v58
	v_rcp_f32_e32 v63, v63
	v_rcp_f32_e32 v59, v59
	v_rcp_f32_e32 v60, v60
	v_mul_f32_e32 v56, v69, v56
	v_mul_f32_e32 v61, v70, v61
	v_mul_f32_e32 v57, v71, v57
	v_mul_f32_e32 v62, v72, v62
	v_mul_f32_e32 v58, v73, v58
	v_mul_f32_e32 v63, v74, v63
	v_mul_f32_e32 v59, v67, v59
	v_mul_f32_e32 v60, v68, v60
	v_mul_f32_e32 v56, v48, v56
	v_mul_f32_e32 v48, v53, v61
	v_mul_f32_e32 v53, v49, v57
	v_mul_f32_e32 v49, v54, v62
	v_mul_f32_e32 v54, v50, v58
	v_mul_f32_e32 v50, v55, v63
	v_mul_f32_e32 v51, v51, v59
	v_mul_f32_e32 v52, v52, v60
	v_cvt_pk_bf16_f32 v48, v52, v48
	v_cvt_pk_bf16_f32 v49, v49, v50
	v_cvt_pk_bf16_f32 v50, v56, v53
	v_cvt_pk_bf16_f32 v51, v54, v51
	global_store_dwordx4 v[64:65], v[48:51], off
	s_nop 1
	v_mov_b32_e32 v50, v208
	s_nop 0
	v_add_u32_e32 v48, 0x90, v144
	v_mad_i64_i32 v[48:49], s[40:41], v48, s52, v[146:147]
	v_lshl_add_u64 v[48:49], v[48:49], 0, v[148:149]
	v_mul_f32_e32 v51, v50, v50
	v_mul_f32_e32 v50, 0xbfb8aa3b, v50
	v_mul_f32_e32 v52, v44, v51
	v_mul_f32_e32 v53, v40, v51
	v_mul_f32_e32 v40, v40, v50
	v_mul_f32_e32 v54, v45, v51
	v_mul_f32_e32 v45, v45, v50
	v_mul_f32_e32 v55, v41, v51
	v_mul_f32_e32 v41, v41, v50
	v_mul_f32_e32 v56, v46, v51
	v_mul_f32_e32 v46, v46, v50
	v_mul_f32_e32 v57, v42, v51
	v_mul_f32_e32 v42, v42, v50
	v_mul_f32_e32 v58, v47, v51
	v_mul_f32_e32 v47, v47, v50
	v_mul_f32_e32 v51, v43, v51
	v_mul_f32_e32 v43, v43, v50
	v_mul_f32_e32 v44, v44, v50
	v_exp_f32_e32 v40, v40
	v_exp_f32_e32 v45, v45
	v_exp_f32_e32 v41, v41
	v_exp_f32_e32 v46, v46
	v_exp_f32_e32 v42, v42
	v_exp_f32_e32 v47, v47
	v_exp_f32_e32 v43, v43
	v_exp_f32_e32 v44, v44
	v_add_f32_e32 v40, 1.0, v40
	v_add_f32_e32 v45, 1.0, v45
	v_add_f32_e32 v41, 1.0, v41
	v_add_f32_e32 v46, 1.0, v46
	v_add_f32_e32 v42, 1.0, v42
	v_add_f32_e32 v47, 1.0, v47
	v_add_f32_e32 v43, 1.0, v43
	v_add_f32_e32 v44, 1.0, v44
	v_rcp_f32_e32 v40, v40
	v_rcp_f32_e32 v45, v45
	v_rcp_f32_e32 v41, v41
	v_rcp_f32_e32 v46, v46
	v_rcp_f32_e32 v42, v42
	v_rcp_f32_e32 v47, v47
	v_rcp_f32_e32 v43, v43
	v_rcp_f32_e32 v44, v44
	v_mul_f32_e32 v40, v53, v40
	v_mul_f32_e32 v45, v54, v45
	v_mul_f32_e32 v41, v55, v41
	v_mul_f32_e32 v46, v56, v46
	v_mul_f32_e32 v42, v57, v42
	v_mul_f32_e32 v47, v58, v47
	v_mul_f32_e32 v43, v51, v43
	v_mul_f32_e32 v44, v52, v44
	v_mul_f32_e32 v40, v32, v40
	v_mul_f32_e32 v32, v37, v45
	v_mul_f32_e32 v37, v33, v41
	v_mul_f32_e32 v33, v38, v46
	v_mul_f32_e32 v38, v34, v42
	v_mul_f32_e32 v34, v39, v47
	v_mul_f32_e32 v35, v35, v43
	v_mul_f32_e32 v36, v36, v44
	v_cvt_pk_bf16_f32 v32, v36, v32
	v_cvt_pk_bf16_f32 v33, v33, v34
	v_cvt_pk_bf16_f32 v34, v40, v37
	v_cvt_pk_bf16_f32 v35, v38, v35
; __device__ __forceinline__ float fast_rcp(float x) { return __builtin_amdgcn_rcpf(x); }
; __device__ __forceinline__ float fast_exp2(float x) { return __builtin_amdgcn_exp2f(x); }
; #define PG8_WAIT_V(n) asm volatile("s_waitcnt vmcnt(" #n ")" ::: "memory")
; #define PG8_BAR __builtin_amdgcn_s_barrier()
; __device__ __forceinline__ u32x4 pack8(f32x4 v0, f32x4 v1) { u32x4 w; w.x = cvt_pk_bf16(v0[0], v0[1]); w.y = cvt_pk_bf16(v0[2], v0[3]); w.z = cvt_pk_bf16(v1[0], v1[1]); w.w = cvt_pk_bf16(v1[2], v1[3]); return w; }
; template <class Epi>
; __device__ __forceinline__ void gemm_phase(LAS unsigned char* lds, const Gemm g, const StaticOrder& S, const Epi& E) {
;     ...
;         if (!has_next) break;
; #pragma unroll
;         for (int a = 0; a < 2; ++a)
; #pragma unroll
;             for (int b = 0; b < 2; ++b)
; #pragma unroll
;                 for (int m = 0; m < 4; ++m)
; #pragma unroll
;                     for (int n = 0; n < 2; ++n) acc[a][b][m][n] = (f32x4){0.f, 0.f, 0.f, 0.f};
;         cur = nxt; cA = nA; cB = nB; ++ui;
;     }
;     PG8_WAIT_V(0);
;     if (wr == 0) PG8_BAR;
;     __device__ __forceinline__ void operator()(const f32x4 (&acc)[2][2][4][2], const Unit& u, int wr, int wc, int fr, int fq) const {
;         const int row0 = u.pm * BM + wr * 64 + fr, col0 = u.pn * HALF + wc * 32 + 8 * fq;
; #pragma unroll
;         for (int ai = 0; ai < 2; ++ai)
; #pragma unroll
;             for (int m = 0; m < 4; ++m) { bf16_t* rowp = O + (size_t)(row0 + ai * HALF + m * 16) * DFF + col0;
;                 const float r = rs[row0 + ai * HALF + m * 16], r2 = r * r;
;                 f32x4 h0, h1;
; #pragma unroll
;                 for (int j = 0; j < 4; ++j) {
;                     const float g0 = acc[ai][0][m][0][j], g1 = acc[ai][0][m][1][j];
;                     h0[j] = g0 * r2 * fast_rcp(1.0f + fast_exp2(g0 * (-LOG2E * r))) * acc[ai][1][m][0][j];
;                     h1[j] = g1 * r2 * fast_rcp(1.0f + fast_exp2(g1 * (-LOG2E * r))) * acc[ai][1][m][1][j]; }
;                 *(u32x4*)rowp = pack8(h0, h1); }
	global_store_dwordx4 v[48:49], v[32:35], off
	s_nop 1
	v_mov_b32_e32 v34, v209
	s_nop 0
	v_add_u32_e32 v32, 0xa0, v144
	v_mad_i64_i32 v[32:33], s[40:41], v32, s52, v[146:147]
	v_lshl_add_u64 v[32:33], v[32:33], 0, v[148:149]
	s_mov_b64 s[40:41], s[34:35]
	v_mul_f32_e32 v35, v34, v34
	v_mul_f32_e32 v34, 0xbfb8aa3b, v34
	v_mul_f32_e32 v36, v28, v35
	v_mul_f32_e32 v37, v24, v35
	v_mul_f32_e32 v24, v24, v34
	v_mul_f32_e32 v38, v29, v35
	v_mul_f32_e32 v29, v29, v34
	v_mul_f32_e32 v39, v25, v35
	v_mul_f32_e32 v25, v25, v34
	v_mul_f32_e32 v40, v30, v35
	v_mul_f32_e32 v30, v30, v34
	v_mul_f32_e32 v41, v26, v35
	v_mul_f32_e32 v26, v26, v34
	v_mul_f32_e32 v42, v31, v35
	v_mul_f32_e32 v31, v31, v34
	v_mul_f32_e32 v35, v27, v35
	v_mul_f32_e32 v27, v27, v34
	v_mul_f32_e32 v28, v28, v34
	v_exp_f32_e32 v24, v24
	v_exp_f32_e32 v29, v29
	v_exp_f32_e32 v25, v25
	v_exp_f32_e32 v30, v30
	v_exp_f32_e32 v26, v26
	v_exp_f32_e32 v31, v31
	v_exp_f32_e32 v27, v27
	v_exp_f32_e32 v28, v28
	v_add_f32_e32 v24, 1.0, v24
	v_add_f32_e32 v29, 1.0, v29
	v_add_f32_e32 v25, 1.0, v25
	v_add_f32_e32 v30, 1.0, v30
	v_add_f32_e32 v26, 1.0, v26
	v_add_f32_e32 v31, 1.0, v31
	v_add_f32_e32 v27, 1.0, v27
	v_add_f32_e32 v28, 1.0, v28
	v_rcp_f32_e32 v24, v24
	v_rcp_f32_e32 v29, v29
	v_rcp_f32_e32 v25, v25
	v_rcp_f32_e32 v30, v30
	v_rcp_f32_e32 v26, v26
	v_rcp_f32_e32 v31, v31
	v_rcp_f32_e32 v27, v27
	v_rcp_f32_e32 v28, v28
	v_mul_f32_e32 v24, v37, v24
	v_mul_f32_e32 v29, v38, v29
	v_mul_f32_e32 v25, v39, v25
	v_mul_f32_e32 v30, v40, v30
	v_mul_f32_e32 v26, v41, v26
	v_mul_f32_e32 v31, v42, v31
	v_mul_f32_e32 v27, v35, v27
	v_mul_f32_e32 v28, v36, v28
	v_mul_f32_e32 v24, v16, v24
	v_mul_f32_e32 v16, v21, v29
	v_mul_f32_e32 v21, v17, v25
	v_mul_f32_e32 v17, v22, v30
	v_mul_f32_e32 v22, v18, v26
	v_mul_f32_e32 v18, v23, v31
	v_mul_f32_e32 v19, v19, v27
	v_mul_f32_e32 v20, v20, v28
	v_cvt_pk_bf16_f32 v16, v20, v16
	v_cvt_pk_bf16_f32 v17, v17, v18
	v_cvt_pk_bf16_f32 v18, v24, v21
	v_cvt_pk_bf16_f32 v19, v22, v19
	global_store_dwordx4 v[32:33], v[16:19], off
	s_nop 1
	v_mov_b32_e32 v18, v210
	s_nop 0
	v_add_u32_e32 v16, 0xb0, v144
	v_mad_i64_i32 v[16:17], s[6:7], v16, s52, v[146:147]
	v_lshl_add_u64 v[16:17], v[16:17], 0, v[148:149]
	v_mul_f32_e32 v19, v18, v18
	v_mul_f32_e32 v18, 0xbfb8aa3b, v18
	v_mul_f32_e32 v20, v12, v19
	v_mul_f32_e32 v21, v8, v19
	v_mul_f32_e32 v8, v8, v18
	v_mul_f32_e32 v22, v13, v19
	v_mul_f32_e32 v13, v13, v18
	v_mul_f32_e32 v23, v9, v19
	v_mul_f32_e32 v9, v9, v18
	v_mul_f32_e32 v24, v14, v19
	v_mul_f32_e32 v14, v14, v18
	v_mul_f32_e32 v25, v10, v19
	v_mul_f32_e32 v10, v10, v18
	v_mul_f32_e32 v26, v15, v19
	v_mul_f32_e32 v15, v15, v18
	v_mul_f32_e32 v19, v11, v19
	v_mul_f32_e32 v11, v11, v18
	v_mul_f32_e32 v12, v12, v18
	v_exp_f32_e32 v8, v8
	v_exp_f32_e32 v13, v13
	v_exp_f32_e32 v9, v9
	v_exp_f32_e32 v14, v14
	v_exp_f32_e32 v10, v10
	v_exp_f32_e32 v15, v15
	v_exp_f32_e32 v11, v11
	v_exp_f32_e32 v12, v12
	v_add_f32_e32 v8, 1.0, v8
	v_add_f32_e32 v13, 1.0, v13
	v_add_f32_e32 v9, 1.0, v9
	v_add_f32_e32 v14, 1.0, v14
	v_add_f32_e32 v10, 1.0, v10
	v_add_f32_e32 v15, 1.0, v15
	v_add_f32_e32 v11, 1.0, v11
	v_add_f32_e32 v12, 1.0, v12
	v_rcp_f32_e32 v8, v8
	v_rcp_f32_e32 v13, v13
	v_rcp_f32_e32 v9, v9
	v_rcp_f32_e32 v14, v14
	v_rcp_f32_e32 v10, v10
	v_rcp_f32_e32 v15, v15
	v_rcp_f32_e32 v11, v11
	v_rcp_f32_e32 v12, v12
	v_mul_f32_e32 v8, v21, v8
	v_mul_f32_e32 v13, v22, v13
	v_mul_f32_e32 v9, v23, v9
	v_mul_f32_e32 v14, v24, v14
	v_mul_f32_e32 v10, v25, v10
	v_mul_f32_e32 v15, v26, v15
	v_mul_f32_e32 v11, v19, v11
	v_mul_f32_e32 v12, v20, v12
	v_mul_f32_e32 v8, v0, v8
	v_mul_f32_e32 v0, v5, v13
	v_mul_f32_e32 v5, v1, v9
	v_mul_f32_e32 v1, v6, v14
	v_mul_f32_e32 v6, v2, v10
	v_mul_f32_e32 v2, v7, v15
	v_mul_f32_e32 v3, v3, v11
	v_mul_f32_e32 v4, v4, v12
	v_cvt_pk_bf16_f32 v0, v4, v0
	v_cvt_pk_bf16_f32 v1, v1, v2
	v_cvt_pk_bf16_f32 v2, v8, v5
	v_cvt_pk_bf16_f32 v3, v6, v3
	global_store_dwordx4 v[16:17], v[0:3], off
	s_cbranch_vccz .LBB0_793
	s_waitcnt vmcnt(0)
	s_cmpk_gt_u32 s10, 0xff
	s_cbranch_scc1 .LBB0_800
	s_barrier

; #define PG8_STAGE(bufoff, gbase, voff) do { _Pragma("unroll") for (int _i = 0; _i < 2; ++_i) \
;         __builtin_amdgcn_global_load_lds((const unsigned*)((const char*)(gbase) + (voff)[_i]), (LAS unsigned*)(lds + (bufoff) + ldsw + _i * 8192), 16, 0, 0); } while (0)
; #define PG8_LDA(dst, b, h) do { _Pragma("unroll") for (int m = 0; m < 4; ++m) _Pragma("unroll") for (int k = 0; k < 2; ++k) dst[m][k] = *(const LAS bf16x8*)(lds + PG8_SA(b, h) + aoff + m * 2048 + k * 1024); } while (0)
; #define PG8_LDB(dst, b, h) do { _Pragma("unroll") for (int n = 0; n < 2; ++n) _Pragma("unroll") for (int k = 0; k < 2; ++k) dst[n][k] = *(const LAS bf16x8*)(lds + PG8_SB(b, h) + boff + n * 2048 + k * 1024); } while (0)
; #define PG8_MMA(ai, bj, At, Bt) do { __builtin_amdgcn_s_setprio(1); _Pragma("unroll") for (int m = 0; m < 4; ++m) _Pragma("unroll") for (int n = 0; n < 2; ++n) _Pragma("unroll") for (int k = 0; k < 2; ++k) \
;         acc[ai][bj][m][n] = __builtin_amdgcn_mfma_f32_16x16x32_bf16(Bt[n][k], At[m][k], acc[ai][bj][m][n], 0, 0, 0); __builtin_amdgcn_s_setprio(0); } while (0)
; #define PG8_WAIT_V(n) asm volatile("s_waitcnt vmcnt(" #n ")" ::: "memory")
; #define PG8_WAIT_L(n) asm volatile("s_waitcnt lgkmcnt(" #n ")" ::: "memory")
; #define PG8_BAR __builtin_amdgcn_s_barrier()
; #define PG8_SCHED __builtin_amdgcn_sched_barrier(0)
; template <class Epi>
; __device__ __forceinline__ void gemm_phase(LAS unsigned char* lds, const Gemm g, const StaticOrder& S, const Epi& E) {
;     ...
;             PG8_LDB(B0, 0, 0); PG8_SCHED; PG8_LDA(At, 0, 0); PG8_STAGE(PG8_SA(1, 1), a1 + hstep, voffA);
;             PG8_WAIT_L(8); PG8_BAR; PG8_WAIT_L(0); PG8_MMA(0, 0, At, B0); PG8_BAR; PG8_SCHED;
;             PG8_LDB(B1, 0, 1); PG8_STAGE(PG8_SB(0, 0), b2, voffB);
;             PG8_BAR; PG8_WAIT_L(0); PG8_MMA(0, 1, At, B1); PG8_BAR;
;             PG8_LDA(At, 0, 1); PG8_STAGE(PG8_SA(0, 0), a2, voffA);
;             PG8_BAR; PG8_WAIT_L(0); PG8_MMA(1, 0, At, B0); PG8_BAR; PG8_SCHED;
;             PG8_STAGE(PG8_SB(0, 1), b2 + hstep, voffB);
;             PG8_WAIT_V(6); PG8_BAR; PG8_MMA(1, 1, At, B1); PG8_BAR;
.LBB0_864:
	ds_read_b128 v[148:151], v145
	ds_read_b128 v[152:155], v145 offset:1024
	ds_read_b128 v[160:163], v145 offset:2048
	ds_read_b128 v[164:167], v145 offset:3072
	s_add_u32 s44, s42, 0x100
	s_addc_u32 s45, s43, 0
	s_cmpk_eq_i32 s67, 0x54
	s_cselect_b32 s49, s41, s45
	s_cselect_b32 s48, s40, s44
	s_cselect_b32 s47, s7, s66
	s_cselect_b32 s46, s6, s65
	s_add_i32 m0, s28, 0xc000
	ds_read_b128 v[168:171], v146
	ds_read_b128 v[172:175], v146 offset:1024
	ds_read_b128 v[176:179], v146 offset:2048
	ds_read_b128 v[180:183], v146 offset:3072
	ds_read_b128 v[184:187], v146 offset:4096
	ds_read_b128 v[188:191], v146 offset:5120
	ds_read_b128 v[192:195], v146 offset:6144
	ds_read_b128 v[196:199], v146 offset:7168
	global_load_lds_dwordx4 v136, s[42:43]
	s_add_i32 m0, s28, 0xe000
	s_nop 0
	global_load_lds_dwordx4 v138, s[42:43]
	s_waitcnt lgkmcnt(8)
	s_barrier
	s_waitcnt lgkmcnt(0)
	s_setprio 1
	s_waitcnt lgkmcnt(0)
	v_mfma_f32_16x16x32_bf16 v[124:127], v[148:151], v[168:171], v[124:127]
	v_mfma_f32_16x16x32_bf16 v[120:123], v[160:163], v[168:171], v[120:123]
	v_mfma_f32_16x16x32_bf16 v[112:115], v[148:151], v[176:179], v[112:115]
	v_mfma_f32_16x16x32_bf16 v[104:107], v[160:163], v[176:179], v[104:107]
	v_mfma_f32_16x16x32_bf16 v[96:99], v[148:151], v[184:187], v[96:99]
	v_mfma_f32_16x16x32_bf16 v[88:91], v[160:163], v[184:187], v[88:91]
	v_mfma_f32_16x16x32_bf16 v[80:83], v[148:151], v[192:195], v[80:83]
	v_mfma_f32_16x16x32_bf16 v[72:75], v[160:163], v[192:195], v[72:75]
	v_mfma_f32_16x16x32_bf16 v[124:127], v[152:155], v[172:175], v[124:127]
	v_mfma_f32_16x16x32_bf16 v[120:123], v[164:167], v[172:175], v[120:123]
	v_mfma_f32_16x16x32_bf16 v[112:115], v[152:155], v[180:183], v[112:115]
	v_mfma_f32_16x16x32_bf16 v[104:107], v[164:167], v[180:183], v[104:107]
	v_mfma_f32_16x16x32_bf16 v[96:99], v[152:155], v[188:191], v[96:99]
	v_mfma_f32_16x16x32_bf16 v[88:91], v[164:167], v[188:191], v[88:91]
	v_mfma_f32_16x16x32_bf16 v[80:83], v[152:155], v[196:199], v[80:83]
	v_mfma_f32_16x16x32_bf16 v[72:75], v[164:167], v[196:199], v[72:75]
	s_setprio 0
	s_barrier
	s_add_i32 s42, s55, s23
	v_lshl_add_u64 v[140:141], s[46:47], 0, v[132:133]
	s_mov_b32 m0, s42
	ds_read_b128 v[200:203], v147
	ds_read_b128 v[204:207], v147 offset:1024
	ds_read_b128 v[208:211], v147 offset:2048
	ds_read_b128 v[212:215], v147 offset:3072
	global_load_lds_dwordx4 v132, s[46:47]
	v_lshl_add_u64 v[156:157], s[46:47], 0, v[128:129]
	s_add_i32 m0, s42, 0x2000
	s_nop 0
	global_load_lds_dwordx4 v128, s[46:47]
	s_barrier
	s_waitcnt lgkmcnt(0)
	s_setprio 1
	s_waitcnt lgkmcnt(0)
	v_mfma_f32_16x16x32_bf16 v[116:119], v[200:203], v[168:171], v[116:119]
	v_mfma_f32_16x16x32_bf16 v[108:111], v[208:211], v[168:171], v[108:111]
	v_mfma_f32_16x16x32_bf16 v[100:103], v[200:203], v[176:179], v[100:103]
	v_mfma_f32_16x16x32_bf16 v[92:95], v[208:211], v[176:179], v[92:95]
	v_mfma_f32_16x16x32_bf16 v[84:87], v[200:203], v[184:187], v[84:87]
	v_mfma_f32_16x16x32_bf16 v[76:79], v[208:211], v[184:187], v[76:79]
	v_mfma_f32_16x16x32_bf16 v[68:71], v[200:203], v[192:195], v[68:71]
	v_mfma_f32_16x16x32_bf16 v[64:67], v[208:211], v[192:195], v[64:67]
	v_mfma_f32_16x16x32_bf16 v[116:119], v[204:207], v[172:175], v[116:119]
	v_mfma_f32_16x16x32_bf16 v[108:111], v[212:215], v[172:175], v[108:111]
	v_mfma_f32_16x16x32_bf16 v[100:103], v[204:207], v[180:183], v[100:103]
	v_mfma_f32_16x16x32_bf16 v[92:95], v[212:215], v[180:183], v[92:95]
	v_mfma_f32_16x16x32_bf16 v[84:87], v[204:207], v[188:191], v[84:87]
	v_mfma_f32_16x16x32_bf16 v[76:79], v[212:215], v[188:191], v[76:79]
	v_mfma_f32_16x16x32_bf16 v[68:71], v[204:207], v[196:199], v[68:71]
	v_mfma_f32_16x16x32_bf16 v[64:67], v[212:215], v[196:199], v[64:67]
	s_setprio 0
	s_mov_b32 m0, s28
	v_lshl_add_u64 v[216:217], s[48:49], 0, v[134:135]
	s_barrier
	ds_read_b128 v[168:171], v146 offset:16384
	ds_read_b128 v[172:175], v146 offset:17408
	ds_read_b128 v[176:179], v146 offset:18432
	ds_read_b128 v[180:183], v146 offset:19456
	ds_read_b128 v[184:187], v146 offset:20480
	ds_read_b128 v[188:191], v146 offset:21504
	ds_read_b128 v[192:195], v146 offset:22528
	ds_read_b128 v[196:199], v146 offset:23552
	global_load_lds_dwordx4 v134, s[48:49]
	v_lshl_add_u64 v[218:219], s[48:49], 0, v[130:131]
	s_mov_b32 m0, s29
	s_nop 0
	global_load_lds_dwordx4 v130, s[48:49]
	s_barrier
	s_waitcnt lgkmcnt(0)
	s_setprio 1
	s_waitcnt lgkmcnt(0)
	v_mfma_f32_16x16x32_bf16 v[60:63], v[148:151], v[168:171], v[60:63]
	v_mfma_f32_16x16x32_bf16 v[56:59], v[160:163], v[168:171], v[56:59]
	v_mfma_f32_16x16x32_bf16 v[52:55], v[148:151], v[176:179], v[52:55]
	v_mfma_f32_16x16x32_bf16 v[44:47], v[160:163], v[176:179], v[44:47]
	v_mfma_f32_16x16x32_bf16 v[36:39], v[148:151], v[184:187], v[36:39]
	v_mfma_f32_16x16x32_bf16 v[28:31], v[160:163], v[184:187], v[28:31]
	v_mfma_f32_16x16x32_bf16 v[20:23], v[148:151], v[192:195], v[20:23]
	v_mfma_f32_16x16x32_bf16 v[12:15], v[160:163], v[192:195], v[12:15]
	v_mfma_f32_16x16x32_bf16 v[60:63], v[152:155], v[172:175], v[60:63]
	v_mfma_f32_16x16x32_bf16 v[56:59], v[164:167], v[172:175], v[56:59]
	v_mfma_f32_16x16x32_bf16 v[52:55], v[152:155], v[180:183], v[52:55]
	v_mfma_f32_16x16x32_bf16 v[44:47], v[164:167], v[180:183], v[44:47]
	v_mfma_f32_16x16x32_bf16 v[36:39], v[152:155], v[188:191], v[36:39]
	v_mfma_f32_16x16x32_bf16 v[28:31], v[164:167], v[188:191], v[28:31]
	v_mfma_f32_16x16x32_bf16 v[20:23], v[152:155], v[196:199], v[20:23]
	v_mfma_f32_16x16x32_bf16 v[12:15], v[164:167], v[196:199], v[12:15]
	s_setprio 0
	s_barrier
	s_add_u32 s42, s46, 0x160000
	s_addc_u32 s43, s47, 0
	s_add_i32 s68, s56, s23
	s_mov_b32 m0, s68
	s_nop 0
	global_load_lds_dwordx4 v132, s[42:43]
	s_add_i32 m0, s68, 0x2000
	s_nop 0
	global_load_lds_dwordx4 v128, s[42:43]
	s_waitcnt vmcnt(6)
	s_barrier
; #define PG8_STAGE(bufoff, gbase, voff) do { _Pragma("unroll") for (int _i = 0; _i < 2; ++_i) \
;         __builtin_amdgcn_global_load_lds((const unsigned*)((const char*)(gbase) + (voff)[_i]), (LAS unsigned*)(lds + (bufoff) + ldsw + _i * 8192), 16, 0, 0); } while (0)
; #define PG8_LDA(dst, b, h) do { _Pragma("unroll") for (int m = 0; m < 4; ++m) _Pragma("unroll") for (int k = 0; k < 2; ++k) dst[m][k] = *(const LAS bf16x8*)(lds + PG8_SA(b, h) + aoff + m * 2048 + k * 1024); } while (0)
; #define PG8_LDB(dst, b, h) do { _Pragma("unroll") for (int n = 0; n < 2; ++n) _Pragma("unroll") for (int k = 0; k < 2; ++k) dst[n][k] = *(const LAS bf16x8*)(lds + PG8_SB(b, h) + boff + n * 2048 + k * 1024); } while (0)
; #define PG8_MMA(ai, bj, At, Bt) do { __builtin_amdgcn_s_setprio(1); _Pragma("unroll") for (int m = 0; m < 4; ++m) _Pragma("unroll") for (int n = 0; n < 2; ++n) _Pragma("unroll") for (int k = 0; k < 2; ++k) \
;         acc[ai][bj][m][n] = __builtin_amdgcn_mfma_f32_16x16x32_bf16(Bt[n][k], At[m][k], acc[ai][bj][m][n], 0, 0, 0); __builtin_amdgcn_s_setprio(0); } while (0)
; #define PG8_WAIT_V(n) asm volatile("s_waitcnt vmcnt(" #n ")" ::: "memory")
; #define PG8_WAIT_L(n) asm volatile("s_waitcnt lgkmcnt(" #n ")" ::: "memory")
; #define PG8_BAR __builtin_amdgcn_s_barrier()
; #define PG8_SCHED __builtin_amdgcn_sched_barrier(0)
; template <class Epi>
; __device__ __forceinline__ void gemm_phase(LAS unsigned char* lds, const Gemm g, const StaticOrder& S, const Epi& E) {
;     ...
;             PG8_WAIT_V(6); PG8_BAR; PG8_MMA(1, 1, At, B1); PG8_BAR;
;             PG8_LDB(B0, 1, 0); PG8_SCHED; PG8_LDA(At, 1, 0); PG8_STAGE(PG8_SA(0, 1), a2 + hstep, voffA);
;             PG8_WAIT_L(8); PG8_BAR; PG8_WAIT_L(0); PG8_MMA(0, 0, At, B0); PG8_BAR; PG8_SCHED;
;             PG8_LDB(B1, 1, 1); PG8_STAGE(PG8_SB(1, 0), b3, voffB);
;             PG8_BAR; PG8_WAIT_L(0); PG8_MMA(0, 1, At, B1); PG8_BAR;
;             PG8_LDA(At, 1, 1); PG8_STAGE(PG8_SA(1, 0), a3, voffA);
	s_setprio 1
	v_mfma_f32_16x16x32_bf16 v[48:51], v[200:203], v[168:171], v[48:51]
	v_mfma_f32_16x16x32_bf16 v[40:43], v[208:211], v[168:171], v[40:43]
	v_mfma_f32_16x16x32_bf16 v[32:35], v[200:203], v[176:179], v[32:35]
	v_mfma_f32_16x16x32_bf16 v[24:27], v[208:211], v[176:179], v[24:27]
	v_mfma_f32_16x16x32_bf16 v[16:19], v[200:203], v[184:187], v[16:19]
	v_mfma_f32_16x16x32_bf16 v[8:11], v[208:211], v[184:187], v[8:11]
	v_mfma_f32_16x16x32_bf16 v[4:7], v[200:203], v[192:195], v[4:7]
	v_mfma_f32_16x16x32_bf16 v[0:3], v[208:211], v[192:195], v[0:3]
	v_mfma_f32_16x16x32_bf16 v[48:51], v[204:207], v[172:175], v[48:51]
	v_mfma_f32_16x16x32_bf16 v[40:43], v[212:215], v[172:175], v[40:43]
	v_mfma_f32_16x16x32_bf16 v[32:35], v[204:207], v[180:183], v[32:35]
	v_mfma_f32_16x16x32_bf16 v[24:27], v[212:215], v[180:183], v[24:27]
	v_mfma_f32_16x16x32_bf16 v[16:19], v[204:207], v[188:191], v[16:19]
	v_mfma_f32_16x16x32_bf16 v[8:11], v[212:215], v[188:191], v[8:11]
	v_mfma_f32_16x16x32_bf16 v[4:7], v[204:207], v[196:199], v[4:7]
	v_mfma_f32_16x16x32_bf16 v[0:3], v[212:215], v[196:199], v[0:3]
	s_setprio 0
	s_add_i32 s68, 0, 0x18000
	v_add_u32_e32 v164, s68, v143
	s_barrier
	ds_read_b128 v[148:151], v164
	ds_read_b128 v[152:155], v164 offset:1024
	ds_read_b128 v[160:163], v164 offset:2048
	ds_read_b128 v[164:167], v164 offset:3072
	s_add_u32 s42, s48, 0x160000
	s_addc_u32 s43, s49, 0
	s_mov_b32 m0, s33
	ds_read_b128 v[168:171], v146 offset:32768
	ds_read_b128 v[172:175], v146 offset:33792
	ds_read_b128 v[176:179], v146 offset:34816
	ds_read_b128 v[180:183], v146 offset:35840
	ds_read_b128 v[184:187], v146 offset:36864
	ds_read_b128 v[188:191], v146 offset:37888
	ds_read_b128 v[192:195], v146 offset:38912
	ds_read_b128 v[196:199], v146 offset:39936
	global_load_lds_dwordx4 v134, s[42:43]
	s_mov_b32 m0, s50
	s_nop 0
	global_load_lds_dwordx4 v130, s[42:43]
	s_waitcnt lgkmcnt(8)
	s_barrier
	s_waitcnt lgkmcnt(0)
	s_setprio 1
	s_waitcnt lgkmcnt(0)
	v_mfma_f32_16x16x32_bf16 v[124:127], v[148:151], v[168:171], v[124:127]
	v_mfma_f32_16x16x32_bf16 v[120:123], v[160:163], v[168:171], v[120:123]
	v_mfma_f32_16x16x32_bf16 v[112:115], v[148:151], v[176:179], v[112:115]
	v_mfma_f32_16x16x32_bf16 v[104:107], v[160:163], v[176:179], v[104:107]
	v_mfma_f32_16x16x32_bf16 v[96:99], v[148:151], v[184:187], v[96:99]
	v_mfma_f32_16x16x32_bf16 v[88:91], v[160:163], v[184:187], v[88:91]
	v_mfma_f32_16x16x32_bf16 v[80:83], v[148:151], v[192:195], v[80:83]
	v_mfma_f32_16x16x32_bf16 v[72:75], v[160:163], v[192:195], v[72:75]
	v_mfma_f32_16x16x32_bf16 v[124:127], v[152:155], v[172:175], v[124:127]
	v_mfma_f32_16x16x32_bf16 v[120:123], v[164:167], v[172:175], v[120:123]
	v_mfma_f32_16x16x32_bf16 v[112:115], v[152:155], v[180:183], v[112:115]
	v_mfma_f32_16x16x32_bf16 v[104:107], v[164:167], v[180:183], v[104:107]
	v_mfma_f32_16x16x32_bf16 v[96:99], v[152:155], v[188:191], v[96:99]
	v_mfma_f32_16x16x32_bf16 v[88:91], v[164:167], v[188:191], v[88:91]
	v_mfma_f32_16x16x32_bf16 v[80:83], v[152:155], v[196:199], v[80:83]
	v_mfma_f32_16x16x32_bf16 v[72:75], v[164:167], v[196:199], v[72:75]
	s_setprio 0
	s_barrier
	s_add_i32 s48, 0, 0x1c000
	s_add_i32 s42, s68, s23
	v_add_u32_e32 v212, s48, v143
	v_lshl_add_u64 v[140:141], v[140:141], 0, s[2:3]
	s_mov_b32 m0, s42
	ds_read_b128 v[200:203], v212
	ds_read_b128 v[204:207], v212 offset:1024
	ds_read_b128 v[208:211], v212 offset:2048
	ds_read_b128 v[212:215], v212 offset:3072
	global_load_lds_dwordx4 v[140:141], off
	v_lshl_add_u64 v[140:141], v[156:157], 0, s[2:3]
	s_add_i32 m0, s42, 0x2000
	s_nop 0
	global_load_lds_dwordx4 v[140:141], off
	s_barrier
	s_waitcnt lgkmcnt(0)
	s_setprio 1
	s_waitcnt lgkmcnt(0)
	v_mfma_f32_16x16x32_bf16 v[116:119], v[200:203], v[168:171], v[116:119]
	v_mfma_f32_16x16x32_bf16 v[108:111], v[208:211], v[168:171], v[108:111]
	v_mfma_f32_16x16x32_bf16 v[100:103], v[200:203], v[176:179], v[100:103]
	v_mfma_f32_16x16x32_bf16 v[92:95], v[208:211], v[176:179], v[92:95]
	v_mfma_f32_16x16x32_bf16 v[84:87], v[200:203], v[184:187], v[84:87]
	v_mfma_f32_16x16x32_bf16 v[76:79], v[208:211], v[184:187], v[76:79]
	v_mfma_f32_16x16x32_bf16 v[68:71], v[200:203], v[192:195], v[68:71]
	v_mfma_f32_16x16x32_bf16 v[64:67], v[208:211], v[192:195], v[64:67]
	v_mfma_f32_16x16x32_bf16 v[116:119], v[204:207], v[172:175], v[116:119]
	v_mfma_f32_16x16x32_bf16 v[108:111], v[212:215], v[172:175], v[108:111]
	v_mfma_f32_16x16x32_bf16 v[100:103], v[204:207], v[180:183], v[100:103]
	v_mfma_f32_16x16x32_bf16 v[92:95], v[212:215], v[180:183], v[92:95]
	v_mfma_f32_16x16x32_bf16 v[84:87], v[204:207], v[188:191], v[84:87]
	v_mfma_f32_16x16x32_bf16 v[76:79], v[212:215], v[188:191], v[76:79]
	v_mfma_f32_16x16x32_bf16 v[68:71], v[204:207], v[196:199], v[68:71]
	v_mfma_f32_16x16x32_bf16 v[64:67], v[212:215], v[196:199], v[64:67]
	s_setprio 0
	s_mov_b32 m0, s52
	v_lshl_add_u64 v[140:141], v[216:217], 0, s[2:3]
	s_barrier
	ds_read_b128 v[168:171], v146 offset:49152
	ds_read_b128 v[172:175], v146 offset:50176
	ds_read_b128 v[176:179], v146 offset:51200
	ds_read_b128 v[180:183], v146 offset:52224
	ds_read_b128 v[184:187], v146 offset:53248
	ds_read_b128 v[188:191], v146 offset:54272
	ds_read_b128 v[192:195], v146 offset:55296
	ds_read_b128 v[196:199], v146 offset:56320
	global_load_lds_dwordx4 v[140:141], off
	v_lshl_add_u64 v[140:141], v[218:219], 0, s[2:3]
	s_mov_b32 m0, s53
	s_nop 0
	global_load_lds_dwordx4 v[140:141], off
	s_barrier
; #define PG8_STAGE(bufoff, gbase, voff) do { _Pragma("unroll") for (int _i = 0; _i < 2; ++_i) \
;         __builtin_amdgcn_global_load_lds((const unsigned*)((const char*)(gbase) + (voff)[_i]), (LAS unsigned*)(lds + (bufoff) + ldsw + _i * 8192), 16, 0, 0); } while (0)
; #define PG8_MMA(ai, bj, At, Bt) do { __builtin_amdgcn_s_setprio(1); _Pragma("unroll") for (int m = 0; m < 4; ++m) _Pragma("unroll") for (int n = 0; n < 2; ++n) _Pragma("unroll") for (int k = 0; k < 2; ++k) \
;         acc[ai][bj][m][n] = __builtin_amdgcn_mfma_f32_16x16x32_bf16(Bt[n][k], At[m][k], acc[ai][bj][m][n], 0, 0, 0); __builtin_amdgcn_s_setprio(0); } while (0)
; #define PG8_WAIT_V(n) asm volatile("s_waitcnt vmcnt(" #n ")" ::: "memory")
; #define PG8_WAIT_L(n) asm volatile("s_waitcnt lgkmcnt(" #n ")" ::: "memory")
; #define PG8_BAR __builtin_amdgcn_s_barrier()
; #define PG8_SCHED __builtin_amdgcn_sched_barrier(0)
; template <class Epi>
; __device__ __forceinline__ void gemm_phase(LAS unsigned char* lds, const Gemm g, const StaticOrder& S, const Epi& E) {
;     ...
;         for (int t = 0; t < nt; t += 2) {
;     ...
;             PG8_BAR; PG8_WAIT_L(0); PG8_MMA(1, 0, At, B0); PG8_BAR; PG8_SCHED;
;             PG8_STAGE(PG8_SB(1, 1), b3 + hstep, voffB);
;             PG8_WAIT_V(6); PG8_BAR; PG8_MMA(1, 1, At, B1); PG8_BAR;
	s_waitcnt lgkmcnt(0)
	s_setprio 1
	s_waitcnt lgkmcnt(0)
	v_mfma_f32_16x16x32_bf16 v[60:63], v[148:151], v[168:171], v[60:63]
	v_mfma_f32_16x16x32_bf16 v[56:59], v[160:163], v[168:171], v[56:59]
	v_mfma_f32_16x16x32_bf16 v[52:55], v[148:151], v[176:179], v[52:55]
	v_mfma_f32_16x16x32_bf16 v[44:47], v[160:163], v[176:179], v[44:47]
	v_mfma_f32_16x16x32_bf16 v[36:39], v[148:151], v[184:187], v[36:39]
	v_mfma_f32_16x16x32_bf16 v[28:31], v[160:163], v[184:187], v[28:31]
	v_mfma_f32_16x16x32_bf16 v[20:23], v[148:151], v[192:195], v[20:23]
	v_mfma_f32_16x16x32_bf16 v[12:15], v[160:163], v[192:195], v[12:15]
	v_mfma_f32_16x16x32_bf16 v[60:63], v[152:155], v[172:175], v[60:63]
	v_mfma_f32_16x16x32_bf16 v[56:59], v[164:167], v[172:175], v[56:59]
	v_mfma_f32_16x16x32_bf16 v[52:55], v[152:155], v[180:183], v[52:55]
	v_mfma_f32_16x16x32_bf16 v[44:47], v[164:167], v[180:183], v[44:47]
	v_mfma_f32_16x16x32_bf16 v[36:39], v[152:155], v[188:191], v[36:39]
	v_mfma_f32_16x16x32_bf16 v[28:31], v[164:167], v[188:191], v[28:31]
	v_mfma_f32_16x16x32_bf16 v[20:23], v[152:155], v[196:199], v[20:23]
	v_mfma_f32_16x16x32_bf16 v[12:15], v[164:167], v[196:199], v[12:15]
	s_setprio 0
	s_barrier
	s_add_u32 s42, s46, 0x160080
	s_addc_u32 s43, s47, 0
	s_add_i32 s46, s48, s23
	s_mov_b32 m0, s46
	s_nop 0
	global_load_lds_dwordx4 v132, s[42:43]
	s_add_i32 m0, s46, 0x2000
	s_nop 0
	global_load_lds_dwordx4 v128, s[42:43]
	s_waitcnt vmcnt(6)
	s_barrier
	s_setprio 1
	v_mfma_f32_16x16x32_bf16 v[48:51], v[200:203], v[168:171], v[48:51]
	v_mfma_f32_16x16x32_bf16 v[40:43], v[208:211], v[168:171], v[40:43]
	v_mfma_f32_16x16x32_bf16 v[32:35], v[200:203], v[176:179], v[32:35]
	v_mfma_f32_16x16x32_bf16 v[24:27], v[208:211], v[176:179], v[24:27]
	v_mfma_f32_16x16x32_bf16 v[16:19], v[200:203], v[184:187], v[16:19]
	v_mfma_f32_16x16x32_bf16 v[8:11], v[208:211], v[184:187], v[8:11]
	v_mfma_f32_16x16x32_bf16 v[4:7], v[200:203], v[192:195], v[4:7]
	v_mfma_f32_16x16x32_bf16 v[0:3], v[208:211], v[192:195], v[0:3]
	v_mfma_f32_16x16x32_bf16 v[48:51], v[204:207], v[172:175], v[48:51]
	v_mfma_f32_16x16x32_bf16 v[40:43], v[212:215], v[172:175], v[40:43]
	v_mfma_f32_16x16x32_bf16 v[32:35], v[204:207], v[180:183], v[32:35]
	v_mfma_f32_16x16x32_bf16 v[24:27], v[212:215], v[180:183], v[24:27]
	v_mfma_f32_16x16x32_bf16 v[16:19], v[204:207], v[188:191], v[16:19]
	v_mfma_f32_16x16x32_bf16 v[8:11], v[212:215], v[188:191], v[8:11]
	v_mfma_f32_16x16x32_bf16 v[4:7], v[204:207], v[196:199], v[4:7]
	v_mfma_f32_16x16x32_bf16 v[0:3], v[212:215], v[196:199], v[0:3]
	s_setprio 0
	s_add_i32 s67, s67, 2
	s_add_u32 s65, s65, 0x100
	s_addc_u32 s66, s66, 0
	s_cmpk_gt_u32 s67, 0x55
	s_mov_b64 s[42:43], s[44:45]
	s_barrier
	s_cbranch_scc0 .LBB0_864
; #define PG8_WAIT_V(n) asm volatile("s_waitcnt vmcnt(" #n ")" ::: "memory")
; #define PG8_BAR __builtin_amdgcn_s_barrier()
; __device__ __forceinline__ u32x4 pack8(f32x4 v0, f32x4 v1) { u32x4 w; w.x = cvt_pk_bf16(v0[0], v0[1]); w.y = cvt_pk_bf16(v0[2], v0[3]); w.z = cvt_pk_bf16(v1[0], v1[1]); w.w = cvt_pk_bf16(v1[2], v1[3]); return w; }
; template <class Epi>
; __device__ __forceinline__ void gemm_phase(LAS unsigned char* lds, const Gemm g, const StaticOrder& S, const Epi& E) {
;     ...
;         if (!has_next) break;
; #pragma unroll
;         for (int a = 0; a < 2; ++a)
; #pragma unroll
;             for (int b = 0; b < 2; ++b)
; #pragma unroll
;                 for (int m = 0; m < 4; ++m)
; #pragma unroll
;                     for (int n = 0; n < 2; ++n) acc[a][b][m][n] = (f32x4){0.f, 0.f, 0.f, 0.f};
;         cur = nxt; cA = nA; cB = nB; ++ui;
;     }
;     PG8_WAIT_V(0);
;     if (wr == 0) PG8_BAR;
;     __device__ __forceinline__ void operator()(const f32x4 (&acc)[2][2][4][2], const Unit& u, int wr, int wc, int fr, int fq) const {
;         const int row0 = u.pm * BM + wr * 64 + fr, col0 = u.pn * BM + wc * 32 + 8 * fq;
; #pragma unroll
;         for (int ai = 0; ai < 2; ++ai)
; #pragma unroll
;             for (int m = 0; m < 4; ++m) { bf16_t* rowp = O + (size_t)(row0 + ai * HALF + m * 16) * ldc + col0;
; #pragma unroll
;                 for (int bj = 0; bj < 2; ++bj) *(u32x4*)(rowp + bj * HALF) = pack8(acc[ai][bj][m][0], acc[ai][bj][m][1]); }
	v_lshl_add_u32 v148, s63, 8, v142
	v_lshl_or_b32 v140, s64, 8, v144
	v_ashrrev_i32_e32 v149, 31, v148
	v_ashrrev_i32_e32 v141, 31, v140
	v_lshlrev_b64 v[150:151], 12, v[148:149]
	v_lshl_add_u64 v[150:151], s[24:25], 0, v[150:151]
	v_lshlrev_b64 v[152:153], 1, v[140:141]
	v_lshl_add_u64 v[140:141], v[150:151], 0, v[152:153]
	v_cvt_pk_bf16_f32 v124, v124, v125
	v_cvt_pk_bf16_f32 v125, v126, v127
	v_cvt_pk_bf16_f32 v126, v120, v121
	v_cvt_pk_bf16_f32 v127, v122, v123
	global_store_dwordx4 v[140:141], v[124:127], off
	v_cvt_pk_bf16_f32 v116, v116, v117
	v_cvt_pk_bf16_f32 v117, v118, v119
	v_cvt_pk_bf16_f32 v118, v108, v109
	v_or_b32_e32 v108, 16, v148
	v_ashrrev_i32_e32 v109, 31, v108
	v_lshlrev_b64 v[108:109], 12, v[108:109]
	v_lshl_add_u64 v[108:109], s[24:25], 0, v[108:109]
	v_cvt_pk_bf16_f32 v119, v110, v111
	global_store_dwordx4 v[140:141], v[116:119], off offset:256
	s_mov_b32 s64, s61
	s_mov_b32 s63, s62
	v_lshl_add_u64 v[116:117], v[108:109], 0, v[152:153]
	v_cvt_pk_bf16_f32 v108, v112, v113
	v_cvt_pk_bf16_f32 v109, v114, v115
	v_cvt_pk_bf16_f32 v110, v104, v105
	v_cvt_pk_bf16_f32 v111, v106, v107
	global_store_dwordx4 v[116:117], v[108:111], off
	v_cvt_pk_bf16_f32 v100, v100, v101
	v_cvt_pk_bf16_f32 v101, v102, v103
	v_cvt_pk_bf16_f32 v102, v92, v93
	v_or_b32_e32 v92, 32, v148
	v_ashrrev_i32_e32 v93, 31, v92
	v_lshlrev_b64 v[92:93], 12, v[92:93]
	v_lshl_add_u64 v[92:93], s[24:25], 0, v[92:93]
	v_cvt_pk_bf16_f32 v103, v94, v95
	global_store_dwordx4 v[116:117], v[100:103], off offset:256
	s_mov_b64 s[44:45], s[6:7]
	s_mov_b64 s[42:43], s[40:41]
	v_lshl_add_u64 v[100:101], v[92:93], 0, v[152:153]
	v_cvt_pk_bf16_f32 v92, v96, v97
	v_cvt_pk_bf16_f32 v93, v98, v99
	v_cvt_pk_bf16_f32 v94, v88, v89
	v_cvt_pk_bf16_f32 v95, v90, v91
	global_store_dwordx4 v[100:101], v[92:95], off
	v_cvt_pk_bf16_f32 v84, v84, v85
	v_cvt_pk_bf16_f32 v85, v86, v87
	v_cvt_pk_bf16_f32 v86, v76, v77
	v_or_b32_e32 v76, 48, v148
	v_ashrrev_i32_e32 v77, 31, v76
	v_lshlrev_b64 v[76:77], 12, v[76:77]
	v_lshl_add_u64 v[76:77], s[24:25], 0, v[76:77]
	v_cvt_pk_bf16_f32 v87, v78, v79
	global_store_dwordx4 v[100:101], v[84:87], off offset:256
	s_nop 1
	v_lshl_add_u64 v[84:85], v[76:77], 0, v[152:153]
	v_cvt_pk_bf16_f32 v76, v80, v81
	v_cvt_pk_bf16_f32 v77, v82, v83
	v_cvt_pk_bf16_f32 v78, v72, v73
	v_cvt_pk_bf16_f32 v79, v74, v75
	global_store_dwordx4 v[84:85], v[76:79], off
	v_cvt_pk_bf16_f32 v68, v68, v69
	v_cvt_pk_bf16_f32 v69, v70, v71
	v_cvt_pk_bf16_f32 v70, v64, v65
	v_cvt_pk_bf16_f32 v71, v66, v67
	global_store_dwordx4 v[84:85], v[68:71], off offset:256
	v_cvt_pk_bf16_f32 v60, v60, v61
	v_cvt_pk_bf16_f32 v61, v62, v63
	v_cvt_pk_bf16_f32 v62, v56, v57
	v_add_co_u32_e32 v56, vcc, s57, v140
	v_lshl_add_u64 v[64:65], v[140:141], 0, s[8:9]
	s_nop 0
	v_addc_co_u32_e32 v57, vcc, 0, v141, vcc
	v_cvt_pk_bf16_f32 v63, v58, v59
	global_store_dwordx4 v[56:57], v[60:63], off
	v_cvt_pk_bf16_f32 v48, v48, v49
	v_cvt_pk_bf16_f32 v49, v50, v51
	v_cvt_pk_bf16_f32 v50, v40, v41
	v_cvt_pk_bf16_f32 v51, v42, v43
	global_store_dwordx4 v[64:65], v[48:51], off offset:256
	v_cvt_pk_bf16_f32 v40, v52, v53
	v_cvt_pk_bf16_f32 v41, v54, v55
	v_cvt_pk_bf16_f32 v42, v44, v45
	v_add_co_u32_e32 v44, vcc, s58, v140
	s_nop 0
	v_lshl_add_u64 v[48:49], v[140:141], 0, s[30:31]
	v_addc_co_u32_e32 v45, vcc, 0, v141, vcc
	v_cvt_pk_bf16_f32 v43, v46, v47
	global_store_dwordx4 v[44:45], v[40:43], off
	v_cvt_pk_bf16_f32 v32, v32, v33
	v_cvt_pk_bf16_f32 v33, v34, v35
	v_cvt_pk_bf16_f32 v34, v24, v25
	v_cvt_pk_bf16_f32 v35, v26, v27
	global_store_dwordx4 v[48:49], v[32:35], off offset:256
	v_cvt_pk_bf16_f32 v24, v36, v37
	v_cvt_pk_bf16_f32 v25, v38, v39
	v_cvt_pk_bf16_f32 v26, v28, v29
	v_add_co_u32_e32 v28, vcc, s59, v140
	s_nop 0
	v_lshl_add_u64 v[32:33], v[140:141], 0, s[34:35]
	v_addc_co_u32_e32 v29, vcc, 0, v141, vcc
	v_cvt_pk_bf16_f32 v27, v30, v31
	global_store_dwordx4 v[28:29], v[24:27], off
	v_cvt_pk_bf16_f32 v16, v16, v17
	v_cvt_pk_bf16_f32 v17, v18, v19
	v_cvt_pk_bf16_f32 v18, v8, v9
	v_cvt_pk_bf16_f32 v19, v10, v11
	global_store_dwordx4 v[32:33], v[16:19], off offset:256
	v_cvt_pk_bf16_f32 v8, v20, v21
	v_cvt_pk_bf16_f32 v9, v22, v23
	v_cvt_pk_bf16_f32 v10, v12, v13
	v_add_co_u32_e32 v12, vcc, s60, v140
	s_nop 0
	v_lshl_add_u64 v[16:17], v[140:141], 0, s[36:37]
	v_addc_co_u32_e32 v13, vcc, 0, v141, vcc
	s_and_b64 vcc, exec, s[38:39]
	v_cvt_pk_bf16_f32 v11, v14, v15
	global_store_dwordx4 v[12:13], v[8:11], off
	v_cvt_pk_bf16_f32 v4, v4, v5
	v_cvt_pk_bf16_f32 v5, v6, v7
	v_cvt_pk_bf16_f32 v6, v0, v1
	v_cvt_pk_bf16_f32 v7, v2, v3
	global_store_dwordx4 v[16:17], v[4:7], off offset:256
	s_cbranch_vccz .LBB0_857
	s_waitcnt vmcnt(0)
	s_cmpk_gt_u32 s10, 0xff
	v_readlane_b32 s62, v232, 20
	v_readlane_b32 s61, v232, 21
	s_cbranch_scc1 .LBB0_868
	s_barrier

; #define PG8_STAGE(bufoff, gbase, voff) do { _Pragma("unroll") for (int _i = 0; _i < 2; ++_i) \
;         __builtin_amdgcn_global_load_lds((const unsigned*)((const char*)(gbase) + (voff)[_i]), (LAS unsigned*)(lds + (bufoff) + ldsw + _i * 8192), 16, 0, 0); } while (0)
; #define PG8_LDA(dst, b, h) do { _Pragma("unroll") for (int m = 0; m < 4; ++m) _Pragma("unroll") for (int k = 0; k < 2; ++k) dst[m][k] = *(const LAS bf16x8*)(lds + PG8_SA(b, h) + aoff + m * 2048 + k * 1024); } while (0)
; #define PG8_LDB(dst, b, h) do { _Pragma("unroll") for (int n = 0; n < 2; ++n) _Pragma("unroll") for (int k = 0; k < 2; ++k) dst[n][k] = *(const LAS bf16x8*)(lds + PG8_SB(b, h) + boff + n * 2048 + k * 1024); } while (0)
; #define PG8_MMA(ai, bj, At, Bt) do { __builtin_amdgcn_s_setprio(1); _Pragma("unroll") for (int m = 0; m < 4; ++m) _Pragma("unroll") for (int n = 0; n < 2; ++n) _Pragma("unroll") for (int k = 0; k < 2; ++k) \
;         acc[ai][bj][m][n] = __builtin_amdgcn_mfma_f32_16x16x32_bf16(Bt[n][k], At[m][k], acc[ai][bj][m][n], 0, 0, 0); __builtin_amdgcn_s_setprio(0); } while (0)
; #define PG8_WAIT_V(n) asm volatile("s_waitcnt vmcnt(" #n ")" ::: "memory")
; #define PG8_WAIT_L(n) asm volatile("s_waitcnt lgkmcnt(" #n ")" ::: "memory")
; #define PG8_BAR __builtin_amdgcn_s_barrier()
; #define PG8_SCHED __builtin_amdgcn_sched_barrier(0)
; template <class Epi>
; __device__ __forceinline__ void gemm_phase(LAS unsigned char* lds, const Gemm g, const StaticOrder& S, const Epi& E) {
;     ...
;             PG8_LDB(B0, 0, 0); PG8_SCHED; PG8_LDA(At, 0, 0); PG8_STAGE(PG8_SA(1, 1), a1 + hstep, voffA);
;             PG8_WAIT_L(8); PG8_BAR; PG8_WAIT_L(0); PG8_MMA(0, 0, At, B0); PG8_BAR; PG8_SCHED;
;             PG8_LDB(B1, 0, 1); PG8_STAGE(PG8_SB(0, 0), b2, voffB);
;             PG8_BAR; PG8_WAIT_L(0); PG8_MMA(0, 1, At, B1); PG8_BAR;
;             PG8_LDA(At, 0, 1); PG8_STAGE(PG8_SA(0, 0), a2, voffA);
;             PG8_BAR; PG8_WAIT_L(0); PG8_MMA(1, 0, At, B0); PG8_BAR; PG8_SCHED;
;             PG8_STAGE(PG8_SB(0, 1), b2 + hstep, voffB);
;             PG8_WAIT_V(6); PG8_BAR; PG8_MMA(1, 1, At, B1); PG8_BAR;
.LBB0_999:
	ds_read_b128 v[140:143], v151
	ds_read_b128 v[144:147], v151 offset:1024
	ds_read_b128 v[154:157], v151 offset:2048
	ds_read_b128 v[160:163], v151 offset:3072
	s_add_u32 s48, s46, 0xfff80080
	s_addc_u32 s49, s47, -1
	s_cmp_eq_u32 s63, 28
	s_cselect_b32 s51, s37, s49
	s_cselect_b32 s50, s59, s48
	s_cselect_b32 s49, s35, s62
	s_cselect_b32 s48, s60, s61
	s_add_i32 m0, s28, 0xc000
	ds_read_b128 v[164:167], v152
	ds_read_b128 v[168:171], v152 offset:1024
	ds_read_b128 v[172:175], v152 offset:2048
	ds_read_b128 v[176:179], v152 offset:3072
	ds_read_b128 v[180:183], v152 offset:4096
	ds_read_b128 v[184:187], v152 offset:5120
	ds_read_b128 v[188:191], v152 offset:6144
	ds_read_b128 v[192:195], v152 offset:7168
	global_load_lds_dwordx4 v136, s[46:47]
	s_add_i32 m0, s28, 0xe000
	s_nop 0
	global_load_lds_dwordx4 v138, s[46:47]
	s_waitcnt lgkmcnt(8)
	s_barrier
	s_waitcnt lgkmcnt(0)
	s_setprio 1
	s_waitcnt lgkmcnt(0)
	v_mfma_f32_16x16x32_bf16 v[124:127], v[140:143], v[164:167], v[124:127]
	v_mfma_f32_16x16x32_bf16 v[120:123], v[154:157], v[164:167], v[120:123]
	v_mfma_f32_16x16x32_bf16 v[108:111], v[140:143], v[172:175], v[108:111]
	v_mfma_f32_16x16x32_bf16 v[104:107], v[154:157], v[172:175], v[104:107]
	v_mfma_f32_16x16x32_bf16 v[92:95], v[140:143], v[180:183], v[92:95]
	v_mfma_f32_16x16x32_bf16 v[88:91], v[154:157], v[180:183], v[88:91]
	v_mfma_f32_16x16x32_bf16 v[76:79], v[140:143], v[188:191], v[76:79]
	v_mfma_f32_16x16x32_bf16 v[72:75], v[154:157], v[188:191], v[72:75]
	v_mfma_f32_16x16x32_bf16 v[124:127], v[144:147], v[168:171], v[124:127]
	v_mfma_f32_16x16x32_bf16 v[120:123], v[160:163], v[168:171], v[120:123]
	v_mfma_f32_16x16x32_bf16 v[108:111], v[144:147], v[176:179], v[108:111]
	v_mfma_f32_16x16x32_bf16 v[104:107], v[160:163], v[176:179], v[104:107]
	v_mfma_f32_16x16x32_bf16 v[92:95], v[144:147], v[184:187], v[92:95]
	v_mfma_f32_16x16x32_bf16 v[88:91], v[160:163], v[184:187], v[88:91]
	v_mfma_f32_16x16x32_bf16 v[76:79], v[144:147], v[192:195], v[76:79]
	v_mfma_f32_16x16x32_bf16 v[72:75], v[160:163], v[192:195], v[72:75]
	s_setprio 0
	s_barrier
	s_add_i32 s64, s56, s23
	v_lshl_add_u64 v[212:213], s[48:49], 0, v[132:133]
	s_mov_b32 m0, s64
	ds_read_b128 v[196:199], v153
	ds_read_b128 v[200:203], v153 offset:1024
	ds_read_b128 v[204:207], v153 offset:2048
	ds_read_b128 v[208:211], v153 offset:3072
	global_load_lds_dwordx4 v132, s[48:49]
	v_lshl_add_u64 v[214:215], s[48:49], 0, v[128:129]
	s_add_i32 m0, s64, 0x2000
	s_nop 0
	global_load_lds_dwordx4 v128, s[48:49]
	s_barrier
	s_waitcnt lgkmcnt(0)
	s_setprio 1
	s_waitcnt lgkmcnt(0)
	v_mfma_f32_16x16x32_bf16 v[116:119], v[196:199], v[164:167], v[116:119]
	v_mfma_f32_16x16x32_bf16 v[112:115], v[204:207], v[164:167], v[112:115]
	v_mfma_f32_16x16x32_bf16 v[100:103], v[196:199], v[172:175], v[100:103]
	v_mfma_f32_16x16x32_bf16 v[96:99], v[204:207], v[172:175], v[96:99]
	v_mfma_f32_16x16x32_bf16 v[84:87], v[196:199], v[180:183], v[84:87]
	v_mfma_f32_16x16x32_bf16 v[80:83], v[204:207], v[180:183], v[80:83]
	v_mfma_f32_16x16x32_bf16 v[68:71], v[196:199], v[188:191], v[68:71]
	v_mfma_f32_16x16x32_bf16 v[64:67], v[204:207], v[188:191], v[64:67]
	v_mfma_f32_16x16x32_bf16 v[116:119], v[200:203], v[168:171], v[116:119]
	v_mfma_f32_16x16x32_bf16 v[112:115], v[208:211], v[168:171], v[112:115]
	v_mfma_f32_16x16x32_bf16 v[100:103], v[200:203], v[176:179], v[100:103]
	v_mfma_f32_16x16x32_bf16 v[96:99], v[208:211], v[176:179], v[96:99]
	v_mfma_f32_16x16x32_bf16 v[84:87], v[200:203], v[184:187], v[84:87]
	v_mfma_f32_16x16x32_bf16 v[80:83], v[208:211], v[184:187], v[80:83]
	v_mfma_f32_16x16x32_bf16 v[68:71], v[200:203], v[192:195], v[68:71]
	v_mfma_f32_16x16x32_bf16 v[64:67], v[208:211], v[192:195], v[64:67]
	s_setprio 0
	s_mov_b32 m0, s28
	v_lshl_add_u64 v[216:217], s[50:51], 0, v[134:135]
	s_barrier
	ds_read_b128 v[164:167], v152 offset:16384
	ds_read_b128 v[168:171], v152 offset:17408
	ds_read_b128 v[172:175], v152 offset:18432
	ds_read_b128 v[176:179], v152 offset:19456
	ds_read_b128 v[180:183], v152 offset:20480
	ds_read_b128 v[184:187], v152 offset:21504
	ds_read_b128 v[188:191], v152 offset:22528
	ds_read_b128 v[192:195], v152 offset:23552
	global_load_lds_dwordx4 v134, s[50:51]
	v_lshl_add_u64 v[218:219], s[50:51], 0, v[130:131]
	s_mov_b32 m0, s29
	s_nop 0
	global_load_lds_dwordx4 v130, s[50:51]
	s_barrier
	s_waitcnt lgkmcnt(0)
	s_setprio 1
	s_waitcnt lgkmcnt(0)
	v_mfma_f32_16x16x32_bf16 v[60:63], v[140:143], v[164:167], v[60:63]
	v_mfma_f32_16x16x32_bf16 v[56:59], v[154:157], v[164:167], v[56:59]
	v_mfma_f32_16x16x32_bf16 v[44:47], v[140:143], v[172:175], v[44:47]
	v_mfma_f32_16x16x32_bf16 v[40:43], v[154:157], v[172:175], v[40:43]
	v_mfma_f32_16x16x32_bf16 v[28:31], v[140:143], v[180:183], v[28:31]
	v_mfma_f32_16x16x32_bf16 v[24:27], v[154:157], v[180:183], v[24:27]
	v_mfma_f32_16x16x32_bf16 v[12:15], v[140:143], v[188:191], v[12:15]
	v_mfma_f32_16x16x32_bf16 v[8:11], v[154:157], v[188:191], v[8:11]
	v_mfma_f32_16x16x32_bf16 v[60:63], v[144:147], v[168:171], v[60:63]
	v_mfma_f32_16x16x32_bf16 v[56:59], v[160:163], v[168:171], v[56:59]
	v_mfma_f32_16x16x32_bf16 v[44:47], v[144:147], v[176:179], v[44:47]
	v_mfma_f32_16x16x32_bf16 v[40:43], v[160:163], v[176:179], v[40:43]
	v_mfma_f32_16x16x32_bf16 v[28:31], v[144:147], v[184:187], v[28:31]
	v_mfma_f32_16x16x32_bf16 v[24:27], v[160:163], v[184:187], v[24:27]
	v_mfma_f32_16x16x32_bf16 v[12:15], v[144:147], v[192:195], v[12:15]
	v_mfma_f32_16x16x32_bf16 v[8:11], v[160:163], v[192:195], v[8:11]
	s_setprio 0
	s_barrier
	s_add_u32 s64, s48, 0x80000
	s_addc_u32 s65, s49, 0
	s_add_i32 s66, s57, s23
	s_mov_b32 m0, s66
	s_nop 0
	global_load_lds_dwordx4 v132, s[64:65]
	s_add_i32 m0, s66, 0x2000
	s_nop 0
	global_load_lds_dwordx4 v128, s[64:65]
	s_waitcnt vmcnt(6)
	s_barrier
; #define PG8_STAGE(bufoff, gbase, voff) do { _Pragma("unroll") for (int _i = 0; _i < 2; ++_i) \
;         __builtin_amdgcn_global_load_lds((const unsigned*)((const char*)(gbase) + (voff)[_i]), (LAS unsigned*)(lds + (bufoff) + ldsw + _i * 8192), 16, 0, 0); } while (0)
; #define PG8_LDA(dst, b, h) do { _Pragma("unroll") for (int m = 0; m < 4; ++m) _Pragma("unroll") for (int k = 0; k < 2; ++k) dst[m][k] = *(const LAS bf16x8*)(lds + PG8_SA(b, h) + aoff + m * 2048 + k * 1024); } while (0)
; #define PG8_LDB(dst, b, h) do { _Pragma("unroll") for (int n = 0; n < 2; ++n) _Pragma("unroll") for (int k = 0; k < 2; ++k) dst[n][k] = *(const LAS bf16x8*)(lds + PG8_SB(b, h) + boff + n * 2048 + k * 1024); } while (0)
; #define PG8_MMA(ai, bj, At, Bt) do { __builtin_amdgcn_s_setprio(1); _Pragma("unroll") for (int m = 0; m < 4; ++m) _Pragma("unroll") for (int n = 0; n < 2; ++n) _Pragma("unroll") for (int k = 0; k < 2; ++k) \
;         acc[ai][bj][m][n] = __builtin_amdgcn_mfma_f32_16x16x32_bf16(Bt[n][k], At[m][k], acc[ai][bj][m][n], 0, 0, 0); __builtin_amdgcn_s_setprio(0); } while (0)
; #define PG8_WAIT_V(n) asm volatile("s_waitcnt vmcnt(" #n ")" ::: "memory")
; #define PG8_WAIT_L(n) asm volatile("s_waitcnt lgkmcnt(" #n ")" ::: "memory")
; #define PG8_BAR __builtin_amdgcn_s_barrier()
; #define PG8_SCHED __builtin_amdgcn_sched_barrier(0)
; template <class Epi>
; __device__ __forceinline__ void gemm_phase(LAS unsigned char* lds, const Gemm g, const StaticOrder& S, const Epi& E) {
;     ...
;             PG8_WAIT_V(6); PG8_BAR; PG8_MMA(1, 1, At, B1); PG8_BAR;
;             PG8_LDB(B0, 1, 0); PG8_SCHED; PG8_LDA(At, 1, 0); PG8_STAGE(PG8_SA(0, 1), a2 + hstep, voffA);
;             PG8_WAIT_L(8); PG8_BAR; PG8_WAIT_L(0); PG8_MMA(0, 0, At, B0); PG8_BAR; PG8_SCHED;
;             PG8_LDB(B1, 1, 1); PG8_STAGE(PG8_SB(1, 0), b3, voffB);
;             PG8_BAR; PG8_WAIT_L(0); PG8_MMA(0, 1, At, B1); PG8_BAR;
;             PG8_LDA(At, 1, 1); PG8_STAGE(PG8_SA(1, 0), a3, voffA);
	s_setprio 1
	v_mfma_f32_16x16x32_bf16 v[52:55], v[196:199], v[164:167], v[52:55]
	v_mfma_f32_16x16x32_bf16 v[48:51], v[204:207], v[164:167], v[48:51]
	v_mfma_f32_16x16x32_bf16 v[36:39], v[196:199], v[172:175], v[36:39]
	v_mfma_f32_16x16x32_bf16 v[32:35], v[204:207], v[172:175], v[32:35]
	v_mfma_f32_16x16x32_bf16 v[20:23], v[196:199], v[180:183], v[20:23]
	v_mfma_f32_16x16x32_bf16 v[16:19], v[204:207], v[180:183], v[16:19]
	v_mfma_f32_16x16x32_bf16 v[4:7], v[196:199], v[188:191], v[4:7]
	v_mfma_f32_16x16x32_bf16 v[0:3], v[204:207], v[188:191], v[0:3]
	v_mfma_f32_16x16x32_bf16 v[52:55], v[200:203], v[168:171], v[52:55]
	v_mfma_f32_16x16x32_bf16 v[48:51], v[208:211], v[168:171], v[48:51]
	v_mfma_f32_16x16x32_bf16 v[36:39], v[200:203], v[176:179], v[36:39]
	v_mfma_f32_16x16x32_bf16 v[32:35], v[208:211], v[176:179], v[32:35]
	v_mfma_f32_16x16x32_bf16 v[20:23], v[200:203], v[184:187], v[20:23]
	v_mfma_f32_16x16x32_bf16 v[16:19], v[208:211], v[184:187], v[16:19]
	v_mfma_f32_16x16x32_bf16 v[4:7], v[200:203], v[192:195], v[4:7]
	v_mfma_f32_16x16x32_bf16 v[0:3], v[208:211], v[192:195], v[0:3]
	s_setprio 0
	s_add_i32 s64, 0, 0x18000
	v_add_u32_e32 v160, s64, v149
	s_barrier
	ds_read_b128 v[140:143], v160
	ds_read_b128 v[144:147], v160 offset:1024
	ds_read_b128 v[154:157], v160 offset:2048
	ds_read_b128 v[160:163], v160 offset:3072
	s_add_u32 s50, s50, 0x80000
	s_addc_u32 s51, s51, 0
	s_mov_b32 m0, s33
	ds_read_b128 v[164:167], v152 offset:32768
	ds_read_b128 v[168:171], v152 offset:33792
	ds_read_b128 v[172:175], v152 offset:34816
	ds_read_b128 v[176:179], v152 offset:35840
	ds_read_b128 v[180:183], v152 offset:36864
	ds_read_b128 v[184:187], v152 offset:37888
	ds_read_b128 v[188:191], v152 offset:38912
	ds_read_b128 v[192:195], v152 offset:39936
	global_load_lds_dwordx4 v134, s[50:51]
	s_mov_b32 m0, s45
	s_nop 0
	global_load_lds_dwordx4 v130, s[50:51]
	s_waitcnt lgkmcnt(8)
	s_barrier
	s_waitcnt lgkmcnt(0)
	s_setprio 1
	s_waitcnt lgkmcnt(0)
	v_mfma_f32_16x16x32_bf16 v[124:127], v[140:143], v[164:167], v[124:127]
	v_mfma_f32_16x16x32_bf16 v[120:123], v[154:157], v[164:167], v[120:123]
	v_mfma_f32_16x16x32_bf16 v[108:111], v[140:143], v[172:175], v[108:111]
	v_mfma_f32_16x16x32_bf16 v[104:107], v[154:157], v[172:175], v[104:107]
	v_mfma_f32_16x16x32_bf16 v[92:95], v[140:143], v[180:183], v[92:95]
	v_mfma_f32_16x16x32_bf16 v[88:91], v[154:157], v[180:183], v[88:91]
	v_mfma_f32_16x16x32_bf16 v[76:79], v[140:143], v[188:191], v[76:79]
	v_mfma_f32_16x16x32_bf16 v[72:75], v[154:157], v[188:191], v[72:75]
	v_mfma_f32_16x16x32_bf16 v[124:127], v[144:147], v[168:171], v[124:127]
	v_mfma_f32_16x16x32_bf16 v[120:123], v[160:163], v[168:171], v[120:123]
	v_mfma_f32_16x16x32_bf16 v[108:111], v[144:147], v[176:179], v[108:111]
	v_mfma_f32_16x16x32_bf16 v[104:107], v[160:163], v[176:179], v[104:107]
	v_mfma_f32_16x16x32_bf16 v[92:95], v[144:147], v[184:187], v[92:95]
	v_mfma_f32_16x16x32_bf16 v[88:91], v[160:163], v[184:187], v[88:91]
	v_mfma_f32_16x16x32_bf16 v[76:79], v[144:147], v[192:195], v[76:79]
	v_mfma_f32_16x16x32_bf16 v[72:75], v[160:163], v[192:195], v[72:75]
	s_setprio 0
	s_barrier
	s_add_i32 s50, 0, 0x1c000
	s_add_i32 s51, s64, s23
	v_add_u32_e32 v208, s50, v149
	v_lshl_add_u64 v[212:213], v[212:213], 0, s[4:5]
	s_mov_b32 m0, s51
	ds_read_b128 v[196:199], v208
	ds_read_b128 v[200:203], v208 offset:1024
	ds_read_b128 v[204:207], v208 offset:2048
	ds_read_b128 v[208:211], v208 offset:3072
	global_load_lds_dwordx4 v[212:213], off
	v_lshl_add_u64 v[212:213], v[214:215], 0, s[4:5]
	s_add_i32 m0, s51, 0x2000
	s_nop 0
	global_load_lds_dwordx4 v[212:213], off
	s_barrier
	s_waitcnt lgkmcnt(0)
	s_setprio 1
	s_waitcnt lgkmcnt(0)
	v_mfma_f32_16x16x32_bf16 v[116:119], v[196:199], v[164:167], v[116:119]
	v_mfma_f32_16x16x32_bf16 v[112:115], v[204:207], v[164:167], v[112:115]
	v_mfma_f32_16x16x32_bf16 v[100:103], v[196:199], v[172:175], v[100:103]
	v_mfma_f32_16x16x32_bf16 v[96:99], v[204:207], v[172:175], v[96:99]
	v_mfma_f32_16x16x32_bf16 v[84:87], v[196:199], v[180:183], v[84:87]
	v_mfma_f32_16x16x32_bf16 v[80:83], v[204:207], v[180:183], v[80:83]
	v_mfma_f32_16x16x32_bf16 v[68:71], v[196:199], v[188:191], v[68:71]
	v_mfma_f32_16x16x32_bf16 v[64:67], v[204:207], v[188:191], v[64:67]
	v_mfma_f32_16x16x32_bf16 v[116:119], v[200:203], v[168:171], v[116:119]
	v_mfma_f32_16x16x32_bf16 v[112:115], v[208:211], v[168:171], v[112:115]
	v_mfma_f32_16x16x32_bf16 v[100:103], v[200:203], v[176:179], v[100:103]
	v_mfma_f32_16x16x32_bf16 v[96:99], v[208:211], v[176:179], v[96:99]
	v_mfma_f32_16x16x32_bf16 v[84:87], v[200:203], v[184:187], v[84:87]
	v_mfma_f32_16x16x32_bf16 v[80:83], v[208:211], v[184:187], v[80:83]
	v_mfma_f32_16x16x32_bf16 v[68:71], v[200:203], v[192:195], v[68:71]
	v_mfma_f32_16x16x32_bf16 v[64:67], v[208:211], v[192:195], v[64:67]
	s_setprio 0
	s_mov_b32 m0, s53
	v_lshl_add_u64 v[212:213], v[216:217], 0, s[4:5]
	s_barrier
	ds_read_b128 v[164:167], v152 offset:49152
	ds_read_b128 v[168:171], v152 offset:50176
	ds_read_b128 v[172:175], v152 offset:51200
	ds_read_b128 v[176:179], v152 offset:52224
	ds_read_b128 v[180:183], v152 offset:53248
	ds_read_b128 v[184:187], v152 offset:54272
	ds_read_b128 v[188:191], v152 offset:55296
	ds_read_b128 v[192:195], v152 offset:56320
	global_load_lds_dwordx4 v[212:213], off
	v_lshl_add_u64 v[212:213], v[218:219], 0, s[4:5]
	s_mov_b32 m0, s54
	s_nop 0
	global_load_lds_dwordx4 v[212:213], off
	s_barrier
; __device__ __forceinline__ float bf_lo(unsigned w) { return __uint_as_float(w << 16); }
; __device__ __forceinline__ float bf_hi(unsigned w) { return __uint_as_float(w & 0xffff0000u); }
; __device__ __forceinline__ float fast_rcp(float x) { return __builtin_amdgcn_rcpf(x); }
; __device__ __forceinline__ float fast_exp2(float x) { return __builtin_amdgcn_exp2f(x); }
; #define PG8_STAGE(bufoff, gbase, voff) do { _Pragma("unroll") for (int _i = 0; _i < 2; ++_i) \
;         __builtin_amdgcn_global_load_lds((const unsigned*)((const char*)(gbase) + (voff)[_i]), (LAS unsigned*)(lds + (bufoff) + ldsw + _i * 8192), 16, 0, 0); } while (0)
; #define PG8_WAIT_V(n) asm volatile("s_waitcnt vmcnt(" #n ")" ::: "memory")
; #define PG8_WAIT_L(n) asm volatile("s_waitcnt lgkmcnt(" #n ")" ::: "memory")
; #define PG8_BAR __builtin_amdgcn_s_barrier()
; #define PG8_SCHED __builtin_amdgcn_sched_barrier(0)
; template <class Epi>
; __device__ __forceinline__ void gemm_phase(LAS unsigned char* lds, const Gemm g, const StaticOrder& S, const Epi& E) {
;     ...
;             PG8_BAR; PG8_WAIT_L(0); PG8_MMA(1, 0, At, B0); PG8_BAR; PG8_SCHED;
;             PG8_STAGE(PG8_SB(1, 1), b3 + hstep, voffB);
;             PG8_WAIT_V(6); PG8_BAR; PG8_MMA(1, 1, At, B1); PG8_BAR;
;     __device__ __forceinline__ void operator()(const f32x4 (&acc)[2][2][4][2], const Unit& u, int wr, int wc, int fr, int fq) const {
;         const int row0 = u.pm * BM + wr * 64 + fr, col0 = u.pn * BM + wc * 32 + 8 * fq;
; #pragma unroll
;         for (int ai = 0; ai < 2; ++ai)
; #pragma unroll
;             for (int m = 0; m < 4; ++m) { const size_t ro = (size_t)(row0 + ai * HALF + m * 16) * DM + col0; const float nr = -LOG2E * rs[row0 + ai * HALF + m * 16];
; #pragma unroll
;                 for (int bj = 0; bj < 2; ++bj) {
;                     const u32x4 pw = *(const u32x4*)(PP + ro + bj * HALF);
;                     const float pv[8] = {bf_lo(pw.x), bf_hi(pw.x), bf_lo(pw.y), bf_hi(pw.y), bf_lo(pw.z), bf_hi(pw.z), bf_lo(pw.w), bf_hi(pw.w)};
;                     f32x4 t0, t1;
; #pragma unroll
;                     for (int j = 0; j < 4; ++j) {
;                         t0[j] = fast_rcp(1.0f + fast_exp2(acc[ai][bj][m][0][j] * nr)) * pv[j];
;                         t1[j] = fast_rcp(1.0f + fast_exp2(acc[ai][bj][m][1][j] * nr)) * pv[4 + j]; }
;                     *(u32x4*)(O + ro + bj * HALF) = pack8(t0, t1); } }
	s_waitcnt lgkmcnt(0)
	s_setprio 1
	s_waitcnt lgkmcnt(0)
	v_mfma_f32_16x16x32_bf16 v[60:63], v[140:143], v[164:167], v[60:63]
	v_mfma_f32_16x16x32_bf16 v[56:59], v[154:157], v[164:167], v[56:59]
	v_mfma_f32_16x16x32_bf16 v[44:47], v[140:143], v[172:175], v[44:47]
	v_mfma_f32_16x16x32_bf16 v[40:43], v[154:157], v[172:175], v[40:43]
	v_mfma_f32_16x16x32_bf16 v[28:31], v[140:143], v[180:183], v[28:31]
	v_mfma_f32_16x16x32_bf16 v[24:27], v[154:157], v[180:183], v[24:27]
	v_mfma_f32_16x16x32_bf16 v[12:15], v[140:143], v[188:191], v[12:15]
	v_mfma_f32_16x16x32_bf16 v[8:11], v[154:157], v[188:191], v[8:11]
	v_mfma_f32_16x16x32_bf16 v[60:63], v[144:147], v[168:171], v[60:63]
	v_mfma_f32_16x16x32_bf16 v[56:59], v[160:163], v[168:171], v[56:59]
	v_mfma_f32_16x16x32_bf16 v[44:47], v[144:147], v[176:179], v[44:47]
	v_mfma_f32_16x16x32_bf16 v[40:43], v[160:163], v[176:179], v[40:43]
	v_mfma_f32_16x16x32_bf16 v[28:31], v[144:147], v[184:187], v[28:31]
	v_mfma_f32_16x16x32_bf16 v[24:27], v[160:163], v[184:187], v[24:27]
	v_mfma_f32_16x16x32_bf16 v[12:15], v[144:147], v[192:195], v[12:15]
	v_mfma_f32_16x16x32_bf16 v[8:11], v[160:163], v[192:195], v[8:11]
	s_setprio 0
	s_barrier
	s_add_u32 s48, s48, 0x80080
	s_addc_u32 s49, s49, 0
	s_add_i32 s50, s50, s23
	s_mov_b32 m0, s50
	s_nop 0
	global_load_lds_dwordx4 v132, s[48:49]
	s_add_i32 m0, s50, 0x2000
	s_nop 0
	global_load_lds_dwordx4 v128, s[48:49]
	s_waitcnt vmcnt(6)
	s_barrier
	s_setprio 1
	v_mfma_f32_16x16x32_bf16 v[52:55], v[196:199], v[164:167], v[52:55]
	v_mfma_f32_16x16x32_bf16 v[48:51], v[204:207], v[164:167], v[48:51]
	v_mfma_f32_16x16x32_bf16 v[36:39], v[196:199], v[172:175], v[36:39]
	v_mfma_f32_16x16x32_bf16 v[32:35], v[204:207], v[172:175], v[32:35]
	v_mfma_f32_16x16x32_bf16 v[20:23], v[196:199], v[180:183], v[20:23]
	v_mfma_f32_16x16x32_bf16 v[16:19], v[204:207], v[180:183], v[16:19]
	v_mfma_f32_16x16x32_bf16 v[4:7], v[196:199], v[188:191], v[4:7]
	v_mfma_f32_16x16x32_bf16 v[0:3], v[204:207], v[188:191], v[0:3]
	v_mfma_f32_16x16x32_bf16 v[52:55], v[200:203], v[168:171], v[52:55]
	v_mfma_f32_16x16x32_bf16 v[48:51], v[208:211], v[168:171], v[48:51]
	v_mfma_f32_16x16x32_bf16 v[36:39], v[200:203], v[176:179], v[36:39]
	v_mfma_f32_16x16x32_bf16 v[32:35], v[208:211], v[176:179], v[32:35]
	v_mfma_f32_16x16x32_bf16 v[20:23], v[200:203], v[184:187], v[20:23]
	v_mfma_f32_16x16x32_bf16 v[16:19], v[208:211], v[184:187], v[16:19]
	v_mfma_f32_16x16x32_bf16 v[4:7], v[200:203], v[192:195], v[4:7]
	v_mfma_f32_16x16x32_bf16 v[0:3], v[208:211], v[192:195], v[0:3]
	s_setprio 0
	s_add_i32 s63, s63, 2
	s_add_u32 s46, s46, 0x100
	s_addc_u32 s47, s47, 0
	s_add_u32 s61, s61, 0x100
	s_addc_u32 s62, s62, 0
	s_cmp_gt_u32 s63, 29
	s_barrier
	s_cbranch_scc0 .LBB0_999
	v_lshl_add_u32 v144, s44, 8, v148
	v_ashrrev_i32_e32 v145, 31, v144
	v_lshl_add_u64 v[140:141], v[144:145], 2, s[14:15]
	global_load_dword v164, v[140:141], off
	v_lshl_or_b32 v146, s58, 8, v150
	v_ashrrev_i32_e32 v147, 31, v146
	v_lshlrev_b64 v[142:143], 11, v[144:145]
	v_lshl_add_u64 v[142:143], v[142:143], 0, v[146:147]
	v_lshlrev_b64 v[142:143], 1, v[142:143]
	v_lshl_add_u64 v[160:161], s[20:21], 0, v[142:143]
	global_load_dwordx4 v[154:157], v[160:161], off
	v_lshl_add_u64 v[162:163], s[24:25], 0, v[142:143]
	s_and_b64 vcc, exec, s[38:39]
	s_mov_b32 s58, s34
	s_mov_b32 s44, s36
	s_mov_b64 s[48:49], s[42:43]
	s_mov_b64 s[46:47], s[40:41]
	s_waitcnt vmcnt(0)
	v_mul_f32_e32 v145, 0xbfb8aa3b, v164
	v_mul_f32_e32 v124, v124, v145
	v_mul_f32_e32 v120, v120, v145
	v_mul_f32_e32 v125, v125, v145
	v_mul_f32_e32 v121, v121, v145
	v_mul_f32_e32 v126, v126, v145
	v_mul_f32_e32 v122, v122, v145
	v_mul_f32_e32 v127, v127, v145
	v_mul_f32_e32 v123, v123, v145
	v_exp_f32_e32 v124, v124
	v_exp_f32_e32 v120, v120
	v_exp_f32_e32 v125, v125
	v_exp_f32_e32 v121, v121
	v_exp_f32_e32 v126, v126
	v_exp_f32_e32 v122, v122
	v_exp_f32_e32 v127, v127
	v_exp_f32_e32 v123, v123
	v_add_f32_e32 v124, 1.0, v124
	v_add_f32_e32 v120, 1.0, v120
	v_add_f32_e32 v125, 1.0, v125
	v_add_f32_e32 v121, 1.0, v121
	v_add_f32_e32 v126, 1.0, v126
	v_add_f32_e32 v122, 1.0, v122
	v_add_f32_e32 v127, 1.0, v127
	v_add_f32_e32 v123, 1.0, v123
	v_rcp_f32_e32 v124, v124
	v_rcp_f32_e32 v120, v120
	v_rcp_f32_e32 v125, v125
	v_rcp_f32_e32 v121, v121
	v_rcp_f32_e32 v126, v126
	v_rcp_f32_e32 v122, v122
	v_rcp_f32_e32 v127, v127
	v_rcp_f32_e32 v123, v123
	v_lshlrev_b32_e32 v164, 16, v154
	v_and_b32_e32 v154, 0xffff0000, v154
	v_lshlrev_b32_e32 v165, 16, v155
	v_and_b32_e32 v155, 0xffff0000, v155
	v_lshlrev_b32_e32 v166, 16, v156
	v_and_b32_e32 v156, 0xffff0000, v156
	v_lshlrev_b32_e32 v167, 16, v157
	v_and_b32_e32 v157, 0xffff0000, v157
	v_mul_f32_e32 v124, v124, v164
	v_mul_f32_e32 v164, v120, v166
	v_mul_f32_e32 v120, v125, v154
	v_mul_f32_e32 v125, v121, v156
	v_mul_f32_e32 v121, v126, v165
	v_mul_f32_e32 v126, v122, v167
	v_mul_f32_e32 v122, v127, v155
	v_mul_f32_e32 v123, v123, v157
	v_cvt_pk_bf16_f32 v120, v124, v120
	v_cvt_pk_bf16_f32 v121, v121, v122
	v_cvt_pk_bf16_f32 v122, v164, v125
	v_cvt_pk_bf16_f32 v123, v126, v123
	global_store_dwordx4 v[162:163], v[120:123], off
	global_load_dwordx4 v[120:123], v[160:161], off offset:256
	v_mul_f32_e32 v116, v116, v145
	v_mul_f32_e32 v112, v112, v145
	v_mul_f32_e32 v117, v117, v145
	v_mul_f32_e32 v113, v113, v145
	v_mul_f32_e32 v118, v118, v145
	v_mul_f32_e32 v114, v114, v145
	v_mul_f32_e32 v119, v119, v145
	v_mul_f32_e32 v115, v115, v145
	v_exp_f32_e32 v116, v116
	v_exp_f32_e32 v112, v112
	v_exp_f32_e32 v117, v117
	v_exp_f32_e32 v113, v113
	v_exp_f32_e32 v118, v118
	v_exp_f32_e32 v114, v114
	v_exp_f32_e32 v119, v119
	v_exp_f32_e32 v115, v115
	v_add_f32_e32 v116, 1.0, v116
	v_add_f32_e32 v112, 1.0, v112
	v_add_f32_e32 v117, 1.0, v117
	v_add_f32_e32 v113, 1.0, v113
	v_add_f32_e32 v118, 1.0, v118
	v_add_f32_e32 v114, 1.0, v114
	v_add_f32_e32 v119, 1.0, v119
	v_add_f32_e32 v115, 1.0, v115
	v_rcp_f32_e32 v116, v116
	v_rcp_f32_e32 v112, v112
	v_rcp_f32_e32 v117, v117
	v_rcp_f32_e32 v113, v113
	v_rcp_f32_e32 v118, v118
	v_rcp_f32_e32 v114, v114
	v_rcp_f32_e32 v119, v119
	v_rcp_f32_e32 v115, v115
	v_or_b32_e32 v124, 16, v144
	v_ashrrev_i32_e32 v125, 31, v124
	v_lshlrev_b64 v[124:125], 11, v[124:125]
	v_lshl_add_u64 v[124:125], v[124:125], 0, v[146:147]
	v_lshlrev_b64 v[124:125], 1, v[124:125]
	v_lshl_add_u64 v[126:127], s[20:21], 0, v[124:125]
	s_waitcnt vmcnt(0)
; __device__ __forceinline__ float bf_lo(unsigned w) { return __uint_as_float(w << 16); }
; __device__ __forceinline__ float bf_hi(unsigned w) { return __uint_as_float(w & 0xffff0000u); }
; __device__ __forceinline__ float fast_rcp(float x) { return __builtin_amdgcn_rcpf(x); }
; __device__ __forceinline__ float fast_exp2(float x) { return __builtin_amdgcn_exp2f(x); }
; __device__ __forceinline__ u32x4 pack8(f32x4 v0, f32x4 v1) { u32x4 w; w.x = cvt_pk_bf16(v0[0], v0[1]); w.y = cvt_pk_bf16(v0[2], v0[3]); w.z = cvt_pk_bf16(v1[0], v1[1]); w.w = cvt_pk_bf16(v1[2], v1[3]); return w; }
;     __device__ __forceinline__ void operator()(const f32x4 (&acc)[2][2][4][2], const Unit& u, int wr, int wc, int fr, int fq) const {
;         const int row0 = u.pm * BM + wr * 64 + fr, col0 = u.pn * BM + wc * 32 + 8 * fq;
; #pragma unroll
;         for (int ai = 0; ai < 2; ++ai)
; #pragma unroll
;             for (int m = 0; m < 4; ++m) { const size_t ro = (size_t)(row0 + ai * HALF + m * 16) * DM + col0; const float nr = -LOG2E * rs[row0 + ai * HALF + m * 16];
; #pragma unroll
;                 for (int bj = 0; bj < 2; ++bj) {
;                     const u32x4 pw = *(const u32x4*)(PP + ro + bj * HALF);
;                     const float pv[8] = {bf_lo(pw.x), bf_hi(pw.x), bf_lo(pw.y), bf_hi(pw.y), bf_lo(pw.z), bf_hi(pw.z), bf_lo(pw.w), bf_hi(pw.w)};
;                     f32x4 t0, t1;
; #pragma unroll
;                     for (int j = 0; j < 4; ++j) {
;                         t0[j] = fast_rcp(1.0f + fast_exp2(acc[ai][bj][m][0][j] * nr)) * pv[j];
;                         t1[j] = fast_rcp(1.0f + fast_exp2(acc[ai][bj][m][1][j] * nr)) * pv[4 + j]; }
;                     *(u32x4*)(O + ro + bj * HALF) = pack8(t0, t1); } }
	v_lshlrev_b32_e32 v145, 16, v120
	v_and_b32_e32 v120, 0xffff0000, v120
	v_lshlrev_b32_e32 v154, 16, v121
	v_and_b32_e32 v121, 0xffff0000, v121
	v_lshlrev_b32_e32 v155, 16, v122
	v_and_b32_e32 v122, 0xffff0000, v122
	v_lshlrev_b32_e32 v156, 16, v123
	v_and_b32_e32 v123, 0xffff0000, v123
	v_mul_f32_e32 v116, v116, v145
	v_mul_f32_e32 v145, v112, v155
	v_mul_f32_e32 v112, v117, v120
	v_mul_f32_e32 v117, v113, v122
	v_mul_f32_e32 v113, v118, v154
	v_mul_f32_e32 v118, v114, v156
	v_mul_f32_e32 v114, v119, v121
	v_mul_f32_e32 v115, v115, v123
	v_cvt_pk_bf16_f32 v112, v116, v112
	v_cvt_pk_bf16_f32 v113, v113, v114
	v_cvt_pk_bf16_f32 v114, v145, v117
	v_cvt_pk_bf16_f32 v115, v118, v115
	global_store_dwordx4 v[162:163], v[112:115], off offset:256
	global_load_dword v118, v[140:141], off offset:64
	s_nop 0
	global_load_dwordx4 v[112:115], v[126:127], off
	v_lshl_add_u64 v[116:117], s[24:25], 0, v[124:125]
	s_waitcnt vmcnt(0)
	v_mul_f32_e32 v118, 0xbfb8aa3b, v118
	v_mul_f32_e32 v108, v108, v118
	v_mul_f32_e32 v104, v104, v118
	v_mul_f32_e32 v109, v109, v118
	v_mul_f32_e32 v105, v105, v118
	v_mul_f32_e32 v110, v110, v118
	v_mul_f32_e32 v106, v106, v118
	v_mul_f32_e32 v111, v111, v118
	v_mul_f32_e32 v107, v107, v118
	v_exp_f32_e32 v108, v108
	v_exp_f32_e32 v104, v104
	v_exp_f32_e32 v109, v109
	v_exp_f32_e32 v105, v105
	v_exp_f32_e32 v110, v110
	v_exp_f32_e32 v106, v106
	v_exp_f32_e32 v111, v111
	v_exp_f32_e32 v107, v107
	v_add_f32_e32 v108, 1.0, v108
	v_add_f32_e32 v104, 1.0, v104
	v_add_f32_e32 v109, 1.0, v109
	v_add_f32_e32 v105, 1.0, v105
	v_add_f32_e32 v110, 1.0, v110
	v_add_f32_e32 v106, 1.0, v106
	v_add_f32_e32 v111, 1.0, v111
	v_add_f32_e32 v107, 1.0, v107
	v_rcp_f32_e32 v108, v108
	v_rcp_f32_e32 v104, v104
	v_rcp_f32_e32 v109, v109
	v_rcp_f32_e32 v105, v105
	v_rcp_f32_e32 v110, v110
	v_rcp_f32_e32 v106, v106
	v_rcp_f32_e32 v111, v111
	v_rcp_f32_e32 v107, v107
	v_lshlrev_b32_e32 v119, 16, v112
	v_and_b32_e32 v112, 0xffff0000, v112
	v_lshlrev_b32_e32 v120, 16, v113
	v_and_b32_e32 v113, 0xffff0000, v113
	v_lshlrev_b32_e32 v121, 16, v114
	v_and_b32_e32 v114, 0xffff0000, v114
	v_lshlrev_b32_e32 v122, 16, v115
	v_and_b32_e32 v115, 0xffff0000, v115
	v_mul_f32_e32 v108, v108, v119
	v_mul_f32_e32 v119, v104, v121
	v_mul_f32_e32 v104, v109, v112
	v_mul_f32_e32 v109, v105, v114
	v_mul_f32_e32 v105, v110, v120
	v_mul_f32_e32 v110, v106, v122
	v_mul_f32_e32 v106, v111, v113
	v_mul_f32_e32 v107, v107, v115
	v_cvt_pk_bf16_f32 v104, v108, v104
	v_cvt_pk_bf16_f32 v105, v105, v106
	v_cvt_pk_bf16_f32 v106, v119, v109
	v_cvt_pk_bf16_f32 v107, v110, v107
	global_store_dwordx4 v[116:117], v[104:107], off
	global_load_dwordx4 v[104:107], v[126:127], off offset:256
	v_mul_f32_e32 v100, v100, v118
	v_mul_f32_e32 v96, v96, v118
	v_mul_f32_e32 v101, v101, v118
	v_mul_f32_e32 v97, v97, v118
	v_mul_f32_e32 v102, v102, v118
	v_mul_f32_e32 v98, v98, v118
	v_mul_f32_e32 v103, v103, v118
	v_mul_f32_e32 v99, v99, v118
	v_exp_f32_e32 v100, v100
	v_exp_f32_e32 v96, v96
	v_exp_f32_e32 v101, v101
	v_exp_f32_e32 v97, v97
	v_exp_f32_e32 v102, v102
	v_exp_f32_e32 v98, v98
	v_exp_f32_e32 v103, v103
	v_exp_f32_e32 v99, v99
	v_add_f32_e32 v100, 1.0, v100
	v_add_f32_e32 v96, 1.0, v96
	v_add_f32_e32 v101, 1.0, v101
	v_add_f32_e32 v97, 1.0, v97
	v_add_f32_e32 v102, 1.0, v102
	v_add_f32_e32 v98, 1.0, v98
	v_add_f32_e32 v103, 1.0, v103
	v_add_f32_e32 v99, 1.0, v99
	v_rcp_f32_e32 v100, v100
	v_rcp_f32_e32 v96, v96
	v_rcp_f32_e32 v101, v101
	v_rcp_f32_e32 v97, v97
	v_rcp_f32_e32 v102, v102
	v_rcp_f32_e32 v98, v98
	v_rcp_f32_e32 v103, v103
	v_rcp_f32_e32 v99, v99
	v_or_b32_e32 v108, 32, v144
	v_ashrrev_i32_e32 v109, 31, v108
	v_lshlrev_b64 v[108:109], 11, v[108:109]
	v_lshl_add_u64 v[108:109], v[108:109], 0, v[146:147]
	v_lshlrev_b64 v[108:109], 1, v[108:109]
	v_lshl_add_u64 v[110:111], s[20:21], 0, v[108:109]
	s_waitcnt vmcnt(0)
	v_lshlrev_b32_e32 v112, 16, v104
	v_and_b32_e32 v104, 0xffff0000, v104
	v_lshlrev_b32_e32 v113, 16, v105
	v_and_b32_e32 v105, 0xffff0000, v105
	v_lshlrev_b32_e32 v114, 16, v106
	v_and_b32_e32 v106, 0xffff0000, v106
	v_lshlrev_b32_e32 v115, 16, v107
	v_and_b32_e32 v107, 0xffff0000, v107
	v_mul_f32_e32 v100, v100, v112
	v_mul_f32_e32 v112, v96, v114
	v_mul_f32_e32 v96, v101, v104
	v_mul_f32_e32 v101, v97, v106
	v_mul_f32_e32 v97, v102, v113
	v_mul_f32_e32 v102, v98, v115
	v_mul_f32_e32 v98, v103, v105
	v_mul_f32_e32 v99, v99, v107
	v_cvt_pk_bf16_f32 v96, v100, v96
	v_cvt_pk_bf16_f32 v97, v97, v98
	v_cvt_pk_bf16_f32 v98, v112, v101
	v_cvt_pk_bf16_f32 v99, v102, v99
	global_store_dwordx4 v[116:117], v[96:99], off offset:256
	global_load_dword v102, v[140:141], off offset:128
	s_nop 0
	global_load_dwordx4 v[96:99], v[110:111], off
	v_lshl_add_u64 v[100:101], s[24:25], 0, v[108:109]
	s_waitcnt vmcnt(0)
; __device__ __forceinline__ float bf_lo(unsigned w) { return __uint_as_float(w << 16); }
; __device__ __forceinline__ float bf_hi(unsigned w) { return __uint_as_float(w & 0xffff0000u); }
; __device__ __forceinline__ float fast_rcp(float x) { return __builtin_amdgcn_rcpf(x); }
; __device__ __forceinline__ float fast_exp2(float x) { return __builtin_amdgcn_exp2f(x); }
; __device__ __forceinline__ u32x4 pack8(f32x4 v0, f32x4 v1) { u32x4 w; w.x = cvt_pk_bf16(v0[0], v0[1]); w.y = cvt_pk_bf16(v0[2], v0[3]); w.z = cvt_pk_bf16(v1[0], v1[1]); w.w = cvt_pk_bf16(v1[2], v1[3]); return w; }
;     __device__ __forceinline__ void operator()(const f32x4 (&acc)[2][2][4][2], const Unit& u, int wr, int wc, int fr, int fq) const {
;         const int row0 = u.pm * BM + wr * 64 + fr, col0 = u.pn * BM + wc * 32 + 8 * fq;
; #pragma unroll
;         for (int ai = 0; ai < 2; ++ai)
; #pragma unroll
;             for (int m = 0; m < 4; ++m) { const size_t ro = (size_t)(row0 + ai * HALF + m * 16) * DM + col0; const float nr = -LOG2E * rs[row0 + ai * HALF + m * 16];
; #pragma unroll
;                 for (int bj = 0; bj < 2; ++bj) {
;                     const u32x4 pw = *(const u32x4*)(PP + ro + bj * HALF);
;                     const float pv[8] = {bf_lo(pw.x), bf_hi(pw.x), bf_lo(pw.y), bf_hi(pw.y), bf_lo(pw.z), bf_hi(pw.z), bf_lo(pw.w), bf_hi(pw.w)};
;                     f32x4 t0, t1;
; #pragma unroll
;                     for (int j = 0; j < 4; ++j) {
;                         t0[j] = fast_rcp(1.0f + fast_exp2(acc[ai][bj][m][0][j] * nr)) * pv[j];
;                         t1[j] = fast_rcp(1.0f + fast_exp2(acc[ai][bj][m][1][j] * nr)) * pv[4 + j]; }
;                     *(u32x4*)(O + ro + bj * HALF) = pack8(t0, t1); } }
	v_mul_f32_e32 v102, 0xbfb8aa3b, v102
	v_mul_f32_e32 v92, v92, v102
	v_mul_f32_e32 v88, v88, v102
	v_mul_f32_e32 v93, v93, v102
	v_mul_f32_e32 v89, v89, v102
	v_mul_f32_e32 v94, v94, v102
	v_mul_f32_e32 v90, v90, v102
	v_mul_f32_e32 v95, v95, v102
	v_mul_f32_e32 v91, v91, v102
	v_exp_f32_e32 v92, v92
	v_exp_f32_e32 v88, v88
	v_exp_f32_e32 v93, v93
	v_exp_f32_e32 v89, v89
	v_exp_f32_e32 v94, v94
	v_exp_f32_e32 v90, v90
	v_exp_f32_e32 v95, v95
	v_exp_f32_e32 v91, v91
	v_add_f32_e32 v92, 1.0, v92
	v_add_f32_e32 v88, 1.0, v88
	v_add_f32_e32 v93, 1.0, v93
	v_add_f32_e32 v89, 1.0, v89
	v_add_f32_e32 v94, 1.0, v94
	v_add_f32_e32 v90, 1.0, v90
	v_add_f32_e32 v95, 1.0, v95
	v_add_f32_e32 v91, 1.0, v91
	v_rcp_f32_e32 v92, v92
	v_rcp_f32_e32 v88, v88
	v_rcp_f32_e32 v93, v93
	v_rcp_f32_e32 v89, v89
	v_rcp_f32_e32 v94, v94
	v_rcp_f32_e32 v90, v90
	v_rcp_f32_e32 v95, v95
	v_rcp_f32_e32 v91, v91
	v_lshlrev_b32_e32 v103, 16, v96
	v_and_b32_e32 v96, 0xffff0000, v96
	v_lshlrev_b32_e32 v104, 16, v97
	v_and_b32_e32 v97, 0xffff0000, v97
	v_lshlrev_b32_e32 v105, 16, v98
	v_and_b32_e32 v98, 0xffff0000, v98
	v_lshlrev_b32_e32 v106, 16, v99
	v_and_b32_e32 v99, 0xffff0000, v99
	v_mul_f32_e32 v92, v92, v103
	v_mul_f32_e32 v103, v88, v105
	v_mul_f32_e32 v88, v93, v96
	v_mul_f32_e32 v93, v89, v98
	v_mul_f32_e32 v89, v94, v104
	v_mul_f32_e32 v94, v90, v106
	v_mul_f32_e32 v90, v95, v97
	v_mul_f32_e32 v91, v91, v99
	v_cvt_pk_bf16_f32 v88, v92, v88
	v_cvt_pk_bf16_f32 v89, v89, v90
	v_cvt_pk_bf16_f32 v90, v103, v93
	v_cvt_pk_bf16_f32 v91, v94, v91
	global_store_dwordx4 v[100:101], v[88:91], off
	global_load_dwordx4 v[88:91], v[110:111], off offset:256
	v_mul_f32_e32 v84, v84, v102
	v_mul_f32_e32 v80, v80, v102
	v_mul_f32_e32 v85, v85, v102
	v_mul_f32_e32 v81, v81, v102
	v_mul_f32_e32 v86, v86, v102
	v_mul_f32_e32 v82, v82, v102
	v_mul_f32_e32 v87, v87, v102
	v_mul_f32_e32 v83, v83, v102
	v_exp_f32_e32 v84, v84
	v_exp_f32_e32 v80, v80
	v_exp_f32_e32 v85, v85
	v_exp_f32_e32 v81, v81
	v_exp_f32_e32 v86, v86
	v_exp_f32_e32 v82, v82
	v_exp_f32_e32 v87, v87
	v_exp_f32_e32 v83, v83
	v_add_f32_e32 v84, 1.0, v84
	v_add_f32_e32 v80, 1.0, v80
	v_add_f32_e32 v85, 1.0, v85
	v_add_f32_e32 v81, 1.0, v81
	v_add_f32_e32 v86, 1.0, v86
	v_add_f32_e32 v82, 1.0, v82
	v_add_f32_e32 v87, 1.0, v87
	v_add_f32_e32 v83, 1.0, v83
	v_rcp_f32_e32 v84, v84
	v_rcp_f32_e32 v80, v80
	v_rcp_f32_e32 v85, v85
	v_rcp_f32_e32 v81, v81
	v_rcp_f32_e32 v86, v86
	v_rcp_f32_e32 v82, v82
	v_rcp_f32_e32 v87, v87
	v_rcp_f32_e32 v83, v83
	v_or_b32_e32 v92, 48, v144
	v_ashrrev_i32_e32 v93, 31, v92
	v_lshlrev_b64 v[92:93], 11, v[92:93]
	v_lshl_add_u64 v[92:93], v[92:93], 0, v[146:147]
	v_lshlrev_b64 v[92:93], 1, v[92:93]
	v_lshl_add_u64 v[94:95], s[20:21], 0, v[92:93]
	s_waitcnt vmcnt(0)
	v_lshlrev_b32_e32 v96, 16, v88
	v_and_b32_e32 v88, 0xffff0000, v88
	v_lshlrev_b32_e32 v97, 16, v89
	v_and_b32_e32 v89, 0xffff0000, v89
	v_lshlrev_b32_e32 v98, 16, v90
	v_and_b32_e32 v90, 0xffff0000, v90
	v_lshlrev_b32_e32 v99, 16, v91
	v_and_b32_e32 v91, 0xffff0000, v91
	v_mul_f32_e32 v84, v84, v96
	v_mul_f32_e32 v96, v80, v98
	v_mul_f32_e32 v80, v85, v88
	v_mul_f32_e32 v85, v81, v90
	v_mul_f32_e32 v81, v86, v97
	v_mul_f32_e32 v86, v82, v99
	v_mul_f32_e32 v82, v87, v89
	v_mul_f32_e32 v83, v83, v91
	v_cvt_pk_bf16_f32 v80, v84, v80
	v_cvt_pk_bf16_f32 v81, v81, v82
	v_cvt_pk_bf16_f32 v82, v96, v85
	v_cvt_pk_bf16_f32 v83, v86, v83
	global_store_dwordx4 v[100:101], v[80:83], off offset:256
	global_load_dword v86, v[140:141], off offset:192
	s_nop 0
	global_load_dwordx4 v[80:83], v[94:95], off
	v_lshl_add_u64 v[84:85], s[24:25], 0, v[92:93]
	s_waitcnt vmcnt(0)
	v_mul_f32_e32 v86, 0xbfb8aa3b, v86
	v_mul_f32_e32 v76, v76, v86
	v_mul_f32_e32 v72, v72, v86
	v_mul_f32_e32 v77, v77, v86
	v_mul_f32_e32 v73, v73, v86
	v_mul_f32_e32 v78, v78, v86
	v_mul_f32_e32 v74, v74, v86
	v_mul_f32_e32 v79, v79, v86
	v_mul_f32_e32 v75, v75, v86
	v_exp_f32_e32 v76, v76
	v_exp_f32_e32 v72, v72
	v_exp_f32_e32 v77, v77
	v_exp_f32_e32 v73, v73
	v_exp_f32_e32 v78, v78
	v_exp_f32_e32 v74, v74
	v_exp_f32_e32 v79, v79
	v_exp_f32_e32 v75, v75
	v_add_f32_e32 v76, 1.0, v76
	v_add_f32_e32 v72, 1.0, v72
	v_add_f32_e32 v77, 1.0, v77
	v_add_f32_e32 v73, 1.0, v73
	v_add_f32_e32 v78, 1.0, v78
	v_add_f32_e32 v74, 1.0, v74
	v_add_f32_e32 v79, 1.0, v79
	v_add_f32_e32 v75, 1.0, v75
	v_rcp_f32_e32 v76, v76
	v_rcp_f32_e32 v72, v72
	v_rcp_f32_e32 v77, v77
	v_rcp_f32_e32 v73, v73
	v_rcp_f32_e32 v78, v78
	v_rcp_f32_e32 v74, v74
	v_rcp_f32_e32 v79, v79
	v_rcp_f32_e32 v75, v75
	v_lshlrev_b32_e32 v87, 16, v80
	v_and_b32_e32 v80, 0xffff0000, v80
	v_lshlrev_b32_e32 v88, 16, v81
	v_and_b32_e32 v81, 0xffff0000, v81
	v_lshlrev_b32_e32 v89, 16, v82
	v_and_b32_e32 v82, 0xffff0000, v82
	v_lshlrev_b32_e32 v90, 16, v83
	v_and_b32_e32 v83, 0xffff0000, v83
	v_mul_f32_e32 v76, v76, v87
	v_mul_f32_e32 v87, v72, v89
	v_mul_f32_e32 v72, v77, v80
	v_mul_f32_e32 v77, v73, v82
	v_mul_f32_e32 v73, v78, v88
	v_mul_f32_e32 v78, v74, v90
	v_mul_f32_e32 v74, v79, v81
	v_mul_f32_e32 v75, v75, v83
	v_cvt_pk_bf16_f32 v72, v76, v72
	v_cvt_pk_bf16_f32 v73, v73, v74
	v_cvt_pk_bf16_f32 v74, v87, v77
	v_cvt_pk_bf16_f32 v75, v78, v75
	global_store_dwordx4 v[84:85], v[72:75], off
	global_load_dwordx4 v[72:75], v[94:95], off offset:256
	v_mul_f32_e32 v68, v68, v86
	v_mul_f32_e32 v64, v64, v86
	v_mul_f32_e32 v69, v69, v86
	v_mul_f32_e32 v65, v65, v86
	v_mul_f32_e32 v70, v70, v86
	v_mul_f32_e32 v66, v66, v86
	v_mul_f32_e32 v71, v71, v86
	v_mul_f32_e32 v67, v67, v86
	v_exp_f32_e32 v68, v68
	v_exp_f32_e32 v64, v64
	v_exp_f32_e32 v69, v69
	v_exp_f32_e32 v65, v65
	v_exp_f32_e32 v70, v70
	v_exp_f32_e32 v66, v66
	v_exp_f32_e32 v71, v71
	v_exp_f32_e32 v67, v67
	v_add_f32_e32 v68, 1.0, v68
	v_add_f32_e32 v64, 1.0, v64
	v_add_f32_e32 v69, 1.0, v69
	v_add_f32_e32 v65, 1.0, v65
	v_add_f32_e32 v70, 1.0, v70
	v_add_f32_e32 v66, 1.0, v66
	v_add_f32_e32 v71, 1.0, v71
	v_add_f32_e32 v67, 1.0, v67
	v_rcp_f32_e32 v68, v68
	v_rcp_f32_e32 v64, v64
	v_rcp_f32_e32 v69, v69
	v_rcp_f32_e32 v65, v65
	v_rcp_f32_e32 v70, v70
	v_rcp_f32_e32 v66, v66
	v_rcp_f32_e32 v71, v71
	v_rcp_f32_e32 v67, v67
	v_lshl_add_u64 v[76:77], v[142:143], 0, s[2:3]
	v_lshl_add_u64 v[78:79], s[20:21], 0, v[76:77]
	s_waitcnt vmcnt(0)
; __device__ __forceinline__ float bf_lo(unsigned w) { return __uint_as_float(w << 16); }
; __device__ __forceinline__ float bf_hi(unsigned w) { return __uint_as_float(w & 0xffff0000u); }
; __device__ __forceinline__ float fast_rcp(float x) { return __builtin_amdgcn_rcpf(x); }
; __device__ __forceinline__ float fast_exp2(float x) { return __builtin_amdgcn_exp2f(x); }
; __device__ __forceinline__ u32x4 pack8(f32x4 v0, f32x4 v1) { u32x4 w; w.x = cvt_pk_bf16(v0[0], v0[1]); w.y = cvt_pk_bf16(v0[2], v0[3]); w.z = cvt_pk_bf16(v1[0], v1[1]); w.w = cvt_pk_bf16(v1[2], v1[3]); return w; }
;     __device__ __forceinline__ void operator()(const f32x4 (&acc)[2][2][4][2], const Unit& u, int wr, int wc, int fr, int fq) const {
;         const int row0 = u.pm * BM + wr * 64 + fr, col0 = u.pn * BM + wc * 32 + 8 * fq;
; #pragma unroll
;         for (int ai = 0; ai < 2; ++ai)
; #pragma unroll
;             for (int m = 0; m < 4; ++m) { const size_t ro = (size_t)(row0 + ai * HALF + m * 16) * DM + col0; const float nr = -LOG2E * rs[row0 + ai * HALF + m * 16];
; #pragma unroll
;                 for (int bj = 0; bj < 2; ++bj) {
;                     const u32x4 pw = *(const u32x4*)(PP + ro + bj * HALF);
;                     const float pv[8] = {bf_lo(pw.x), bf_hi(pw.x), bf_lo(pw.y), bf_hi(pw.y), bf_lo(pw.z), bf_hi(pw.z), bf_lo(pw.w), bf_hi(pw.w)};
;                     f32x4 t0, t1;
; #pragma unroll
;                     for (int j = 0; j < 4; ++j) {
;                         t0[j] = fast_rcp(1.0f + fast_exp2(acc[ai][bj][m][0][j] * nr)) * pv[j];
;                         t1[j] = fast_rcp(1.0f + fast_exp2(acc[ai][bj][m][1][j] * nr)) * pv[4 + j]; }
;                     *(u32x4*)(O + ro + bj * HALF) = pack8(t0, t1); } }
	v_lshlrev_b32_e32 v80, 16, v72
	v_and_b32_e32 v72, 0xffff0000, v72
	v_lshlrev_b32_e32 v81, 16, v73
	v_and_b32_e32 v73, 0xffff0000, v73
	v_lshlrev_b32_e32 v82, 16, v74
	v_and_b32_e32 v74, 0xffff0000, v74
	v_lshlrev_b32_e32 v83, 16, v75
	v_and_b32_e32 v75, 0xffff0000, v75
	v_mul_f32_e32 v68, v68, v80
	v_mul_f32_e32 v80, v64, v82
	v_mul_f32_e32 v64, v69, v72
	v_mul_f32_e32 v69, v65, v74
	v_mul_f32_e32 v65, v70, v81
	v_mul_f32_e32 v70, v66, v83
	v_mul_f32_e32 v66, v71, v73
	v_mul_f32_e32 v67, v67, v75
	v_cvt_pk_bf16_f32 v64, v68, v64
	v_cvt_pk_bf16_f32 v65, v65, v66
	v_cvt_pk_bf16_f32 v66, v80, v69
	v_cvt_pk_bf16_f32 v67, v70, v67
	global_store_dwordx4 v[84:85], v[64:67], off offset:256
	global_load_dword v70, v[140:141], off offset:512
	s_nop 0
	global_load_dwordx4 v[64:67], v[78:79], off
	v_lshl_add_u64 v[68:69], s[24:25], 0, v[76:77]
	s_waitcnt vmcnt(0)
	v_mul_f32_e32 v70, 0xbfb8aa3b, v70
	v_mul_f32_e32 v60, v60, v70
	v_mul_f32_e32 v56, v56, v70
	v_mul_f32_e32 v61, v61, v70
	v_mul_f32_e32 v57, v57, v70
	v_mul_f32_e32 v62, v62, v70
	v_mul_f32_e32 v58, v58, v70
	v_mul_f32_e32 v63, v63, v70
	v_mul_f32_e32 v59, v59, v70
	v_exp_f32_e32 v60, v60
	v_exp_f32_e32 v56, v56
	v_exp_f32_e32 v61, v61
	v_exp_f32_e32 v57, v57
	v_exp_f32_e32 v62, v62
	v_exp_f32_e32 v58, v58
	v_exp_f32_e32 v63, v63
	v_exp_f32_e32 v59, v59
	v_add_f32_e32 v60, 1.0, v60
	v_add_f32_e32 v56, 1.0, v56
	v_add_f32_e32 v61, 1.0, v61
	v_add_f32_e32 v57, 1.0, v57
	v_add_f32_e32 v62, 1.0, v62
	v_add_f32_e32 v58, 1.0, v58
	v_add_f32_e32 v63, 1.0, v63
	v_add_f32_e32 v59, 1.0, v59
	v_rcp_f32_e32 v60, v60
	v_rcp_f32_e32 v56, v56
	v_rcp_f32_e32 v61, v61
	v_rcp_f32_e32 v57, v57
	v_rcp_f32_e32 v62, v62
	v_rcp_f32_e32 v58, v58
	v_rcp_f32_e32 v63, v63
	v_rcp_f32_e32 v59, v59
	v_lshlrev_b32_e32 v71, 16, v64
	v_and_b32_e32 v64, 0xffff0000, v64
	v_lshlrev_b32_e32 v72, 16, v65
	v_and_b32_e32 v65, 0xffff0000, v65
	v_lshlrev_b32_e32 v73, 16, v66
	v_and_b32_e32 v66, 0xffff0000, v66
	v_lshlrev_b32_e32 v74, 16, v67
	v_and_b32_e32 v67, 0xffff0000, v67
	v_mul_f32_e32 v60, v60, v71
	v_mul_f32_e32 v71, v56, v73
	v_mul_f32_e32 v56, v61, v64
	v_mul_f32_e32 v61, v57, v66
	v_mul_f32_e32 v57, v62, v72
	v_mul_f32_e32 v62, v58, v74
	v_mul_f32_e32 v58, v63, v65
	v_mul_f32_e32 v59, v59, v67
	v_cvt_pk_bf16_f32 v56, v60, v56
	v_cvt_pk_bf16_f32 v57, v57, v58
	v_cvt_pk_bf16_f32 v58, v71, v61
	v_cvt_pk_bf16_f32 v59, v62, v59
	global_store_dwordx4 v[68:69], v[56:59], off
	global_load_dwordx4 v[56:59], v[78:79], off offset:256
	v_mul_f32_e32 v52, v52, v70
	v_mul_f32_e32 v48, v48, v70
	v_mul_f32_e32 v53, v53, v70
	v_mul_f32_e32 v49, v49, v70
	v_mul_f32_e32 v54, v54, v70
	v_mul_f32_e32 v50, v50, v70
	v_mul_f32_e32 v55, v55, v70
	v_mul_f32_e32 v51, v51, v70
	v_exp_f32_e32 v52, v52
	v_exp_f32_e32 v48, v48
	v_exp_f32_e32 v53, v53
	v_exp_f32_e32 v49, v49
	v_exp_f32_e32 v54, v54
	v_exp_f32_e32 v50, v50
	v_exp_f32_e32 v55, v55
	v_exp_f32_e32 v51, v51
	v_add_f32_e32 v52, 1.0, v52
	v_add_f32_e32 v48, 1.0, v48
	v_add_f32_e32 v53, 1.0, v53
	v_add_f32_e32 v49, 1.0, v49
	v_add_f32_e32 v54, 1.0, v54
	v_add_f32_e32 v50, 1.0, v50
	v_add_f32_e32 v55, 1.0, v55
	v_add_f32_e32 v51, 1.0, v51
	v_rcp_f32_e32 v52, v52
	v_rcp_f32_e32 v48, v48
	v_rcp_f32_e32 v53, v53
	v_rcp_f32_e32 v49, v49
	v_rcp_f32_e32 v54, v54
	v_rcp_f32_e32 v50, v50
	v_rcp_f32_e32 v55, v55
	v_rcp_f32_e32 v51, v51
	v_lshl_add_u64 v[60:61], v[142:143], 0, s[6:7]
	v_lshl_add_u64 v[62:63], s[20:21], 0, v[60:61]
	s_waitcnt vmcnt(0)
	v_lshlrev_b32_e32 v64, 16, v56
	v_and_b32_e32 v56, 0xffff0000, v56
	v_lshlrev_b32_e32 v65, 16, v57
	v_and_b32_e32 v57, 0xffff0000, v57
	v_lshlrev_b32_e32 v66, 16, v58
	v_and_b32_e32 v58, 0xffff0000, v58
	v_lshlrev_b32_e32 v67, 16, v59
	v_and_b32_e32 v59, 0xffff0000, v59
	v_mul_f32_e32 v52, v52, v64
	v_mul_f32_e32 v64, v48, v66
	v_mul_f32_e32 v48, v53, v56
	v_mul_f32_e32 v53, v49, v58
	v_mul_f32_e32 v49, v54, v65
	v_mul_f32_e32 v54, v50, v67
	v_mul_f32_e32 v50, v55, v57
	v_mul_f32_e32 v51, v51, v59
	v_cvt_pk_bf16_f32 v48, v52, v48
	v_cvt_pk_bf16_f32 v49, v49, v50
	v_cvt_pk_bf16_f32 v50, v64, v53
	v_cvt_pk_bf16_f32 v51, v54, v51
	global_store_dwordx4 v[68:69], v[48:51], off offset:256
	global_load_dword v54, v[140:141], off offset:576
	s_nop 0
	global_load_dwordx4 v[48:51], v[62:63], off
	v_lshl_add_u64 v[52:53], s[24:25], 0, v[60:61]
	s_waitcnt vmcnt(0)
	v_mul_f32_e32 v54, 0xbfb8aa3b, v54
	v_mul_f32_e32 v44, v44, v54
	v_mul_f32_e32 v40, v40, v54
	v_mul_f32_e32 v45, v45, v54
	v_mul_f32_e32 v41, v41, v54
	v_mul_f32_e32 v46, v46, v54
	v_mul_f32_e32 v42, v42, v54
	v_mul_f32_e32 v47, v47, v54
	v_mul_f32_e32 v43, v43, v54
	v_exp_f32_e32 v44, v44
	v_exp_f32_e32 v40, v40
	v_exp_f32_e32 v45, v45
	v_exp_f32_e32 v41, v41
	v_exp_f32_e32 v46, v46
	v_exp_f32_e32 v42, v42
	v_exp_f32_e32 v47, v47
	v_exp_f32_e32 v43, v43
	v_add_f32_e32 v44, 1.0, v44
	v_add_f32_e32 v40, 1.0, v40
	v_add_f32_e32 v45, 1.0, v45
	v_add_f32_e32 v41, 1.0, v41
	v_add_f32_e32 v46, 1.0, v46
	v_add_f32_e32 v42, 1.0, v42
	v_add_f32_e32 v47, 1.0, v47
	v_add_f32_e32 v43, 1.0, v43
	v_rcp_f32_e32 v44, v44
	v_rcp_f32_e32 v40, v40
	v_rcp_f32_e32 v45, v45
	v_rcp_f32_e32 v41, v41
	v_rcp_f32_e32 v46, v46
	v_rcp_f32_e32 v42, v42
	v_rcp_f32_e32 v47, v47
	v_rcp_f32_e32 v43, v43
	v_lshlrev_b32_e32 v55, 16, v48
	v_and_b32_e32 v48, 0xffff0000, v48
	v_lshlrev_b32_e32 v56, 16, v49
	v_and_b32_e32 v49, 0xffff0000, v49
	v_lshlrev_b32_e32 v57, 16, v50
	v_and_b32_e32 v50, 0xffff0000, v50
	v_lshlrev_b32_e32 v58, 16, v51
	v_and_b32_e32 v51, 0xffff0000, v51
	v_mul_f32_e32 v44, v44, v55
	v_mul_f32_e32 v55, v40, v57
	v_mul_f32_e32 v40, v45, v48
	v_mul_f32_e32 v45, v41, v50
	v_mul_f32_e32 v41, v46, v56
	v_mul_f32_e32 v46, v42, v58
	v_mul_f32_e32 v42, v47, v49
	v_mul_f32_e32 v43, v43, v51
	v_cvt_pk_bf16_f32 v40, v44, v40
	v_cvt_pk_bf16_f32 v41, v41, v42
	v_cvt_pk_bf16_f32 v42, v55, v45
	v_cvt_pk_bf16_f32 v43, v46, v43
	global_store_dwordx4 v[52:53], v[40:43], off
	global_load_dwordx4 v[40:43], v[62:63], off offset:256
	v_mul_f32_e32 v36, v36, v54
	v_mul_f32_e32 v32, v32, v54
	v_mul_f32_e32 v37, v37, v54
	v_mul_f32_e32 v33, v33, v54
	v_mul_f32_e32 v38, v38, v54
	v_mul_f32_e32 v34, v34, v54
	v_mul_f32_e32 v39, v39, v54
	v_mul_f32_e32 v35, v35, v54
	v_exp_f32_e32 v36, v36
	v_exp_f32_e32 v32, v32
	v_exp_f32_e32 v37, v37
	v_exp_f32_e32 v33, v33
	v_exp_f32_e32 v38, v38
	v_exp_f32_e32 v34, v34
	v_exp_f32_e32 v39, v39
	v_exp_f32_e32 v35, v35
	v_add_f32_e32 v36, 1.0, v36
	v_add_f32_e32 v32, 1.0, v32
	v_add_f32_e32 v37, 1.0, v37
	v_add_f32_e32 v33, 1.0, v33
	v_add_f32_e32 v38, 1.0, v38
	v_add_f32_e32 v34, 1.0, v34
	v_add_f32_e32 v39, 1.0, v39
	v_add_f32_e32 v35, 1.0, v35
	v_rcp_f32_e32 v36, v36
	v_rcp_f32_e32 v32, v32
	v_rcp_f32_e32 v37, v37
	v_rcp_f32_e32 v33, v33
	v_rcp_f32_e32 v38, v38
	v_rcp_f32_e32 v34, v34
	v_rcp_f32_e32 v39, v39
	v_rcp_f32_e32 v35, v35
	v_lshl_add_u64 v[44:45], v[142:143], 0, s[8:9]
	v_lshl_add_u64 v[46:47], s[20:21], 0, v[44:45]
	s_waitcnt vmcnt(0)
; __device__ __forceinline__ float bf_lo(unsigned w) { return __uint_as_float(w << 16); }
; __device__ __forceinline__ float bf_hi(unsigned w) { return __uint_as_float(w & 0xffff0000u); }
; __device__ __forceinline__ float fast_rcp(float x) { return __builtin_amdgcn_rcpf(x); }
; __device__ __forceinline__ float fast_exp2(float x) { return __builtin_amdgcn_exp2f(x); }
; __device__ __forceinline__ u32x4 pack8(f32x4 v0, f32x4 v1) { u32x4 w; w.x = cvt_pk_bf16(v0[0], v0[1]); w.y = cvt_pk_bf16(v0[2], v0[3]); w.z = cvt_pk_bf16(v1[0], v1[1]); w.w = cvt_pk_bf16(v1[2], v1[3]); return w; }
;     __device__ __forceinline__ void operator()(const f32x4 (&acc)[2][2][4][2], const Unit& u, int wr, int wc, int fr, int fq) const {
;         const int row0 = u.pm * BM + wr * 64 + fr, col0 = u.pn * BM + wc * 32 + 8 * fq;
; #pragma unroll
;         for (int ai = 0; ai < 2; ++ai)
; #pragma unroll
;             for (int m = 0; m < 4; ++m) { const size_t ro = (size_t)(row0 + ai * HALF + m * 16) * DM + col0; const float nr = -LOG2E * rs[row0 + ai * HALF + m * 16];
; #pragma unroll
;                 for (int bj = 0; bj < 2; ++bj) {
;                     const u32x4 pw = *(const u32x4*)(PP + ro + bj * HALF);
;                     const float pv[8] = {bf_lo(pw.x), bf_hi(pw.x), bf_lo(pw.y), bf_hi(pw.y), bf_lo(pw.z), bf_hi(pw.z), bf_lo(pw.w), bf_hi(pw.w)};
;                     f32x4 t0, t1;
; #pragma unroll
;                     for (int j = 0; j < 4; ++j) {
;                         t0[j] = fast_rcp(1.0f + fast_exp2(acc[ai][bj][m][0][j] * nr)) * pv[j];
;                         t1[j] = fast_rcp(1.0f + fast_exp2(acc[ai][bj][m][1][j] * nr)) * pv[4 + j]; }
;                     *(u32x4*)(O + ro + bj * HALF) = pack8(t0, t1); } }
	v_lshlrev_b32_e32 v48, 16, v40
	v_and_b32_e32 v40, 0xffff0000, v40
	v_lshlrev_b32_e32 v49, 16, v41
	v_and_b32_e32 v41, 0xffff0000, v41
	v_lshlrev_b32_e32 v50, 16, v42
	v_and_b32_e32 v42, 0xffff0000, v42
	v_lshlrev_b32_e32 v51, 16, v43
	v_and_b32_e32 v43, 0xffff0000, v43
	v_mul_f32_e32 v36, v36, v48
	v_mul_f32_e32 v48, v32, v50
	v_mul_f32_e32 v32, v37, v40
	v_mul_f32_e32 v37, v33, v42
	v_mul_f32_e32 v33, v38, v49
	v_mul_f32_e32 v38, v34, v51
	v_mul_f32_e32 v34, v39, v41
	v_mul_f32_e32 v35, v35, v43
	v_cvt_pk_bf16_f32 v32, v36, v32
	v_cvt_pk_bf16_f32 v33, v33, v34
	v_cvt_pk_bf16_f32 v34, v48, v37
	v_cvt_pk_bf16_f32 v35, v38, v35
	global_store_dwordx4 v[52:53], v[32:35], off offset:256
	global_load_dword v38, v[140:141], off offset:640
	s_nop 0
	global_load_dwordx4 v[32:35], v[46:47], off
	v_lshl_add_u64 v[36:37], s[24:25], 0, v[44:45]
	s_waitcnt vmcnt(0)
	v_mul_f32_e32 v38, 0xbfb8aa3b, v38
	v_mul_f32_e32 v28, v28, v38
	v_mul_f32_e32 v24, v24, v38
	v_mul_f32_e32 v29, v29, v38
	v_mul_f32_e32 v25, v25, v38
	v_mul_f32_e32 v30, v30, v38
	v_mul_f32_e32 v26, v26, v38
	v_mul_f32_e32 v31, v31, v38
	v_mul_f32_e32 v27, v27, v38
	v_exp_f32_e32 v28, v28
	v_exp_f32_e32 v24, v24
	v_exp_f32_e32 v29, v29
	v_exp_f32_e32 v25, v25
	v_exp_f32_e32 v30, v30
	v_exp_f32_e32 v26, v26
	v_exp_f32_e32 v31, v31
	v_exp_f32_e32 v27, v27
	v_add_f32_e32 v28, 1.0, v28
	v_add_f32_e32 v24, 1.0, v24
	v_add_f32_e32 v29, 1.0, v29
	v_add_f32_e32 v25, 1.0, v25
	v_add_f32_e32 v30, 1.0, v30
	v_add_f32_e32 v26, 1.0, v26
	v_add_f32_e32 v31, 1.0, v31
	v_add_f32_e32 v27, 1.0, v27
	v_rcp_f32_e32 v28, v28
	v_rcp_f32_e32 v24, v24
	v_rcp_f32_e32 v29, v29
	v_rcp_f32_e32 v25, v25
	v_rcp_f32_e32 v30, v30
	v_rcp_f32_e32 v26, v26
	v_rcp_f32_e32 v31, v31
	v_rcp_f32_e32 v27, v27
	v_lshlrev_b32_e32 v39, 16, v32
	v_and_b32_e32 v32, 0xffff0000, v32
	v_lshlrev_b32_e32 v40, 16, v33
	v_and_b32_e32 v33, 0xffff0000, v33
	v_lshlrev_b32_e32 v41, 16, v34
	v_and_b32_e32 v34, 0xffff0000, v34
	v_lshlrev_b32_e32 v42, 16, v35
	v_and_b32_e32 v35, 0xffff0000, v35
	v_mul_f32_e32 v28, v28, v39
	v_mul_f32_e32 v39, v24, v41
	v_mul_f32_e32 v24, v29, v32
	v_mul_f32_e32 v29, v25, v34
	v_mul_f32_e32 v25, v30, v40
	v_mul_f32_e32 v30, v26, v42
	v_mul_f32_e32 v26, v31, v33
	v_mul_f32_e32 v27, v27, v35
	v_cvt_pk_bf16_f32 v24, v28, v24
	v_cvt_pk_bf16_f32 v25, v25, v26
	v_cvt_pk_bf16_f32 v26, v39, v29
	v_cvt_pk_bf16_f32 v27, v30, v27
	global_store_dwordx4 v[36:37], v[24:27], off
	global_load_dwordx4 v[24:27], v[46:47], off offset:256
	v_mul_f32_e32 v20, v20, v38
	v_mul_f32_e32 v16, v16, v38
	v_mul_f32_e32 v21, v21, v38
	v_mul_f32_e32 v17, v17, v38
	v_mul_f32_e32 v22, v22, v38
	v_mul_f32_e32 v18, v18, v38
	v_mul_f32_e32 v23, v23, v38
	v_mul_f32_e32 v19, v19, v38
	v_exp_f32_e32 v20, v20
	v_exp_f32_e32 v16, v16
	v_exp_f32_e32 v21, v21
	v_exp_f32_e32 v17, v17
	v_exp_f32_e32 v22, v22
	v_exp_f32_e32 v18, v18
	v_exp_f32_e32 v23, v23
	v_exp_f32_e32 v19, v19
	v_add_f32_e32 v20, 1.0, v20
	v_add_f32_e32 v16, 1.0, v16
	v_add_f32_e32 v21, 1.0, v21
	v_add_f32_e32 v17, 1.0, v17
	v_add_f32_e32 v22, 1.0, v22
	v_add_f32_e32 v18, 1.0, v18
	v_add_f32_e32 v23, 1.0, v23
	v_add_f32_e32 v19, 1.0, v19
	v_rcp_f32_e32 v20, v20
	v_rcp_f32_e32 v16, v16
	v_rcp_f32_e32 v21, v21
	v_rcp_f32_e32 v17, v17
	v_rcp_f32_e32 v22, v22
	v_rcp_f32_e32 v18, v18
	v_rcp_f32_e32 v23, v23
	v_rcp_f32_e32 v19, v19
	v_lshl_add_u64 v[28:29], v[142:143], 0, s[30:31]
	v_lshl_add_u64 v[30:31], s[20:21], 0, v[28:29]
	s_waitcnt vmcnt(0)
; __device__ __forceinline__ float bf_lo(unsigned w) { return __uint_as_float(w << 16); }
; __device__ __forceinline__ float bf_hi(unsigned w) { return __uint_as_float(w & 0xffff0000u); }
; __device__ __forceinline__ float fast_rcp(float x) { return __builtin_amdgcn_rcpf(x); }
; __device__ __forceinline__ float fast_exp2(float x) { return __builtin_amdgcn_exp2f(x); }
; #define PG8_WAIT_V(n) asm volatile("s_waitcnt vmcnt(" #n ")" ::: "memory")
; #define PG8_BAR __builtin_amdgcn_s_barrier()
; template <class Epi>
; __device__ __forceinline__ void gemm_phase(LAS unsigned char* lds, const Gemm g, const StaticOrder& S, const Epi& E) {
;     ...
;         if (!has_next) break;
; #pragma unroll
;         for (int a = 0; a < 2; ++a)
; #pragma unroll
;             for (int b = 0; b < 2; ++b)
; #pragma unroll
;                 for (int m = 0; m < 4; ++m)
; #pragma unroll
;                     for (int n = 0; n < 2; ++n) acc[a][b][m][n] = (f32x4){0.f, 0.f, 0.f, 0.f};
;         cur = nxt; cA = nA; cB = nB; ++ui;
;     }
;     PG8_WAIT_V(0);
;     if (wr == 0) PG8_BAR;
;     __device__ __forceinline__ void operator()(const f32x4 (&acc)[2][2][4][2], const Unit& u, int wr, int wc, int fr, int fq) const {
;         const int row0 = u.pm * BM + wr * 64 + fr, col0 = u.pn * BM + wc * 32 + 8 * fq;
; #pragma unroll
;         for (int ai = 0; ai < 2; ++ai)
; #pragma unroll
;             for (int m = 0; m < 4; ++m) { const size_t ro = (size_t)(row0 + ai * HALF + m * 16) * DM + col0; const float nr = -LOG2E * rs[row0 + ai * HALF + m * 16];
; #pragma unroll
;                 for (int bj = 0; bj < 2; ++bj) {
;                     const u32x4 pw = *(const u32x4*)(PP + ro + bj * HALF);
;                     const float pv[8] = {bf_lo(pw.x), bf_hi(pw.x), bf_lo(pw.y), bf_hi(pw.y), bf_lo(pw.z), bf_hi(pw.z), bf_lo(pw.w), bf_hi(pw.w)};
;                     f32x4 t0, t1;
; #pragma unroll
;                     for (int j = 0; j < 4; ++j) {
;                         t0[j] = fast_rcp(1.0f + fast_exp2(acc[ai][bj][m][0][j] * nr)) * pv[j];
;                         t1[j] = fast_rcp(1.0f + fast_exp2(acc[ai][bj][m][1][j] * nr)) * pv[4 + j]; }
;                     *(u32x4*)(O + ro + bj * HALF) = pack8(t0, t1); } }
	v_lshlrev_b32_e32 v32, 16, v24
	v_and_b32_e32 v24, 0xffff0000, v24
	v_lshlrev_b32_e32 v33, 16, v25
	v_and_b32_e32 v25, 0xffff0000, v25
	v_lshlrev_b32_e32 v34, 16, v26
	v_and_b32_e32 v26, 0xffff0000, v26
	v_lshlrev_b32_e32 v35, 16, v27
	v_and_b32_e32 v27, 0xffff0000, v27
	v_mul_f32_e32 v20, v20, v32
	v_mul_f32_e32 v32, v16, v34
	v_mul_f32_e32 v16, v21, v24
	v_mul_f32_e32 v21, v17, v26
	v_mul_f32_e32 v17, v22, v33
	v_mul_f32_e32 v22, v18, v35
	v_mul_f32_e32 v18, v23, v25
	v_mul_f32_e32 v19, v19, v27
	v_cvt_pk_bf16_f32 v16, v20, v16
	v_cvt_pk_bf16_f32 v17, v17, v18
	v_cvt_pk_bf16_f32 v18, v32, v21
	v_cvt_pk_bf16_f32 v19, v22, v19
	global_store_dwordx4 v[36:37], v[16:19], off offset:256
	global_load_dword v22, v[140:141], off offset:704
	s_nop 0
	global_load_dwordx4 v[16:19], v[30:31], off
	v_lshl_add_u64 v[20:21], s[24:25], 0, v[28:29]
	s_waitcnt vmcnt(0)
	v_mul_f32_e32 v22, 0xbfb8aa3b, v22
	v_mul_f32_e32 v12, v12, v22
	v_mul_f32_e32 v8, v8, v22
	v_mul_f32_e32 v13, v13, v22
	v_mul_f32_e32 v9, v9, v22
	v_mul_f32_e32 v14, v14, v22
	v_mul_f32_e32 v10, v10, v22
	v_mul_f32_e32 v15, v15, v22
	v_mul_f32_e32 v11, v11, v22
	v_exp_f32_e32 v12, v12
	v_exp_f32_e32 v8, v8
	v_exp_f32_e32 v13, v13
	v_exp_f32_e32 v9, v9
	v_exp_f32_e32 v14, v14
	v_exp_f32_e32 v10, v10
	v_exp_f32_e32 v15, v15
	v_exp_f32_e32 v11, v11
	v_add_f32_e32 v12, 1.0, v12
	v_add_f32_e32 v8, 1.0, v8
	v_add_f32_e32 v13, 1.0, v13
	v_add_f32_e32 v9, 1.0, v9
	v_add_f32_e32 v14, 1.0, v14
	v_add_f32_e32 v10, 1.0, v10
	v_add_f32_e32 v15, 1.0, v15
	v_add_f32_e32 v11, 1.0, v11
	v_rcp_f32_e32 v12, v12
	v_rcp_f32_e32 v8, v8
	v_rcp_f32_e32 v13, v13
	v_rcp_f32_e32 v9, v9
	v_rcp_f32_e32 v14, v14
	v_rcp_f32_e32 v10, v10
	v_rcp_f32_e32 v15, v15
	v_rcp_f32_e32 v11, v11
	v_lshlrev_b32_e32 v23, 16, v16
	v_and_b32_e32 v16, 0xffff0000, v16
	v_lshlrev_b32_e32 v24, 16, v17
	v_and_b32_e32 v17, 0xffff0000, v17
	v_lshlrev_b32_e32 v25, 16, v18
	v_and_b32_e32 v18, 0xffff0000, v18
	v_lshlrev_b32_e32 v26, 16, v19
	v_and_b32_e32 v19, 0xffff0000, v19
	v_mul_f32_e32 v12, v12, v23
	v_mul_f32_e32 v23, v8, v25
	v_mul_f32_e32 v8, v13, v16
	v_mul_f32_e32 v13, v9, v18
	v_mul_f32_e32 v9, v14, v24
	v_mul_f32_e32 v14, v10, v26
	v_mul_f32_e32 v10, v15, v17
	v_mul_f32_e32 v11, v11, v19
	v_cvt_pk_bf16_f32 v8, v12, v8
	v_cvt_pk_bf16_f32 v9, v9, v10
	v_cvt_pk_bf16_f32 v10, v23, v13
	v_cvt_pk_bf16_f32 v11, v14, v11
	global_store_dwordx4 v[20:21], v[8:11], off
	global_load_dwordx4 v[8:11], v[30:31], off offset:256
	v_mul_f32_e32 v4, v4, v22
	v_mul_f32_e32 v0, v0, v22
	v_mul_f32_e32 v5, v5, v22
	v_mul_f32_e32 v1, v1, v22
	v_mul_f32_e32 v6, v6, v22
	v_mul_f32_e32 v2, v2, v22
	v_mul_f32_e32 v7, v7, v22
	v_mul_f32_e32 v3, v3, v22
	v_exp_f32_e32 v4, v4
	v_exp_f32_e32 v0, v0
	v_exp_f32_e32 v5, v5
	v_exp_f32_e32 v1, v1
	v_exp_f32_e32 v6, v6
	v_exp_f32_e32 v2, v2
	v_exp_f32_e32 v7, v7
	v_exp_f32_e32 v3, v3
	v_add_f32_e32 v4, 1.0, v4
	v_add_f32_e32 v0, 1.0, v0
	v_add_f32_e32 v5, 1.0, v5
	v_add_f32_e32 v1, 1.0, v1
	v_add_f32_e32 v6, 1.0, v6
	v_add_f32_e32 v2, 1.0, v2
	v_add_f32_e32 v7, 1.0, v7
	v_add_f32_e32 v3, 1.0, v3
	v_rcp_f32_e32 v4, v4
	v_rcp_f32_e32 v0, v0
	v_rcp_f32_e32 v5, v5
	v_rcp_f32_e32 v1, v1
	v_rcp_f32_e32 v6, v6
	v_rcp_f32_e32 v2, v2
	v_rcp_f32_e32 v7, v7
	v_rcp_f32_e32 v3, v3
	s_waitcnt vmcnt(0)
	v_lshlrev_b32_e32 v12, 16, v8
	v_and_b32_e32 v8, 0xffff0000, v8
	v_lshlrev_b32_e32 v13, 16, v9
	v_and_b32_e32 v9, 0xffff0000, v9
	v_lshlrev_b32_e32 v14, 16, v10
	v_and_b32_e32 v10, 0xffff0000, v10
	v_lshlrev_b32_e32 v15, 16, v11
	v_and_b32_e32 v11, 0xffff0000, v11
	v_mul_f32_e32 v4, v4, v12
	v_mul_f32_e32 v12, v0, v14
	v_mul_f32_e32 v0, v5, v8
	v_mul_f32_e32 v5, v1, v10
	v_mul_f32_e32 v1, v6, v13
	v_mul_f32_e32 v6, v2, v15
	v_mul_f32_e32 v2, v7, v9
	v_mul_f32_e32 v3, v3, v11
	v_cvt_pk_bf16_f32 v0, v4, v0
	v_cvt_pk_bf16_f32 v1, v1, v2
	v_cvt_pk_bf16_f32 v2, v12, v5
	v_cvt_pk_bf16_f32 v3, v6, v3
	global_store_dwordx4 v[20:21], v[0:3], off offset:256
	s_cbranch_vccz .LBB0_996
	s_waitcnt vmcnt(0)
	s_cmpk_gt_u32 s10, 0xff
	s_cbranch_scc1 .LBB0_1003
	s_barrier
